# GEMM K loops: LDS-DMA loads in SGPR-base + VGPR-offset form (no per-load 64-bit VALU address add; +128B loads use saved base, offset:128, M0-128)
# speedup vs baseline: 1.0043x; 1.0043x over previous
.LBB0_115:
	ds_read_b128 v[128:131], v172
	ds_read_b128 v[132:135], v172 offset:1024
	ds_read_b128 v[156:159], v172 offset:2048
	ds_read_b128 v[160:163], v172 offset:3072
	ds_read_b128 v[164:167], v173
	ds_read_b128 v[176:179], v173 offset:1024
	ds_read_b128 v[180:183], v173 offset:2048
	ds_read_b128 v[184:187], v173 offset:3072
	s_add_u32 s18, s14, 0xfff80080
	s_addc_u32 s19, s15, -1
	s_cmp_eq_u32 s81, 28
	s_cselect_b32 s55, s5, s19
	s_cselect_b32 s54, s13, s18
	s_cselect_b32 s19, s33, s80
	s_cselect_b32 s18, s39, s41
	s_add_i32 m0, s63, 0xc000
	ds_read_b128 v[188:191], v174
	ds_read_b128 v[192:195], v174 offset:1024
	ds_read_b128 v[196:199], v174 offset:2048
	ds_read_b128 v[200:203], v174 offset:3072
	ds_read_b128 v[204:207], v174 offset:4096
	ds_read_b128 v[208:211], v174 offset:5120
	ds_read_b128 v[212:215], v174 offset:6144
	ds_read_b128 v[216:219], v174 offset:7168
	global_load_lds_dwordx4 v148, s[14:15]
	s_add_i32 m0, s63, 0xe000
	s_nop 0
	global_load_lds_dwordx4 v150, s[14:15]
	s_waitcnt vmcnt(8)
	s_waitcnt lgkmcnt(0)
	s_barrier
	s_setprio 1
	s_waitcnt lgkmcnt(0)
	v_mfma_f32_16x16x32_bf16 v[124:127], v[128:131], v[188:191], v[124:127]
	v_mfma_f32_16x16x32_bf16 v[120:123], v[156:159], v[188:191], v[120:123]
	v_mfma_f32_16x16x32_bf16 v[108:111], v[128:131], v[196:199], v[108:111]
	v_mfma_f32_16x16x32_bf16 v[104:107], v[156:159], v[196:199], v[104:107]
	v_mfma_f32_16x16x32_bf16 v[92:95], v[128:131], v[204:207], v[92:95]
	v_mfma_f32_16x16x32_bf16 v[88:91], v[156:159], v[204:207], v[88:91]
	v_mfma_f32_16x16x32_bf16 v[76:79], v[128:131], v[212:215], v[76:79]
	v_mfma_f32_16x16x32_bf16 v[72:75], v[156:159], v[212:215], v[72:75]
	v_mfma_f32_16x16x32_bf16 v[124:127], v[132:135], v[192:195], v[124:127]
	v_mfma_f32_16x16x32_bf16 v[120:123], v[160:163], v[192:195], v[120:123]
	v_mfma_f32_16x16x32_bf16 v[108:111], v[132:135], v[200:203], v[108:111]
	v_mfma_f32_16x16x32_bf16 v[104:107], v[160:163], v[200:203], v[104:107]
	v_mfma_f32_16x16x32_bf16 v[92:95], v[132:135], v[208:211], v[92:95]
	v_mfma_f32_16x16x32_bf16 v[88:91], v[160:163], v[208:211], v[88:91]
	v_mfma_f32_16x16x32_bf16 v[76:79], v[132:135], v[216:219], v[76:79]
	v_mfma_f32_16x16x32_bf16 v[72:75], v[160:163], v[216:219], v[72:75]
	s_setprio 0
	s_setprio 1
	v_mfma_f32_16x16x32_bf16 v[116:119], v[164:167], v[188:191], v[116:119]
	v_mfma_f32_16x16x32_bf16 v[112:115], v[180:183], v[188:191], v[112:115]
	v_mfma_f32_16x16x32_bf16 v[100:103], v[164:167], v[196:199], v[100:103]
	v_mfma_f32_16x16x32_bf16 v[96:99], v[180:183], v[196:199], v[96:99]
	v_mfma_f32_16x16x32_bf16 v[84:87], v[164:167], v[204:207], v[84:87]
	v_mfma_f32_16x16x32_bf16 v[80:83], v[180:183], v[204:207], v[80:83]
	v_mfma_f32_16x16x32_bf16 v[68:71], v[164:167], v[212:215], v[68:71]
	v_mfma_f32_16x16x32_bf16 v[64:67], v[180:183], v[212:215], v[64:67]
	v_mfma_f32_16x16x32_bf16 v[116:119], v[176:179], v[192:195], v[116:119]
	v_mfma_f32_16x16x32_bf16 v[112:115], v[184:187], v[192:195], v[112:115]
	v_mfma_f32_16x16x32_bf16 v[100:103], v[176:179], v[200:203], v[100:103]
	v_mfma_f32_16x16x32_bf16 v[96:99], v[184:187], v[200:203], v[96:99]
	v_mfma_f32_16x16x32_bf16 v[84:87], v[176:179], v[208:211], v[84:87]
	v_mfma_f32_16x16x32_bf16 v[80:83], v[184:187], v[208:211], v[80:83]
	v_mfma_f32_16x16x32_bf16 v[68:71], v[176:179], v[216:219], v[68:71]
	v_mfma_f32_16x16x32_bf16 v[64:67], v[184:187], v[216:219], v[64:67]
	s_setprio 0
	s_barrier
	s_add_i32 s82, s76, s62
	s_mov_b64 s[98:99], s[18:19]
	s_mov_b32 m0, s82
	ds_read_b128 v[188:191], v174 offset:16384
	ds_read_b128 v[192:195], v174 offset:17408
	ds_read_b128 v[196:199], v174 offset:18432
	ds_read_b128 v[200:203], v174 offset:19456
	ds_read_b128 v[204:207], v174 offset:20480
	ds_read_b128 v[208:211], v174 offset:21504
	ds_read_b128 v[212:215], v174 offset:22528
	ds_read_b128 v[216:219], v174 offset:23552
	global_load_lds_dwordx4 v138, s[18:19]
	s_add_i32 m0, s82, 0x2000
	s_add_u32 s82, s18, 0x80000
	s_addc_u32 s83, s19, 0
	s_add_i32 s84, s77, s62
	global_load_lds_dwordx4 v142, s[18:19]
	s_mov_b32 m0, s84
	s_mov_b64 s[100:101], s[54:55]
	global_load_lds_dwordx4 v138, s[82:83]
	s_add_i32 m0, s84, 0x2000
	s_nop 0
	global_load_lds_dwordx4 v142, s[82:83]
	s_mov_b32 m0, s63
	s_nop 0
	global_load_lds_dwordx4 v136, s[54:55]
	s_mov_b32 m0, s64
	s_nop 0
	global_load_lds_dwordx4 v140, s[54:55]
	s_waitcnt vmcnt(8)
	s_waitcnt lgkmcnt(0)
	s_barrier
	s_setprio 1
	s_waitcnt lgkmcnt(0)
	v_mfma_f32_16x16x32_bf16 v[60:63], v[128:131], v[188:191], v[60:63]
	v_mfma_f32_16x16x32_bf16 v[56:59], v[156:159], v[188:191], v[56:59]
	v_mfma_f32_16x16x32_bf16 v[44:47], v[128:131], v[196:199], v[44:47]
	v_mfma_f32_16x16x32_bf16 v[40:43], v[156:159], v[196:199], v[40:43]
	v_mfma_f32_16x16x32_bf16 v[28:31], v[128:131], v[204:207], v[28:31]
	v_mfma_f32_16x16x32_bf16 v[24:27], v[156:159], v[204:207], v[24:27]
	v_mfma_f32_16x16x32_bf16 v[12:15], v[128:131], v[212:215], v[12:15]
	v_mfma_f32_16x16x32_bf16 v[8:11], v[156:159], v[212:215], v[8:11]
	v_mfma_f32_16x16x32_bf16 v[60:63], v[132:135], v[192:195], v[60:63]
	v_mfma_f32_16x16x32_bf16 v[56:59], v[160:163], v[192:195], v[56:59]
	v_mfma_f32_16x16x32_bf16 v[44:47], v[132:135], v[200:203], v[44:47]
	v_mfma_f32_16x16x32_bf16 v[40:43], v[160:163], v[200:203], v[40:43]
	v_mfma_f32_16x16x32_bf16 v[28:31], v[132:135], v[208:211], v[28:31]
	v_mfma_f32_16x16x32_bf16 v[24:27], v[160:163], v[208:211], v[24:27]
	v_mfma_f32_16x16x32_bf16 v[12:15], v[132:135], v[216:219], v[12:15]
	v_mfma_f32_16x16x32_bf16 v[8:11], v[160:163], v[216:219], v[8:11]
	s_setprio 0
	s_setprio 1
	v_mfma_f32_16x16x32_bf16 v[52:55], v[164:167], v[188:191], v[52:55]
	v_mfma_f32_16x16x32_bf16 v[48:51], v[180:183], v[188:191], v[48:51]
	v_mfma_f32_16x16x32_bf16 v[36:39], v[164:167], v[196:199], v[36:39]
	v_mfma_f32_16x16x32_bf16 v[32:35], v[180:183], v[196:199], v[32:35]
	v_mfma_f32_16x16x32_bf16 v[20:23], v[164:167], v[204:207], v[20:23]
	v_mfma_f32_16x16x32_bf16 v[16:19], v[180:183], v[204:207], v[16:19]
	v_mfma_f32_16x16x32_bf16 v[4:7], v[164:167], v[212:215], v[4:7]
	v_mfma_f32_16x16x32_bf16 v[0:3], v[180:183], v[212:215], v[0:3]
	v_mfma_f32_16x16x32_bf16 v[52:55], v[176:179], v[192:195], v[52:55]
	v_mfma_f32_16x16x32_bf16 v[48:51], v[184:187], v[192:195], v[48:51]
	v_mfma_f32_16x16x32_bf16 v[36:39], v[176:179], v[200:203], v[36:39]
	v_mfma_f32_16x16x32_bf16 v[32:35], v[184:187], v[200:203], v[32:35]
	v_mfma_f32_16x16x32_bf16 v[20:23], v[176:179], v[208:211], v[20:23]
	v_mfma_f32_16x16x32_bf16 v[16:19], v[184:187], v[208:211], v[16:19]
	v_mfma_f32_16x16x32_bf16 v[4:7], v[176:179], v[216:219], v[4:7]
	v_mfma_f32_16x16x32_bf16 v[0:3], v[184:187], v[216:219], v[0:3]
	s_setprio 0
	s_barrier
	s_add_i32 s82, 0, 0x18000
	v_add_u32_e32 v144, s82, v170
	s_add_i32 s83, 0, 0x1c000
	ds_read_b128 v[128:131], v144
	ds_read_b128 v[132:135], v144 offset:1024
	ds_read_b128 v[156:159], v144 offset:2048
	ds_read_b128 v[160:163], v144 offset:3072
	v_add_u32_e32 v144, s83, v170
	ds_read_b128 v[164:167], v144
	ds_read_b128 v[176:179], v144 offset:1024
	ds_read_b128 v[180:183], v144 offset:2048
	ds_read_b128 v[184:187], v144 offset:3072
	s_add_u32 s54, s54, 0x80000
	s_addc_u32 s55, s55, 0
	s_mov_b32 m0, s65
	ds_read_b128 v[188:191], v174 offset:32768
	ds_read_b128 v[192:195], v174 offset:33792
	ds_read_b128 v[196:199], v174 offset:34816
	ds_read_b128 v[200:203], v174 offset:35840
	ds_read_b128 v[204:207], v174 offset:36864
	ds_read_b128 v[208:211], v174 offset:37888
	ds_read_b128 v[212:215], v174 offset:38912
	ds_read_b128 v[216:219], v174 offset:39936
	global_load_lds_dwordx4 v136, s[54:55]
	s_mov_b32 m0, s66
	s_nop 0
	global_load_lds_dwordx4 v140, s[54:55]
	s_waitcnt vmcnt(8)
	s_waitcnt lgkmcnt(0)
	s_barrier
	s_setprio 1
	s_waitcnt lgkmcnt(0)
	v_mfma_f32_16x16x32_bf16 v[124:127], v[128:131], v[188:191], v[124:127]
	v_mfma_f32_16x16x32_bf16 v[120:123], v[156:159], v[188:191], v[120:123]
	v_mfma_f32_16x16x32_bf16 v[108:111], v[128:131], v[196:199], v[108:111]
	v_mfma_f32_16x16x32_bf16 v[104:107], v[156:159], v[196:199], v[104:107]
	v_mfma_f32_16x16x32_bf16 v[92:95], v[128:131], v[204:207], v[92:95]
	v_mfma_f32_16x16x32_bf16 v[88:91], v[156:159], v[204:207], v[88:91]
	v_mfma_f32_16x16x32_bf16 v[76:79], v[128:131], v[212:215], v[76:79]
	v_mfma_f32_16x16x32_bf16 v[72:75], v[156:159], v[212:215], v[72:75]
	v_mfma_f32_16x16x32_bf16 v[124:127], v[132:135], v[192:195], v[124:127]
	v_mfma_f32_16x16x32_bf16 v[120:123], v[160:163], v[192:195], v[120:123]
	v_mfma_f32_16x16x32_bf16 v[108:111], v[132:135], v[200:203], v[108:111]
	v_mfma_f32_16x16x32_bf16 v[104:107], v[160:163], v[200:203], v[104:107]
	v_mfma_f32_16x16x32_bf16 v[92:95], v[132:135], v[208:211], v[92:95]
	v_mfma_f32_16x16x32_bf16 v[88:91], v[160:163], v[208:211], v[88:91]
	v_mfma_f32_16x16x32_bf16 v[76:79], v[132:135], v[216:219], v[76:79]
	v_mfma_f32_16x16x32_bf16 v[72:75], v[160:163], v[216:219], v[72:75]
	s_setprio 0
	s_setprio 1
	v_mfma_f32_16x16x32_bf16 v[116:119], v[164:167], v[188:191], v[116:119]
	v_mfma_f32_16x16x32_bf16 v[112:115], v[180:183], v[188:191], v[112:115]
	v_mfma_f32_16x16x32_bf16 v[100:103], v[164:167], v[196:199], v[100:103]
	v_mfma_f32_16x16x32_bf16 v[96:99], v[180:183], v[196:199], v[96:99]
	v_mfma_f32_16x16x32_bf16 v[84:87], v[164:167], v[204:207], v[84:87]
	v_mfma_f32_16x16x32_bf16 v[80:83], v[180:183], v[204:207], v[80:83]
	v_mfma_f32_16x16x32_bf16 v[68:71], v[164:167], v[212:215], v[68:71]
	v_mfma_f32_16x16x32_bf16 v[64:67], v[180:183], v[212:215], v[64:67]
	v_mfma_f32_16x16x32_bf16 v[116:119], v[176:179], v[192:195], v[116:119]
	v_mfma_f32_16x16x32_bf16 v[112:115], v[184:187], v[192:195], v[112:115]
	v_mfma_f32_16x16x32_bf16 v[100:103], v[176:179], v[200:203], v[100:103]
	v_mfma_f32_16x16x32_bf16 v[96:99], v[184:187], v[200:203], v[96:99]
	v_mfma_f32_16x16x32_bf16 v[84:87], v[176:179], v[208:211], v[84:87]
	v_mfma_f32_16x16x32_bf16 v[80:83], v[184:187], v[208:211], v[80:83]
	v_mfma_f32_16x16x32_bf16 v[68:71], v[176:179], v[216:219], v[68:71]
	v_mfma_f32_16x16x32_bf16 v[64:67], v[184:187], v[216:219], v[64:67]
	s_setprio 0
	s_barrier
	s_add_i32 s54, s82, s62
	s_add_i32 m0, s54, 0xffffff80
	ds_read_b128 v[188:191], v174 offset:49152
	ds_read_b128 v[192:195], v174 offset:50176
	ds_read_b128 v[196:199], v174 offset:51200
	ds_read_b128 v[200:203], v174 offset:52224
	ds_read_b128 v[204:207], v174 offset:53248
	ds_read_b128 v[208:211], v174 offset:54272
	ds_read_b128 v[212:215], v174 offset:55296
	ds_read_b128 v[216:219], v174 offset:56320
	global_load_lds_dwordx4 v138, s[98:99] offset:128
	s_add_i32 m0, s54, 0x1f80
	s_add_u32 s18, s18, 0x80080
	s_addc_u32 s19, s19, 0
	s_add_i32 s54, s83, s62
	global_load_lds_dwordx4 v142, s[98:99] offset:128
	s_mov_b32 m0, s54
	s_nop 0
	global_load_lds_dwordx4 v138, s[18:19]
	s_add_i32 m0, s54, 0x2000
	s_nop 0
	global_load_lds_dwordx4 v142, s[18:19]
	s_add_i32 m0, s71, 0xffffff80
	s_nop 0
	global_load_lds_dwordx4 v136, s[100:101] offset:128
	s_add_i32 m0, s72, 0xffffff80
	s_nop 0
	global_load_lds_dwordx4 v140, s[100:101] offset:128
	s_waitcnt vmcnt(8)
	s_waitcnt lgkmcnt(0)
	s_barrier
	s_setprio 1
	s_waitcnt lgkmcnt(0)
	v_mfma_f32_16x16x32_bf16 v[60:63], v[128:131], v[188:191], v[60:63]
	v_mfma_f32_16x16x32_bf16 v[56:59], v[156:159], v[188:191], v[56:59]
	v_mfma_f32_16x16x32_bf16 v[44:47], v[128:131], v[196:199], v[44:47]
	v_mfma_f32_16x16x32_bf16 v[40:43], v[156:159], v[196:199], v[40:43]
	v_mfma_f32_16x16x32_bf16 v[28:31], v[128:131], v[204:207], v[28:31]
	v_mfma_f32_16x16x32_bf16 v[24:27], v[156:159], v[204:207], v[24:27]
	v_mfma_f32_16x16x32_bf16 v[12:15], v[128:131], v[212:215], v[12:15]
	v_mfma_f32_16x16x32_bf16 v[8:11], v[156:159], v[212:215], v[8:11]
	v_mfma_f32_16x16x32_bf16 v[60:63], v[132:135], v[192:195], v[60:63]
	v_mfma_f32_16x16x32_bf16 v[56:59], v[160:163], v[192:195], v[56:59]
	v_mfma_f32_16x16x32_bf16 v[44:47], v[132:135], v[200:203], v[44:47]
	v_mfma_f32_16x16x32_bf16 v[40:43], v[160:163], v[200:203], v[40:43]
	v_mfma_f32_16x16x32_bf16 v[28:31], v[132:135], v[208:211], v[28:31]
	v_mfma_f32_16x16x32_bf16 v[24:27], v[160:163], v[208:211], v[24:27]
	v_mfma_f32_16x16x32_bf16 v[12:15], v[132:135], v[216:219], v[12:15]
	v_mfma_f32_16x16x32_bf16 v[8:11], v[160:163], v[216:219], v[8:11]
	s_setprio 0
	s_setprio 1
	v_mfma_f32_16x16x32_bf16 v[52:55], v[164:167], v[188:191], v[52:55]
	v_mfma_f32_16x16x32_bf16 v[48:51], v[180:183], v[188:191], v[48:51]
	v_mfma_f32_16x16x32_bf16 v[36:39], v[164:167], v[196:199], v[36:39]
	v_mfma_f32_16x16x32_bf16 v[32:35], v[180:183], v[196:199], v[32:35]
	v_mfma_f32_16x16x32_bf16 v[20:23], v[164:167], v[204:207], v[20:23]
	v_mfma_f32_16x16x32_bf16 v[16:19], v[180:183], v[204:207], v[16:19]
	v_mfma_f32_16x16x32_bf16 v[4:7], v[164:167], v[212:215], v[4:7]
	v_mfma_f32_16x16x32_bf16 v[0:3], v[180:183], v[212:215], v[0:3]
	v_mfma_f32_16x16x32_bf16 v[52:55], v[176:179], v[192:195], v[52:55]
	v_mfma_f32_16x16x32_bf16 v[48:51], v[184:187], v[192:195], v[48:51]
	v_mfma_f32_16x16x32_bf16 v[36:39], v[176:179], v[200:203], v[36:39]
	v_mfma_f32_16x16x32_bf16 v[32:35], v[184:187], v[200:203], v[32:35]
	v_mfma_f32_16x16x32_bf16 v[20:23], v[176:179], v[208:211], v[20:23]
	v_mfma_f32_16x16x32_bf16 v[16:19], v[184:187], v[208:211], v[16:19]
	v_mfma_f32_16x16x32_bf16 v[4:7], v[176:179], v[216:219], v[4:7]
	v_mfma_f32_16x16x32_bf16 v[0:3], v[184:187], v[216:219], v[0:3]
	s_setprio 0
	s_barrier
	s_add_i32 s81, s81, 2
	s_add_u32 s14, s14, 0x100
	s_addc_u32 s15, s15, 0
	s_add_u32 s41, s41, 0x100
	s_addc_u32 s80, s80, 0
	s_cmp_gt_u32 s81, 29
	s_cbranch_scc0 .LBB0_115
	s_and_b64 vcc, exec, s[34:35]
	s_cbranch_vccz .LBB0_118
	s_barrier

.LBB0_440:
	ds_read_b128 v[64:67], v224
	ds_read_b128 v[68:71], v224 offset:1024
	ds_read_b128 v[72:75], v224 offset:2048
	ds_read_b128 v[76:79], v224 offset:3072
	ds_read_b128 v[136:139], v225
	ds_read_b128 v[140:143], v225 offset:1024
	ds_read_b128 v[148:151], v225 offset:2048
	ds_read_b128 v[156:159], v225 offset:3072
	s_add_u32 s18, s14, 0xfffc0080
	s_addc_u32 s19, s15, -1
	s_cmp_eq_u32 s73, 12
	s_cselect_b32 s41, s23, s19
	s_cselect_b32 s40, s67, s18
	s_cselect_b32 s19, s17, s72
	s_cselect_b32 s18, s70, s71
	s_add_i32 m0, s13, 0xc000
	ds_read_b128 v[160:163], v226
	ds_read_b128 v[164:167], v226 offset:1024
	ds_read_b128 v[168:171], v226 offset:2048
	ds_read_b128 v[172:175], v226 offset:3072
	ds_read_b128 v[176:179], v226 offset:4096
	ds_read_b128 v[180:183], v226 offset:5120
	ds_read_b128 v[184:187], v226 offset:6144
	ds_read_b128 v[188:191], v226 offset:7168
	global_load_lds_dwordx4 v200, s[14:15]
	s_add_i32 m0, s13, 0xe000
	s_nop 0
	global_load_lds_dwordx4 v202, s[14:15]
	s_waitcnt vmcnt(8)
	s_waitcnt lgkmcnt(0)
	s_barrier
	s_setprio 1
	s_waitcnt lgkmcnt(0)
	v_mfma_f32_16x16x32_bf16 v[152:155], v[64:67], v[160:163], v[152:155]
	v_mfma_f32_16x16x32_bf16 v[144:147], v[72:75], v[160:163], v[144:147]
	v_mfma_f32_16x16x32_bf16 v[124:127], v[64:67], v[168:171], v[124:127]
	v_mfma_f32_16x16x32_bf16 v[120:123], v[72:75], v[168:171], v[120:123]
	v_mfma_f32_16x16x32_bf16 v[108:111], v[64:67], v[176:179], v[108:111]
	v_mfma_f32_16x16x32_bf16 v[104:107], v[72:75], v[176:179], v[104:107]
	v_mfma_f32_16x16x32_bf16 v[92:95], v[64:67], v[184:187], v[92:95]
	v_mfma_f32_16x16x32_bf16 v[88:91], v[72:75], v[184:187], v[88:91]
	v_mfma_f32_16x16x32_bf16 v[152:155], v[68:71], v[164:167], v[152:155]
	v_mfma_f32_16x16x32_bf16 v[144:147], v[76:79], v[164:167], v[144:147]
	v_mfma_f32_16x16x32_bf16 v[124:127], v[68:71], v[172:175], v[124:127]
	v_mfma_f32_16x16x32_bf16 v[120:123], v[76:79], v[172:175], v[120:123]
	v_mfma_f32_16x16x32_bf16 v[108:111], v[68:71], v[180:183], v[108:111]
	v_mfma_f32_16x16x32_bf16 v[104:107], v[76:79], v[180:183], v[104:107]
	v_mfma_f32_16x16x32_bf16 v[92:95], v[68:71], v[188:191], v[92:95]
	v_mfma_f32_16x16x32_bf16 v[88:91], v[76:79], v[188:191], v[88:91]
	s_setprio 0
	s_setprio 1
	v_mfma_f32_16x16x32_bf16 v[132:135], v[136:139], v[160:163], v[132:135]
	v_mfma_f32_16x16x32_bf16 v[128:131], v[148:151], v[160:163], v[128:131]
	v_mfma_f32_16x16x32_bf16 v[116:119], v[136:139], v[168:171], v[116:119]
	v_mfma_f32_16x16x32_bf16 v[112:115], v[148:151], v[168:171], v[112:115]
	v_mfma_f32_16x16x32_bf16 v[100:103], v[136:139], v[176:179], v[100:103]
	v_mfma_f32_16x16x32_bf16 v[96:99], v[148:151], v[176:179], v[96:99]
	v_mfma_f32_16x16x32_bf16 v[84:87], v[136:139], v[184:187], v[84:87]
	v_mfma_f32_16x16x32_bf16 v[80:83], v[148:151], v[184:187], v[80:83]
	v_mfma_f32_16x16x32_bf16 v[132:135], v[140:143], v[164:167], v[132:135]
	v_mfma_f32_16x16x32_bf16 v[128:131], v[156:159], v[164:167], v[128:131]
	v_mfma_f32_16x16x32_bf16 v[116:119], v[140:143], v[172:175], v[116:119]
	v_mfma_f32_16x16x32_bf16 v[112:115], v[156:159], v[172:175], v[112:115]
	v_mfma_f32_16x16x32_bf16 v[100:103], v[140:143], v[180:183], v[100:103]
	v_mfma_f32_16x16x32_bf16 v[96:99], v[156:159], v[180:183], v[96:99]
	v_mfma_f32_16x16x32_bf16 v[84:87], v[140:143], v[188:191], v[84:87]
	v_mfma_f32_16x16x32_bf16 v[80:83], v[156:159], v[188:191], v[80:83]
	s_setprio 0
	s_barrier
	s_add_i32 s74, s64, s56
	s_mov_b64 s[98:99], s[18:19]
	s_mov_b32 m0, s74
	ds_read_b128 v[160:163], v226 offset:16384
	ds_read_b128 v[164:167], v226 offset:17408
	ds_read_b128 v[168:171], v226 offset:18432
	ds_read_b128 v[172:175], v226 offset:19456
	ds_read_b128 v[176:179], v226 offset:20480
	ds_read_b128 v[180:183], v226 offset:21504
	ds_read_b128 v[184:187], v226 offset:22528
	ds_read_b128 v[188:191], v226 offset:23552
	global_load_lds_dwordx4 v194, s[18:19]
	s_add_i32 m0, s74, 0x2000
	s_add_u32 s74, s18, 0x40000
	s_addc_u32 s75, s19, 0
	s_add_i32 s76, s65, s56
	global_load_lds_dwordx4 v198, s[18:19]
	s_mov_b32 m0, s76
	s_mov_b64 s[100:101], s[40:41]
	global_load_lds_dwordx4 v194, s[74:75]
	s_add_i32 m0, s76, 0x2000
	s_nop 0
	global_load_lds_dwordx4 v198, s[74:75]
	s_mov_b32 m0, s13
	s_nop 0
	global_load_lds_dwordx4 v192, s[40:41]
	s_mov_b32 m0, s57
	s_nop 0
	global_load_lds_dwordx4 v196, s[40:41]
	s_waitcnt vmcnt(8)
	s_waitcnt lgkmcnt(0)
	s_barrier
	s_setprio 1
	s_waitcnt lgkmcnt(0)
	v_mfma_f32_16x16x32_bf16 v[60:63], v[64:67], v[160:163], v[60:63]
	v_mfma_f32_16x16x32_bf16 v[56:59], v[72:75], v[160:163], v[56:59]
	v_mfma_f32_16x16x32_bf16 v[44:47], v[64:67], v[168:171], v[44:47]
	v_mfma_f32_16x16x32_bf16 v[40:43], v[72:75], v[168:171], v[40:43]
	v_mfma_f32_16x16x32_bf16 v[28:31], v[64:67], v[176:179], v[28:31]
	v_mfma_f32_16x16x32_bf16 v[24:27], v[72:75], v[176:179], v[24:27]
	v_mfma_f32_16x16x32_bf16 v[12:15], v[64:67], v[184:187], v[12:15]
	v_mfma_f32_16x16x32_bf16 v[8:11], v[72:75], v[184:187], v[8:11]
	v_mfma_f32_16x16x32_bf16 v[60:63], v[68:71], v[164:167], v[60:63]
	v_mfma_f32_16x16x32_bf16 v[56:59], v[76:79], v[164:167], v[56:59]
	v_mfma_f32_16x16x32_bf16 v[44:47], v[68:71], v[172:175], v[44:47]
	v_mfma_f32_16x16x32_bf16 v[40:43], v[76:79], v[172:175], v[40:43]
	v_mfma_f32_16x16x32_bf16 v[28:31], v[68:71], v[180:183], v[28:31]
	v_mfma_f32_16x16x32_bf16 v[24:27], v[76:79], v[180:183], v[24:27]
	v_mfma_f32_16x16x32_bf16 v[12:15], v[68:71], v[188:191], v[12:15]
	v_mfma_f32_16x16x32_bf16 v[8:11], v[76:79], v[188:191], v[8:11]
	s_setprio 0
	s_setprio 1
	v_mfma_f32_16x16x32_bf16 v[52:55], v[136:139], v[160:163], v[52:55]
	v_mfma_f32_16x16x32_bf16 v[48:51], v[148:151], v[160:163], v[48:51]
	v_mfma_f32_16x16x32_bf16 v[36:39], v[136:139], v[168:171], v[36:39]
	v_mfma_f32_16x16x32_bf16 v[32:35], v[148:151], v[168:171], v[32:35]
	v_mfma_f32_16x16x32_bf16 v[20:23], v[136:139], v[176:179], v[20:23]
	v_mfma_f32_16x16x32_bf16 v[16:19], v[148:151], v[176:179], v[16:19]
	v_mfma_f32_16x16x32_bf16 v[4:7], v[136:139], v[184:187], v[4:7]
	v_mfma_f32_16x16x32_bf16 v[0:3], v[148:151], v[184:187], v[0:3]
	v_mfma_f32_16x16x32_bf16 v[52:55], v[140:143], v[164:167], v[52:55]
	v_mfma_f32_16x16x32_bf16 v[48:51], v[156:159], v[164:167], v[48:51]
	v_mfma_f32_16x16x32_bf16 v[36:39], v[140:143], v[172:175], v[36:39]
	v_mfma_f32_16x16x32_bf16 v[32:35], v[156:159], v[172:175], v[32:35]
	v_mfma_f32_16x16x32_bf16 v[20:23], v[140:143], v[180:183], v[20:23]
	v_mfma_f32_16x16x32_bf16 v[16:19], v[156:159], v[180:183], v[16:19]
	v_mfma_f32_16x16x32_bf16 v[4:7], v[140:143], v[188:191], v[4:7]
	v_mfma_f32_16x16x32_bf16 v[0:3], v[156:159], v[188:191], v[0:3]
	s_setprio 0
	s_barrier
	s_add_i32 s74, 0, 0x18000
	s_add_i32 s75, 0, 0x1c000
	v_add_u32_e32 v76, s74, v222
	v_add_u32_e32 v156, s75, v222
	ds_read_b128 v[64:67], v76
	ds_read_b128 v[68:71], v76 offset:1024
	ds_read_b128 v[72:75], v76 offset:2048
	ds_read_b128 v[76:79], v76 offset:3072
	ds_read_b128 v[136:139], v156
	ds_read_b128 v[140:143], v156 offset:1024
	ds_read_b128 v[148:151], v156 offset:2048
	ds_read_b128 v[156:159], v156 offset:3072
	s_add_u32 s40, s40, 0x40000
	s_addc_u32 s41, s41, 0
	s_mov_b32 m0, s58
	ds_read_b128 v[160:163], v226 offset:32768
	ds_read_b128 v[164:167], v226 offset:33792
	ds_read_b128 v[168:171], v226 offset:34816
	ds_read_b128 v[172:175], v226 offset:35840
	ds_read_b128 v[176:179], v226 offset:36864
	ds_read_b128 v[180:183], v226 offset:37888
	ds_read_b128 v[184:187], v226 offset:38912
	ds_read_b128 v[188:191], v226 offset:39936
	global_load_lds_dwordx4 v192, s[40:41]
	s_mov_b32 m0, s59
	s_nop 0
	global_load_lds_dwordx4 v196, s[40:41]
	s_waitcnt vmcnt(8)
	s_waitcnt lgkmcnt(0)
	s_barrier
	s_setprio 1
	s_waitcnt lgkmcnt(0)
	v_mfma_f32_16x16x32_bf16 v[152:155], v[64:67], v[160:163], v[152:155]
	v_mfma_f32_16x16x32_bf16 v[144:147], v[72:75], v[160:163], v[144:147]
	v_mfma_f32_16x16x32_bf16 v[124:127], v[64:67], v[168:171], v[124:127]
	v_mfma_f32_16x16x32_bf16 v[120:123], v[72:75], v[168:171], v[120:123]
	v_mfma_f32_16x16x32_bf16 v[108:111], v[64:67], v[176:179], v[108:111]
	v_mfma_f32_16x16x32_bf16 v[104:107], v[72:75], v[176:179], v[104:107]
	v_mfma_f32_16x16x32_bf16 v[92:95], v[64:67], v[184:187], v[92:95]
	v_mfma_f32_16x16x32_bf16 v[88:91], v[72:75], v[184:187], v[88:91]
	v_mfma_f32_16x16x32_bf16 v[152:155], v[68:71], v[164:167], v[152:155]
	v_mfma_f32_16x16x32_bf16 v[144:147], v[76:79], v[164:167], v[144:147]
	v_mfma_f32_16x16x32_bf16 v[124:127], v[68:71], v[172:175], v[124:127]
	v_mfma_f32_16x16x32_bf16 v[120:123], v[76:79], v[172:175], v[120:123]
	v_mfma_f32_16x16x32_bf16 v[108:111], v[68:71], v[180:183], v[108:111]
	v_mfma_f32_16x16x32_bf16 v[104:107], v[76:79], v[180:183], v[104:107]
	v_mfma_f32_16x16x32_bf16 v[92:95], v[68:71], v[188:191], v[92:95]
	v_mfma_f32_16x16x32_bf16 v[88:91], v[76:79], v[188:191], v[88:91]
	s_setprio 0
	s_setprio 1
	v_mfma_f32_16x16x32_bf16 v[132:135], v[136:139], v[160:163], v[132:135]
	v_mfma_f32_16x16x32_bf16 v[128:131], v[148:151], v[160:163], v[128:131]
	v_mfma_f32_16x16x32_bf16 v[116:119], v[136:139], v[168:171], v[116:119]
	v_mfma_f32_16x16x32_bf16 v[112:115], v[148:151], v[168:171], v[112:115]
	v_mfma_f32_16x16x32_bf16 v[100:103], v[136:139], v[176:179], v[100:103]
	v_mfma_f32_16x16x32_bf16 v[96:99], v[148:151], v[176:179], v[96:99]
	v_mfma_f32_16x16x32_bf16 v[84:87], v[136:139], v[184:187], v[84:87]
	v_mfma_f32_16x16x32_bf16 v[80:83], v[148:151], v[184:187], v[80:83]
	v_mfma_f32_16x16x32_bf16 v[132:135], v[140:143], v[164:167], v[132:135]
	v_mfma_f32_16x16x32_bf16 v[128:131], v[156:159], v[164:167], v[128:131]
	v_mfma_f32_16x16x32_bf16 v[116:119], v[140:143], v[172:175], v[116:119]
	v_mfma_f32_16x16x32_bf16 v[112:115], v[156:159], v[172:175], v[112:115]
	v_mfma_f32_16x16x32_bf16 v[100:103], v[140:143], v[180:183], v[100:103]
	v_mfma_f32_16x16x32_bf16 v[96:99], v[156:159], v[180:183], v[96:99]
	v_mfma_f32_16x16x32_bf16 v[84:87], v[140:143], v[188:191], v[84:87]
	v_mfma_f32_16x16x32_bf16 v[80:83], v[156:159], v[188:191], v[80:83]
	s_setprio 0
	s_barrier
	s_add_i32 s40, s74, s56
	s_add_i32 m0, s40, 0xffffff80
	ds_read_b128 v[160:163], v226 offset:49152
	ds_read_b128 v[164:167], v226 offset:50176
	ds_read_b128 v[168:171], v226 offset:51200
	ds_read_b128 v[172:175], v226 offset:52224
	ds_read_b128 v[176:179], v226 offset:53248
	ds_read_b128 v[180:183], v226 offset:54272
	ds_read_b128 v[184:187], v226 offset:55296
	ds_read_b128 v[188:191], v226 offset:56320
	global_load_lds_dwordx4 v194, s[98:99] offset:128
	s_add_i32 m0, s40, 0x1f80
	s_add_u32 s18, s18, 0x40080
	s_addc_u32 s19, s19, 0
	s_add_i32 s40, s75, s56
	global_load_lds_dwordx4 v198, s[98:99] offset:128
	s_mov_b32 m0, s40
	s_nop 0
	global_load_lds_dwordx4 v194, s[18:19]
	s_add_i32 m0, s40, 0x2000
	s_nop 0
	global_load_lds_dwordx4 v198, s[18:19]
	s_add_i32 m0, s61, 0xffffff80
	s_nop 0
	global_load_lds_dwordx4 v192, s[100:101] offset:128
	s_add_i32 m0, s62, 0xffffff80
	s_nop 0
	global_load_lds_dwordx4 v196, s[100:101] offset:128
	s_waitcnt vmcnt(8)
	s_waitcnt lgkmcnt(0)
	s_barrier
	s_setprio 1
	s_waitcnt lgkmcnt(0)
	v_mfma_f32_16x16x32_bf16 v[60:63], v[64:67], v[160:163], v[60:63]
	v_mfma_f32_16x16x32_bf16 v[56:59], v[72:75], v[160:163], v[56:59]
	v_mfma_f32_16x16x32_bf16 v[44:47], v[64:67], v[168:171], v[44:47]
	v_mfma_f32_16x16x32_bf16 v[40:43], v[72:75], v[168:171], v[40:43]
	v_mfma_f32_16x16x32_bf16 v[28:31], v[64:67], v[176:179], v[28:31]
	v_mfma_f32_16x16x32_bf16 v[24:27], v[72:75], v[176:179], v[24:27]
	v_mfma_f32_16x16x32_bf16 v[12:15], v[64:67], v[184:187], v[12:15]
	v_mfma_f32_16x16x32_bf16 v[8:11], v[72:75], v[184:187], v[8:11]
	v_mfma_f32_16x16x32_bf16 v[60:63], v[68:71], v[164:167], v[60:63]
	v_mfma_f32_16x16x32_bf16 v[56:59], v[76:79], v[164:167], v[56:59]
	v_mfma_f32_16x16x32_bf16 v[44:47], v[68:71], v[172:175], v[44:47]
	v_mfma_f32_16x16x32_bf16 v[40:43], v[76:79], v[172:175], v[40:43]
	v_mfma_f32_16x16x32_bf16 v[28:31], v[68:71], v[180:183], v[28:31]
	v_mfma_f32_16x16x32_bf16 v[24:27], v[76:79], v[180:183], v[24:27]
	v_mfma_f32_16x16x32_bf16 v[12:15], v[68:71], v[188:191], v[12:15]
	v_mfma_f32_16x16x32_bf16 v[8:11], v[76:79], v[188:191], v[8:11]
	s_setprio 0
	s_setprio 1
	v_mfma_f32_16x16x32_bf16 v[52:55], v[136:139], v[160:163], v[52:55]
	v_mfma_f32_16x16x32_bf16 v[48:51], v[148:151], v[160:163], v[48:51]
	v_mfma_f32_16x16x32_bf16 v[36:39], v[136:139], v[168:171], v[36:39]
	v_mfma_f32_16x16x32_bf16 v[32:35], v[148:151], v[168:171], v[32:35]
	v_mfma_f32_16x16x32_bf16 v[20:23], v[136:139], v[176:179], v[20:23]
	v_mfma_f32_16x16x32_bf16 v[16:19], v[148:151], v[176:179], v[16:19]
	v_mfma_f32_16x16x32_bf16 v[4:7], v[136:139], v[184:187], v[4:7]
	v_mfma_f32_16x16x32_bf16 v[0:3], v[148:151], v[184:187], v[0:3]
	v_mfma_f32_16x16x32_bf16 v[52:55], v[140:143], v[164:167], v[52:55]
	v_mfma_f32_16x16x32_bf16 v[48:51], v[156:159], v[164:167], v[48:51]
	v_mfma_f32_16x16x32_bf16 v[36:39], v[140:143], v[172:175], v[36:39]
	v_mfma_f32_16x16x32_bf16 v[32:35], v[156:159], v[172:175], v[32:35]
	v_mfma_f32_16x16x32_bf16 v[20:23], v[140:143], v[180:183], v[20:23]
	v_mfma_f32_16x16x32_bf16 v[16:19], v[156:159], v[180:183], v[16:19]
	v_mfma_f32_16x16x32_bf16 v[4:7], v[140:143], v[188:191], v[4:7]
	v_mfma_f32_16x16x32_bf16 v[0:3], v[156:159], v[188:191], v[0:3]
	s_setprio 0
	s_barrier
	s_add_i32 s73, s73, 2
	s_add_u32 s14, s14, 0x100
	s_addc_u32 s15, s15, 0
	s_add_u32 s71, s71, 0x100
	s_addc_u32 s72, s72, 0
	s_cmp_gt_u32 s73, 13
	s_cbranch_scc0 .LBB0_440
	v_lshl_or_b32 v64, s33, 8, v223
	v_readlane_b32 s72, v248, 28
	v_ashrrev_i32_e32 v65, 31, v64
	v_readlane_b32 s80, v248, 36
	v_readlane_b32 s81, v248, 37
	v_lshl_add_u32 v210, s12, 8, v221
	v_ashrrev_i32_e32 v211, 31, v210
	v_lshl_add_u64 v[68:69], v[64:65], 2, s[80:81]
	global_load_dwordx4 v[72:75], v[68:69], off offset:16
	global_load_dwordx4 v[76:79], v[68:69], off
	v_mov_b64_e32 v[212:213], s[6:7]
	v_lshlrev_b64 v[208:209], 1, v[64:65]
	v_lshlrev_b64 v[64:65], 11, v[210:211]
	v_mad_i64_i32 v[66:67], s[14:15], v210, s66, v[212:213]
	v_lshl_add_u64 v[64:65], s[4:5], 0, v[64:65]
	v_lshl_add_u64 v[136:137], v[66:67], 0, v[208:209]
	v_lshl_add_u64 v[140:141], v[64:65], 0, v[208:209]
	global_load_dwordx4 v[228:231], v[136:137], off offset:2048
	global_load_dwordx4 v[232:235], v[140:141], off
	global_load_dwordx4 v[64:67], v[68:69], off offset:528
	s_nop 0
	global_load_dwordx4 v[68:71], v[68:69], off offset:512
	v_or_b32_e32 v218, 16, v210
	v_or_b32_e32 v216, 32, v210
	v_or_b32_e32 v214, 48, v210
	v_ashrrev_i32_e32 v219, 31, v218
	v_mad_i64_i32 v[138:139], s[14:15], v218, s66, v[212:213]
	v_mad_i64_i32 v[142:143], s[14:15], v216, s66, v[212:213]
	v_mad_i64_i32 v[148:149], s[14:15], v214, s66, v[212:213]
	v_lshlrev_b64 v[150:151], 11, v[218:219]
	v_lshl_add_u64 v[138:139], v[138:139], 0, v[208:209]
	v_lshl_add_u64 v[142:143], v[142:143], 0, v[208:209]
	v_lshl_add_u64 v[164:165], v[148:149], 0, v[208:209]
	global_load_dwordx4 v[236:239], v[136:137], off offset:2304
	v_lshl_add_u64 v[166:167], s[4:5], 0, v[150:151]
	global_load_dwordx4 v[184:187], v[138:139], off offset:2048
	global_load_dwordx4 v[176:179], v[138:139], off offset:2304
	global_load_dwordx4 v[168:171], v[142:143], off offset:2048
	global_load_dwordx4 v[160:163], v[142:143], off offset:2304
	global_load_dwordx4 v[148:151], v[164:165], off offset:2048
	s_nop 0
	global_load_dwordx4 v[136:139], v[164:165], off offset:2304
	global_load_dwordx4 v[240:243], v[140:141], off offset:256
	v_ashrrev_i32_e32 v217, 31, v216
	v_ashrrev_i32_e32 v215, 31, v214
	v_lshlrev_b64 v[156:157], 11, v[216:217]
	v_lshlrev_b64 v[158:159], 11, v[214:215]
	v_lshl_add_u64 v[156:157], s[4:5], 0, v[156:157]
	v_lshl_add_u64 v[142:143], s[4:5], 0, v[158:159]
	v_lshl_add_u64 v[140:141], v[166:167], 0, v[208:209]
	v_lshl_add_u64 v[156:157], v[156:157], 0, v[208:209]
	v_lshl_add_u64 v[142:143], v[142:143], 0, v[208:209]
	global_load_dwordx4 v[188:191], v[140:141], off
	global_load_dwordx4 v[180:183], v[140:141], off offset:256
	global_load_dwordx4 v[172:175], v[156:157], off
	global_load_dwordx4 v[164:167], v[156:157], off offset:256
	s_nop 0
	global_load_dwordx4 v[156:159], v[142:143], off
	s_nop 0
	global_load_dwordx4 v[140:143], v[142:143], off offset:256
	s_and_b64 vcc, exec, s[2:3]
	s_mov_b32 s33, s16
	s_mov_b32 s12, s22
	s_mov_b64 s[18:19], s[38:39]
	v_readlane_b32 s73, v248, 29
	v_readlane_b32 s74, v248, 30
	v_readlane_b32 s75, v248, 31
	v_readlane_b32 s76, v248, 32
	v_readlane_b32 s77, v248, 33
	v_readlane_b32 s78, v248, 34
	v_readlane_b32 s79, v248, 35
	v_readlane_b32 s82, v248, 38
	v_readlane_b32 s83, v248, 39
	v_readlane_b32 s84, v248, 40
	v_readlane_b32 s85, v248, 41
	v_readlane_b32 s86, v248, 42
	v_readlane_b32 s87, v248, 43
	s_waitcnt vmcnt(0)
	v_pk_add_f32 v[144:145], v[144:145], v[72:73]
	v_pk_add_f32 v[152:153], v[152:153], v[76:77]
	v_mul_f32_e32 v144, 0xbfb8aa3b, v144
	v_mul_f32_e32 v152, 0xbfb8aa3b, v152
	v_exp_f32_e32 v152, v152
	v_exp_f32_e32 v144, v144
	v_mul_f32_e32 v145, 0xbfb8aa3b, v145
	v_pk_add_f32 v[146:147], v[146:147], v[74:75]
	v_add_f32_e32 v152, 1.0, v152
	v_exp_f32_e32 v145, v145
	v_pk_add_f32 v[154:155], v[154:155], v[78:79]
	v_rcp_f32_e32 v152, v152
	v_mul_f32_e32 v146, 0xbfb8aa3b, v146
	v_mul_f32_e32 v153, 0xbfb8aa3b, v153
	v_mul_f32_e32 v154, 0xbfb8aa3b, v154
	v_add_f32_e32 v144, 1.0, v144
	v_exp_f32_e32 v146, v146
	v_mul_f32_e32 v155, 0xbfb8aa3b, v155
	v_exp_f32_e32 v153, v153
	v_exp_f32_e32 v154, v154
	v_rcp_f32_e32 v144, v144
	v_mul_f32_e32 v147, 0xbfb8aa3b, v147
	v_lshlrev_b32_e32 v227, 16, v232
	v_exp_f32_e32 v155, v155
	v_add_f32_e32 v145, 1.0, v145
	v_exp_f32_e32 v147, v147
	v_lshlrev_b32_e32 v211, 16, v228
	v_mul_f32_e32 v152, v152, v227
	v_rcp_f32_e32 v145, v145
	v_mul_f32_e32 v152, v152, v211
	v_lshlrev_b32_e32 v211, 16, v234
	v_add_f32_e32 v146, 1.0, v146
	v_add_f32_e32 v153, 1.0, v153
	v_add_f32_e32 v154, 1.0, v154
	v_mul_f32_e32 v144, v144, v211
	v_lshlrev_b32_e32 v211, 16, v230
	v_rcp_f32_e32 v146, v146
	v_pk_add_f32 v[132:133], v[132:133], v[68:69]
	v_add_f32_e32 v155, 1.0, v155
	v_rcp_f32_e32 v153, v153
	v_rcp_f32_e32 v154, v154
	v_mul_f32_e32 v144, v144, v211
	v_and_b32_e32 v211, 0xffff0000, v234
	v_add_f32_e32 v147, 1.0, v147
	v_mul_f32_e32 v132, 0xbfb8aa3b, v132
	v_rcp_f32_e32 v155, v155
	v_mul_f32_e32 v145, v145, v211
	v_and_b32_e32 v211, 0xffff0000, v230
	v_rcp_f32_e32 v147, v147
	v_exp_f32_e32 v132, v132
	v_mul_f32_e32 v145, v145, v211
	v_lshlrev_b32_e32 v211, 16, v235
	v_mul_f32_e32 v133, 0xbfb8aa3b, v133
	v_and_b32_e32 v215, 0xffff0000, v228
	v_lshlrev_b32_e32 v217, 16, v229
	v_and_b32_e32 v219, 0xffff0000, v229
	v_and_b32_e32 v228, 0xffff0000, v232
	v_lshlrev_b32_e32 v229, 16, v233
	v_mul_f32_e32 v146, v146, v211
	v_lshlrev_b32_e32 v211, 16, v231
	v_pk_add_f32 v[134:135], v[134:135], v[70:71]
	v_exp_f32_e32 v133, v133
	v_and_b32_e32 v232, 0xffff0000, v233
	v_mul_f32_e32 v153, v153, v228
	v_mul_f32_e32 v154, v154, v229
	v_mul_f32_e32 v146, v146, v211
	v_and_b32_e32 v211, 0xffff0000, v235
	v_mul_f32_e32 v134, 0xbfb8aa3b, v134
	v_mul_f32_e32 v155, v155, v232
	v_mul_f32_e32 v153, v153, v215
	v_mul_f32_e32 v154, v154, v217
	v_mul_f32_e32 v147, v147, v211
	v_and_b32_e32 v211, 0xffff0000, v231
	v_add_f32_e32 v132, 1.0, v132
	v_exp_f32_e32 v134, v134
	v_mul_f32_e32 v155, v155, v219
	v_mul_f32_e32 v147, v147, v211
	v_cvt_pk_bf16_f32 v152, v152, v153
	v_cvt_pk_bf16_f32 v153, v154, v155
	v_cvt_pk_bf16_f32 v154, v144, v145
	v_mov_b64_e32 v[144:145], s[8:9]
	v_rcp_f32_e32 v132, v132
	v_mul_f32_e32 v135, 0xbfb8aa3b, v135
	v_cvt_pk_bf16_f32 v155, v146, v147
	v_mad_i64_i32 v[146:147], s[14:15], v210, s66, v[144:145]
	v_pk_add_f32 v[128:129], v[128:129], v[64:65]
	v_add_f32_e32 v133, 1.0, v133
	v_exp_f32_e32 v135, v135
	v_lshl_add_u64 v[146:147], v[146:147], 0, v[208:209]
	v_rcp_f32_e32 v133, v133
	v_mul_f32_e32 v128, 0xbfb8aa3b, v128
	global_store_dwordx4 v[146:147], v[152:155], off
	v_add_f32_e32 v134, 1.0, v134
	v_exp_f32_e32 v128, v128
	v_lshlrev_b32_e32 v152, 16, v240
	v_mul_f32_e32 v132, v132, v152
	v_lshlrev_b32_e32 v152, 16, v236
	v_rcp_f32_e32 v134, v134
	v_mul_f32_e32 v132, v132, v152
	v_and_b32_e32 v152, 0xffff0000, v240
	v_add_f32_e32 v135, 1.0, v135
	v_mul_f32_e32 v133, v133, v152
	v_and_b32_e32 v152, 0xffff0000, v236
	v_rcp_f32_e32 v135, v135
	v_mul_f32_e32 v133, v133, v152
	v_lshlrev_b32_e32 v152, 16, v241
	v_add_f32_e32 v128, 1.0, v128
	v_mul_f32_e32 v134, v134, v152
	v_lshlrev_b32_e32 v152, 16, v237
	v_rcp_f32_e32 v128, v128
	v_mul_f32_e32 v129, 0xbfb8aa3b, v129
	v_mul_f32_e32 v134, v134, v152
	v_and_b32_e32 v152, 0xffff0000, v241
	v_exp_f32_e32 v129, v129
	v_mul_f32_e32 v135, v135, v152
	v_and_b32_e32 v152, 0xffff0000, v237
	v_mul_f32_e32 v135, v135, v152
	v_lshlrev_b32_e32 v152, 16, v242
	v_pk_add_f32 v[130:131], v[130:131], v[66:67]
	v_mul_f32_e32 v128, v128, v152
	v_lshlrev_b32_e32 v152, 16, v238
	v_mul_f32_e32 v152, v128, v152
	v_add_f32_e32 v128, 1.0, v129
	v_mul_f32_e32 v129, 0xbfb8aa3b, v130
	v_exp_f32_e32 v129, v129
	v_rcp_f32_e32 v128, v128
	v_mul_f32_e32 v131, 0xbfb8aa3b, v131
	v_exp_f32_e32 v131, v131
	v_add_f32_e32 v129, 1.0, v129
	v_rcp_f32_e32 v129, v129
	v_and_b32_e32 v130, 0xffff0000, v242
	v_pk_add_f32 v[124:125], v[124:125], v[76:77]
	v_mul_f32_e32 v128, v128, v130
	v_and_b32_e32 v130, 0xffff0000, v238
	v_mul_f32_e32 v124, 0xbfb8aa3b, v124
	v_mul_f32_e32 v130, v128, v130
	v_lshlrev_b32_e32 v128, 16, v243
	v_exp_f32_e32 v124, v124
	v_mul_f32_e32 v128, v129, v128
	v_add_f32_e32 v129, 1.0, v131
	v_mul_f32_e32 v125, 0xbfb8aa3b, v125
	v_rcp_f32_e32 v129, v129
	v_pk_add_f32 v[126:127], v[126:127], v[78:79]
	v_exp_f32_e32 v125, v125
	v_mul_f32_e32 v126, 0xbfb8aa3b, v126
	v_lshlrev_b32_e32 v131, 16, v239
	v_add_f32_e32 v124, 1.0, v124
	v_exp_f32_e32 v126, v126
	v_mul_f32_e32 v131, v128, v131
	v_and_b32_e32 v128, 0xffff0000, v243
	v_rcp_f32_e32 v124, v124
	v_mul_f32_e32 v127, 0xbfb8aa3b, v127
	v_mul_f32_e32 v128, v129, v128
	v_and_b32_e32 v129, 0xffff0000, v239
	v_pk_add_f32 v[120:121], v[120:121], v[72:73]
	v_add_f32_e32 v125, 1.0, v125
	v_exp_f32_e32 v127, v127
	v_mul_f32_e32 v153, v128, v129
	v_cvt_pk_bf16_f32 v128, v132, v133
	v_rcp_f32_e32 v125, v125
	v_mul_f32_e32 v120, 0xbfb8aa3b, v120
	v_cvt_pk_bf16_f32 v129, v134, v135
	v_cvt_pk_bf16_f32 v130, v152, v130
	v_cvt_pk_bf16_f32 v131, v131, v153
	global_store_dwordx4 v[146:147], v[128:131], off offset:256
	v_add_f32_e32 v126, 1.0, v126
	v_exp_f32_e32 v120, v120
	v_lshlrev_b32_e32 v128, 16, v188
	v_mul_f32_e32 v124, v124, v128
	v_lshlrev_b32_e32 v128, 16, v184
	v_rcp_f32_e32 v126, v126
	v_mul_f32_e32 v124, v124, v128
	v_and_b32_e32 v128, 0xffff0000, v188
	v_add_f32_e32 v127, 1.0, v127
	v_mul_f32_e32 v125, v125, v128
	v_and_b32_e32 v128, 0xffff0000, v184
	v_rcp_f32_e32 v127, v127
	v_mul_f32_e32 v125, v125, v128
	v_lshlrev_b32_e32 v128, 16, v189
	v_add_f32_e32 v120, 1.0, v120
	v_mul_f32_e32 v126, v126, v128
	v_lshlrev_b32_e32 v128, 16, v185
	v_rcp_f32_e32 v120, v120
	v_mul_f32_e32 v121, 0xbfb8aa3b, v121
	v_mul_f32_e32 v126, v126, v128
	v_and_b32_e32 v128, 0xffff0000, v189
	v_exp_f32_e32 v121, v121
	v_mul_f32_e32 v127, v127, v128
	v_and_b32_e32 v128, 0xffff0000, v185
	v_mul_f32_e32 v127, v127, v128
	v_lshlrev_b32_e32 v128, 16, v190
	v_pk_add_f32 v[122:123], v[122:123], v[74:75]
	v_mul_f32_e32 v120, v120, v128
	v_lshlrev_b32_e32 v128, 16, v186
	v_mul_f32_e32 v128, v120, v128
	v_add_f32_e32 v120, 1.0, v121
	v_mul_f32_e32 v121, 0xbfb8aa3b, v122
	v_exp_f32_e32 v121, v121
	v_rcp_f32_e32 v120, v120
	v_mul_f32_e32 v123, 0xbfb8aa3b, v123
	v_exp_f32_e32 v123, v123
	v_add_f32_e32 v121, 1.0, v121
	v_rcp_f32_e32 v121, v121
	v_and_b32_e32 v122, 0xffff0000, v190
	v_mul_f32_e32 v120, v120, v122
	v_and_b32_e32 v122, 0xffff0000, v186
	v_pk_add_f32 v[116:117], v[116:117], v[68:69]
	v_mul_f32_e32 v122, v120, v122
	v_lshlrev_b32_e32 v120, 16, v191
	v_mul_f32_e32 v116, 0xbfb8aa3b, v116
	v_mul_f32_e32 v120, v121, v120
	v_add_f32_e32 v121, 1.0, v123
	v_exp_f32_e32 v116, v116
	v_rcp_f32_e32 v121, v121
	v_mul_f32_e32 v117, 0xbfb8aa3b, v117
	v_pk_add_f32 v[118:119], v[118:119], v[70:71]
	v_exp_f32_e32 v117, v117
	v_lshlrev_b32_e32 v123, 16, v187
	v_mul_f32_e32 v118, 0xbfb8aa3b, v118
	v_mul_f32_e32 v123, v120, v123
	v_and_b32_e32 v120, 0xffff0000, v191
	v_add_f32_e32 v116, 1.0, v116
	v_exp_f32_e32 v118, v118
	v_mul_f32_e32 v120, v121, v120
	v_and_b32_e32 v121, 0xffff0000, v187
	v_rcp_f32_e32 v116, v116
	v_mul_f32_e32 v119, 0xbfb8aa3b, v119
	v_mul_f32_e32 v129, v120, v121
	v_cvt_pk_bf16_f32 v120, v124, v125
	v_mad_i64_i32 v[124:125], s[14:15], v218, s66, v[144:145]
	v_pk_add_f32 v[112:113], v[112:113], v[64:65]
	v_add_f32_e32 v117, 1.0, v117
	v_exp_f32_e32 v119, v119
	v_lshl_add_u64 v[124:125], v[124:125], 0, v[208:209]
	v_rcp_f32_e32 v117, v117
	v_mul_f32_e32 v112, 0xbfb8aa3b, v112
	v_cvt_pk_bf16_f32 v121, v126, v127
	v_cvt_pk_bf16_f32 v122, v128, v122
	v_cvt_pk_bf16_f32 v123, v123, v129
	global_store_dwordx4 v[124:125], v[120:123], off
	v_add_f32_e32 v118, 1.0, v118
	v_exp_f32_e32 v112, v112
	v_lshlrev_b32_e32 v120, 16, v180
	v_mul_f32_e32 v116, v116, v120
	v_lshlrev_b32_e32 v120, 16, v176
	v_rcp_f32_e32 v118, v118
	v_mul_f32_e32 v116, v116, v120
	v_and_b32_e32 v120, 0xffff0000, v180
	v_add_f32_e32 v119, 1.0, v119
	v_mul_f32_e32 v117, v117, v120
	v_and_b32_e32 v120, 0xffff0000, v176
	v_rcp_f32_e32 v119, v119
	v_mul_f32_e32 v117, v117, v120
	v_lshlrev_b32_e32 v120, 16, v181
	v_add_f32_e32 v112, 1.0, v112
	v_mul_f32_e32 v118, v118, v120
	v_lshlrev_b32_e32 v120, 16, v177
	v_rcp_f32_e32 v112, v112
	v_mul_f32_e32 v113, 0xbfb8aa3b, v113
	v_mul_f32_e32 v118, v118, v120
	v_and_b32_e32 v120, 0xffff0000, v181
	v_exp_f32_e32 v113, v113
	v_mul_f32_e32 v119, v119, v120
	v_and_b32_e32 v120, 0xffff0000, v177
	v_mul_f32_e32 v119, v119, v120
	v_lshlrev_b32_e32 v120, 16, v182
	v_pk_add_f32 v[114:115], v[114:115], v[66:67]
	v_mul_f32_e32 v112, v112, v120
	v_lshlrev_b32_e32 v120, 16, v178
	v_mul_f32_e32 v120, v112, v120
	v_add_f32_e32 v112, 1.0, v113
	v_mul_f32_e32 v113, 0xbfb8aa3b, v114
	v_exp_f32_e32 v113, v113
	v_rcp_f32_e32 v112, v112
	v_mul_f32_e32 v115, 0xbfb8aa3b, v115
	v_exp_f32_e32 v115, v115
	v_add_f32_e32 v113, 1.0, v113
	v_rcp_f32_e32 v113, v113
	v_and_b32_e32 v114, 0xffff0000, v182
	v_pk_add_f32 v[108:109], v[108:109], v[76:77]
	v_mul_f32_e32 v112, v112, v114
	v_and_b32_e32 v114, 0xffff0000, v178
	v_mul_f32_e32 v108, 0xbfb8aa3b, v108
	v_mul_f32_e32 v114, v112, v114
	v_lshlrev_b32_e32 v112, 16, v183
	v_exp_f32_e32 v108, v108
	v_mul_f32_e32 v112, v113, v112
	v_add_f32_e32 v113, 1.0, v115
	v_mul_f32_e32 v109, 0xbfb8aa3b, v109
	v_rcp_f32_e32 v113, v113
	v_pk_add_f32 v[110:111], v[110:111], v[78:79]
	v_exp_f32_e32 v109, v109
	v_mul_f32_e32 v110, 0xbfb8aa3b, v110
	v_lshlrev_b32_e32 v115, 16, v179
	v_add_f32_e32 v108, 1.0, v108
	v_exp_f32_e32 v110, v110
	v_mul_f32_e32 v115, v112, v115
	v_and_b32_e32 v112, 0xffff0000, v183
	v_rcp_f32_e32 v108, v108
	v_mul_f32_e32 v111, 0xbfb8aa3b, v111
	v_mul_f32_e32 v112, v113, v112
	v_and_b32_e32 v113, 0xffff0000, v179
	v_pk_add_f32 v[104:105], v[104:105], v[72:73]
	v_add_f32_e32 v109, 1.0, v109
	v_exp_f32_e32 v111, v111
	v_mul_f32_e32 v121, v112, v113
	v_cvt_pk_bf16_f32 v112, v116, v117
	v_rcp_f32_e32 v109, v109
	v_mul_f32_e32 v104, 0xbfb8aa3b, v104
	v_cvt_pk_bf16_f32 v113, v118, v119
	v_cvt_pk_bf16_f32 v114, v120, v114
	v_cvt_pk_bf16_f32 v115, v115, v121
	global_store_dwordx4 v[124:125], v[112:115], off offset:256
	v_add_f32_e32 v110, 1.0, v110
	v_exp_f32_e32 v104, v104
	v_lshlrev_b32_e32 v112, 16, v172
	v_mul_f32_e32 v108, v108, v112
	v_lshlrev_b32_e32 v112, 16, v168
	v_rcp_f32_e32 v110, v110
	v_mul_f32_e32 v108, v108, v112
	v_and_b32_e32 v112, 0xffff0000, v172
	v_add_f32_e32 v111, 1.0, v111
	v_mul_f32_e32 v109, v109, v112
	v_and_b32_e32 v112, 0xffff0000, v168
	v_rcp_f32_e32 v111, v111
	v_mul_f32_e32 v109, v109, v112
	v_lshlrev_b32_e32 v112, 16, v173
	v_add_f32_e32 v104, 1.0, v104
	v_mul_f32_e32 v110, v110, v112
	v_lshlrev_b32_e32 v112, 16, v169
	v_rcp_f32_e32 v104, v104
	v_mul_f32_e32 v105, 0xbfb8aa3b, v105
	v_mul_f32_e32 v110, v110, v112
	v_and_b32_e32 v112, 0xffff0000, v173
	v_exp_f32_e32 v105, v105
	v_mul_f32_e32 v111, v111, v112
	v_and_b32_e32 v112, 0xffff0000, v169
	v_mul_f32_e32 v111, v111, v112
	v_lshlrev_b32_e32 v112, 16, v174
	v_pk_add_f32 v[106:107], v[106:107], v[74:75]
	v_mul_f32_e32 v104, v104, v112
	v_lshlrev_b32_e32 v112, 16, v170
	v_mul_f32_e32 v112, v104, v112
	v_add_f32_e32 v104, 1.0, v105
	v_mul_f32_e32 v105, 0xbfb8aa3b, v106
	v_exp_f32_e32 v105, v105
	v_rcp_f32_e32 v104, v104
	v_mul_f32_e32 v107, 0xbfb8aa3b, v107
	v_exp_f32_e32 v107, v107
	v_add_f32_e32 v105, 1.0, v105
	v_rcp_f32_e32 v105, v105
	v_and_b32_e32 v106, 0xffff0000, v174
	v_mul_f32_e32 v104, v104, v106
	v_and_b32_e32 v106, 0xffff0000, v170
	v_pk_add_f32 v[100:101], v[100:101], v[68:69]
	v_mul_f32_e32 v106, v104, v106
	v_lshlrev_b32_e32 v104, 16, v175
	v_mul_f32_e32 v100, 0xbfb8aa3b, v100
	v_mul_f32_e32 v104, v105, v104
	v_add_f32_e32 v105, 1.0, v107
	v_exp_f32_e32 v100, v100
	v_rcp_f32_e32 v105, v105
	v_mul_f32_e32 v101, 0xbfb8aa3b, v101
	v_pk_add_f32 v[102:103], v[102:103], v[70:71]
	v_exp_f32_e32 v101, v101
	v_lshlrev_b32_e32 v107, 16, v171
	v_mul_f32_e32 v102, 0xbfb8aa3b, v102
	v_mul_f32_e32 v107, v104, v107
	v_and_b32_e32 v104, 0xffff0000, v175
	v_add_f32_e32 v100, 1.0, v100
	v_exp_f32_e32 v102, v102
	v_mul_f32_e32 v104, v105, v104
	v_and_b32_e32 v105, 0xffff0000, v171
	v_rcp_f32_e32 v100, v100
	v_mul_f32_e32 v103, 0xbfb8aa3b, v103
	v_mul_f32_e32 v113, v104, v105
	v_cvt_pk_bf16_f32 v104, v108, v109
	v_mad_i64_i32 v[108:109], s[14:15], v216, s66, v[144:145]
	v_pk_add_f32 v[96:97], v[96:97], v[64:65]
	v_add_f32_e32 v101, 1.0, v101
	v_exp_f32_e32 v103, v103
	v_lshl_add_u64 v[108:109], v[108:109], 0, v[208:209]
	v_rcp_f32_e32 v101, v101
	v_mul_f32_e32 v96, 0xbfb8aa3b, v96
	v_cvt_pk_bf16_f32 v105, v110, v111
	v_cvt_pk_bf16_f32 v106, v112, v106
	v_cvt_pk_bf16_f32 v107, v107, v113
	global_store_dwordx4 v[108:109], v[104:107], off
	v_add_f32_e32 v102, 1.0, v102
	v_exp_f32_e32 v96, v96
	v_lshlrev_b32_e32 v104, 16, v164
	v_mul_f32_e32 v100, v100, v104
	v_lshlrev_b32_e32 v104, 16, v160
	v_rcp_f32_e32 v102, v102
	v_mul_f32_e32 v100, v100, v104
	v_and_b32_e32 v104, 0xffff0000, v164
	v_add_f32_e32 v103, 1.0, v103
	v_mul_f32_e32 v101, v101, v104
	v_and_b32_e32 v104, 0xffff0000, v160
	v_rcp_f32_e32 v103, v103
	v_mul_f32_e32 v101, v101, v104
	v_lshlrev_b32_e32 v104, 16, v165
	v_add_f32_e32 v96, 1.0, v96
	v_mul_f32_e32 v102, v102, v104
	v_lshlrev_b32_e32 v104, 16, v161
	v_rcp_f32_e32 v96, v96
	v_mul_f32_e32 v97, 0xbfb8aa3b, v97
	v_mul_f32_e32 v102, v102, v104
	v_and_b32_e32 v104, 0xffff0000, v165
	v_exp_f32_e32 v97, v97
	v_mul_f32_e32 v103, v103, v104
	v_and_b32_e32 v104, 0xffff0000, v161
	v_mul_f32_e32 v103, v103, v104
	v_lshlrev_b32_e32 v104, 16, v166
	v_pk_add_f32 v[98:99], v[98:99], v[66:67]
	v_mul_f32_e32 v96, v96, v104
	v_lshlrev_b32_e32 v104, 16, v162
	v_mul_f32_e32 v104, v96, v104
	v_add_f32_e32 v96, 1.0, v97
	v_mul_f32_e32 v97, 0xbfb8aa3b, v98
	v_exp_f32_e32 v97, v97
	v_rcp_f32_e32 v96, v96
	v_mul_f32_e32 v99, 0xbfb8aa3b, v99
	v_exp_f32_e32 v99, v99
	v_add_f32_e32 v97, 1.0, v97
	v_rcp_f32_e32 v97, v97
	v_and_b32_e32 v98, 0xffff0000, v166
	v_pk_add_f32 v[92:93], v[92:93], v[76:77]
	v_mul_f32_e32 v96, v96, v98
	v_and_b32_e32 v98, 0xffff0000, v162
	v_mul_f32_e32 v92, 0xbfb8aa3b, v92
	v_mul_f32_e32 v98, v96, v98
	v_lshlrev_b32_e32 v96, 16, v167
	v_exp_f32_e32 v92, v92
	v_mul_f32_e32 v96, v97, v96
	v_add_f32_e32 v97, 1.0, v99
	v_mul_f32_e32 v93, 0xbfb8aa3b, v93
	v_rcp_f32_e32 v97, v97
	v_pk_add_f32 v[94:95], v[94:95], v[78:79]
	v_exp_f32_e32 v93, v93
	v_mul_f32_e32 v94, 0xbfb8aa3b, v94
	v_lshlrev_b32_e32 v99, 16, v163
	v_add_f32_e32 v92, 1.0, v92
	v_exp_f32_e32 v94, v94
	v_mul_f32_e32 v99, v96, v99
	v_and_b32_e32 v96, 0xffff0000, v167
	v_rcp_f32_e32 v92, v92
	v_mul_f32_e32 v95, 0xbfb8aa3b, v95
	v_mul_f32_e32 v96, v97, v96
	v_and_b32_e32 v97, 0xffff0000, v163
	v_pk_add_f32 v[88:89], v[88:89], v[72:73]
	v_add_f32_e32 v93, 1.0, v93
	v_exp_f32_e32 v95, v95
	v_mul_f32_e32 v105, v96, v97
	v_cvt_pk_bf16_f32 v96, v100, v101
	v_rcp_f32_e32 v93, v93
	v_mul_f32_e32 v88, 0xbfb8aa3b, v88
	v_cvt_pk_bf16_f32 v97, v102, v103
	v_cvt_pk_bf16_f32 v98, v104, v98
	v_cvt_pk_bf16_f32 v99, v99, v105
	global_store_dwordx4 v[108:109], v[96:99], off offset:256
	v_add_f32_e32 v94, 1.0, v94
	v_exp_f32_e32 v88, v88
	v_lshlrev_b32_e32 v96, 16, v156
	v_mul_f32_e32 v92, v92, v96
	v_lshlrev_b32_e32 v96, 16, v148
	v_rcp_f32_e32 v94, v94
	v_mul_f32_e32 v92, v92, v96
	v_and_b32_e32 v96, 0xffff0000, v156
	v_add_f32_e32 v95, 1.0, v95
	v_mul_f32_e32 v93, v93, v96
	v_and_b32_e32 v96, 0xffff0000, v148
	v_rcp_f32_e32 v95, v95
	v_mul_f32_e32 v93, v93, v96
	v_lshlrev_b32_e32 v96, 16, v157
	v_add_f32_e32 v88, 1.0, v88
	v_mul_f32_e32 v94, v94, v96
	v_lshlrev_b32_e32 v96, 16, v149
	v_rcp_f32_e32 v88, v88
	v_mul_f32_e32 v89, 0xbfb8aa3b, v89
	v_mul_f32_e32 v94, v94, v96
	v_and_b32_e32 v96, 0xffff0000, v157
	v_exp_f32_e32 v89, v89
	v_mul_f32_e32 v95, v95, v96
	v_and_b32_e32 v96, 0xffff0000, v149
	v_mul_f32_e32 v95, v95, v96
	v_lshlrev_b32_e32 v96, 16, v158
	v_pk_add_f32 v[90:91], v[90:91], v[74:75]
	v_mul_f32_e32 v88, v88, v96
	v_lshlrev_b32_e32 v96, 16, v150
	v_mul_f32_e32 v96, v88, v96
	v_add_f32_e32 v88, 1.0, v89
	v_mul_f32_e32 v89, 0xbfb8aa3b, v90
	v_exp_f32_e32 v89, v89
	v_rcp_f32_e32 v88, v88
	v_mul_f32_e32 v91, 0xbfb8aa3b, v91
	v_exp_f32_e32 v91, v91
	v_add_f32_e32 v89, 1.0, v89
	v_rcp_f32_e32 v89, v89
	v_and_b32_e32 v90, 0xffff0000, v158
	v_mul_f32_e32 v88, v88, v90
	v_and_b32_e32 v90, 0xffff0000, v150
	v_pk_add_f32 v[84:85], v[84:85], v[68:69]
	v_mul_f32_e32 v90, v88, v90
	v_lshlrev_b32_e32 v88, 16, v159
	v_mul_f32_e32 v84, 0xbfb8aa3b, v84
	v_mul_f32_e32 v88, v89, v88
	v_add_f32_e32 v89, 1.0, v91
	v_exp_f32_e32 v84, v84
	v_rcp_f32_e32 v89, v89
	v_mul_f32_e32 v85, 0xbfb8aa3b, v85
	v_pk_add_f32 v[86:87], v[86:87], v[70:71]
	v_exp_f32_e32 v85, v85
	v_lshlrev_b32_e32 v91, 16, v151
	v_mul_f32_e32 v86, 0xbfb8aa3b, v86
	v_mul_f32_e32 v91, v88, v91
	v_and_b32_e32 v88, 0xffff0000, v159
	v_add_f32_e32 v84, 1.0, v84
	v_exp_f32_e32 v86, v86
	v_mul_f32_e32 v88, v89, v88
	v_and_b32_e32 v89, 0xffff0000, v151
	v_rcp_f32_e32 v84, v84
	v_mul_f32_e32 v87, 0xbfb8aa3b, v87
	v_mul_f32_e32 v97, v88, v89
	v_cvt_pk_bf16_f32 v88, v92, v93
	v_mad_i64_i32 v[92:93], s[14:15], v214, s66, v[144:145]
	v_pk_add_f32 v[80:81], v[80:81], v[64:65]
	v_add_f32_e32 v85, 1.0, v85
	v_exp_f32_e32 v87, v87
	v_lshl_add_u64 v[92:93], v[92:93], 0, v[208:209]
	v_rcp_f32_e32 v85, v85
	v_mul_f32_e32 v80, 0xbfb8aa3b, v80
	v_cvt_pk_bf16_f32 v89, v94, v95
	v_cvt_pk_bf16_f32 v90, v96, v90
	v_cvt_pk_bf16_f32 v91, v91, v97
	global_store_dwordx4 v[92:93], v[88:91], off
	v_add_f32_e32 v86, 1.0, v86
	v_exp_f32_e32 v80, v80
	v_lshlrev_b32_e32 v88, 16, v140
	v_mul_f32_e32 v84, v84, v88
	v_lshlrev_b32_e32 v88, 16, v136
	v_rcp_f32_e32 v86, v86
	v_mul_f32_e32 v84, v84, v88
	v_and_b32_e32 v88, 0xffff0000, v140
	v_add_f32_e32 v87, 1.0, v87
	v_mul_f32_e32 v85, v85, v88
	v_and_b32_e32 v88, 0xffff0000, v136
	v_rcp_f32_e32 v87, v87
	v_mul_f32_e32 v85, v85, v88
	v_lshlrev_b32_e32 v88, 16, v141
	v_add_f32_e32 v80, 1.0, v80
	v_mul_f32_e32 v86, v86, v88
	v_lshlrev_b32_e32 v88, 16, v137
	v_rcp_f32_e32 v80, v80
	v_mul_f32_e32 v81, 0xbfb8aa3b, v81
	v_mul_f32_e32 v86, v86, v88
	v_and_b32_e32 v88, 0xffff0000, v141
	v_exp_f32_e32 v81, v81
	v_mul_f32_e32 v87, v87, v88
	v_and_b32_e32 v88, 0xffff0000, v137
	v_mul_f32_e32 v87, v87, v88
	v_lshlrev_b32_e32 v88, 16, v142
	v_pk_add_f32 v[82:83], v[82:83], v[66:67]
	v_mul_f32_e32 v80, v80, v88
	v_lshlrev_b32_e32 v88, 16, v138
	v_mul_f32_e32 v88, v80, v88
	v_add_f32_e32 v80, 1.0, v81
	v_mul_f32_e32 v81, 0xbfb8aa3b, v82
	v_exp_f32_e32 v81, v81
	v_rcp_f32_e32 v80, v80
	v_mul_f32_e32 v83, 0xbfb8aa3b, v83
	v_exp_f32_e32 v83, v83
	v_add_f32_e32 v81, 1.0, v81
	v_rcp_f32_e32 v81, v81
	v_and_b32_e32 v82, 0xffff0000, v142
	v_mul_f32_e32 v80, v80, v82
	v_and_b32_e32 v82, 0xffff0000, v138
	v_mul_f32_e32 v82, v80, v82
	v_lshlrev_b32_e32 v80, 16, v143
	v_mul_f32_e32 v80, v81, v80
	v_add_f32_e32 v81, 1.0, v83
	v_rcp_f32_e32 v81, v81
	v_lshlrev_b32_e32 v83, 16, v139
	v_mul_f32_e32 v83, v80, v83
	v_and_b32_e32 v80, 0xffff0000, v143
	v_add_u32_e32 v142, 0x80, v210
	v_mul_f32_e32 v80, v81, v80
	v_and_b32_e32 v81, 0xffff0000, v139
	v_ashrrev_i32_e32 v143, 31, v142
	v_mul_f32_e32 v89, v80, v81
	v_cvt_pk_bf16_f32 v80, v84, v85
	v_lshlrev_b64 v[84:85], 11, v[142:143]
	v_lshl_add_u64 v[84:85], s[4:5], 0, v[84:85]
	v_cvt_pk_bf16_f32 v81, v86, v87
	v_lshl_add_u64 v[84:85], v[84:85], 0, v[208:209]
	v_mad_i64_i32 v[86:87], s[14:15], v142, s66, v[212:213]
	v_cvt_pk_bf16_f32 v82, v88, v82
	v_cvt_pk_bf16_f32 v83, v83, v89
	global_load_dwordx4 v[146:149], v[84:85], off
	v_lshl_add_u64 v[86:87], v[86:87], 0, v[208:209]
	global_load_dwordx4 v[150:153], v[86:87], off offset:2048
	v_add_u32_e32 v140, 0x90, v210
	global_store_dwordx4 v[92:93], v[80:83], off offset:256
	global_load_dwordx4 v[132:135], v[84:85], off offset:256
	global_load_dwordx4 v[128:131], v[86:87], off offset:2304
	v_ashrrev_i32_e32 v141, 31, v140
	v_lshlrev_b64 v[80:81], 11, v[140:141]
	v_lshl_add_u64 v[80:81], s[4:5], 0, v[80:81]
	v_mad_i64_i32 v[82:83], s[14:15], v140, s66, v[212:213]
	v_lshl_add_u64 v[80:81], v[80:81], 0, v[208:209]
	v_lshl_add_u64 v[82:83], v[82:83], 0, v[208:209]
	global_load_dwordx4 v[120:123], v[80:81], off
	global_load_dwordx4 v[112:115], v[80:81], off offset:256
	global_load_dwordx4 v[124:127], v[82:83], off offset:2048
	global_load_dwordx4 v[116:119], v[82:83], off offset:2304
	v_pk_add_f32 v[60:61], v[60:61], v[76:77]
	v_pk_add_f32 v[62:63], v[62:63], v[78:79]
	v_mul_f32_e32 v60, 0xbfb8aa3b, v60
	v_exp_f32_e32 v60, v60
	v_mul_f32_e32 v61, 0xbfb8aa3b, v61
	v_exp_f32_e32 v61, v61
	v_add_u32_e32 v138, 0xa0, v210
	v_mul_f32_e32 v62, 0xbfb8aa3b, v62
	v_ashrrev_i32_e32 v139, 31, v138
	v_add_f32_e32 v60, 1.0, v60
	v_exp_f32_e32 v62, v62
	v_lshlrev_b64 v[80:81], 11, v[138:139]
	v_rcp_f32_e32 v60, v60
	v_mul_f32_e32 v63, 0xbfb8aa3b, v63
	v_lshl_add_u64 v[80:81], s[4:5], 0, v[80:81]
	v_add_u32_e32 v136, 0xb0, v210
	v_pk_add_f32 v[56:57], v[56:57], v[72:73]
	v_add_f32_e32 v61, 1.0, v61
	v_exp_f32_e32 v63, v63
	v_mad_i64_i32 v[82:83], s[14:15], v138, s66, v[212:213]
	v_lshl_add_u64 v[80:81], v[80:81], 0, v[208:209]
	v_ashrrev_i32_e32 v137, 31, v136
	v_rcp_f32_e32 v61, v61
	v_mul_f32_e32 v56, 0xbfb8aa3b, v56
	v_lshl_add_u64 v[82:83], v[82:83], 0, v[208:209]
	global_load_dwordx4 v[104:107], v[80:81], off
	global_load_dwordx4 v[96:99], v[80:81], off offset:256
	global_load_dwordx4 v[108:111], v[82:83], off offset:2048
	global_load_dwordx4 v[100:103], v[82:83], off offset:2304
	v_lshlrev_b64 v[80:81], 11, v[136:137]
	v_add_f32_e32 v62, 1.0, v62
	v_exp_f32_e32 v56, v56
	v_rcp_f32_e32 v62, v62
	v_add_f32_e32 v63, 1.0, v63
	v_rcp_f32_e32 v63, v63
	v_add_f32_e32 v56, 1.0, v56
	v_rcp_f32_e32 v56, v56
	v_mul_f32_e32 v57, 0xbfb8aa3b, v57
	v_exp_f32_e32 v57, v57
	v_pk_add_f32 v[58:59], v[58:59], v[74:75]
	v_pk_add_f32 v[52:53], v[52:53], v[68:69]
	v_mul_f32_e32 v59, 0xbfb8aa3b, v59
	v_exp_f32_e32 v59, v59
	v_mul_f32_e32 v52, 0xbfb8aa3b, v52
	v_exp_f32_e32 v52, v52
	v_mul_f32_e32 v53, 0xbfb8aa3b, v53
	v_pk_add_f32 v[54:55], v[54:55], v[70:71]
	v_exp_f32_e32 v53, v53
	v_mul_f32_e32 v54, 0xbfb8aa3b, v54
	v_lshl_add_u64 v[80:81], s[4:5], 0, v[80:81]
	v_mad_i64_i32 v[82:83], s[14:15], v136, s66, v[212:213]
	v_add_f32_e32 v52, 1.0, v52
	v_exp_f32_e32 v54, v54
	v_lshl_add_u64 v[80:81], v[80:81], 0, v[208:209]
	v_lshl_add_u64 v[84:85], v[82:83], 0, v[208:209]
	v_rcp_f32_e32 v52, v52
	v_mul_f32_e32 v55, 0xbfb8aa3b, v55
	global_load_dwordx4 v[88:91], v[80:81], off
	s_nop 0
	global_load_dwordx4 v[80:83], v[80:81], off offset:256
	s_nop 0
	global_load_dwordx4 v[92:95], v[84:85], off offset:2048
	s_nop 0
	global_load_dwordx4 v[84:87], v[84:85], off offset:2304
	v_pk_add_f32 v[48:49], v[48:49], v[64:65]
	v_add_f32_e32 v53, 1.0, v53
	v_exp_f32_e32 v55, v55
	v_rcp_f32_e32 v53, v53
	v_mul_f32_e32 v48, 0xbfb8aa3b, v48
	v_add_f32_e32 v54, 1.0, v54
	v_exp_f32_e32 v48, v48
	v_rcp_f32_e32 v54, v54
	v_add_f32_e32 v55, 1.0, v55
	s_waitcnt vmcnt(16)
	v_lshlrev_b32_e32 v137, 16, v146
	v_mul_f32_e32 v60, v60, v137
	s_waitcnt vmcnt(15)
	v_lshlrev_b32_e32 v137, 16, v150
	v_mul_f32_e32 v60, v60, v137
	v_and_b32_e32 v137, 0xffff0000, v146
	v_mul_f32_e32 v61, v61, v137
	v_and_b32_e32 v137, 0xffff0000, v150
	v_mul_f32_e32 v61, v61, v137
	v_lshlrev_b32_e32 v137, 16, v147
	v_mul_f32_e32 v62, v62, v137
	v_lshlrev_b32_e32 v137, 16, v151
	v_mul_f32_e32 v62, v62, v137
	v_and_b32_e32 v137, 0xffff0000, v147
	v_mul_f32_e32 v63, v63, v137
	v_and_b32_e32 v137, 0xffff0000, v151
	v_mul_f32_e32 v63, v63, v137
	v_lshlrev_b32_e32 v137, 16, v148
	v_mul_f32_e32 v56, v56, v137
	v_lshlrev_b32_e32 v137, 16, v152
	v_mul_f32_e32 v137, v56, v137
	v_add_f32_e32 v56, 1.0, v57
	v_mul_f32_e32 v57, 0xbfb8aa3b, v58
	v_exp_f32_e32 v57, v57
	v_rcp_f32_e32 v56, v56
	v_and_b32_e32 v58, 0xffff0000, v148
	v_rcp_f32_e32 v55, v55
	v_add_f32_e32 v57, 1.0, v57
	v_rcp_f32_e32 v57, v57
	v_mul_f32_e32 v56, v56, v58
	v_and_b32_e32 v58, 0xffff0000, v152
	v_mul_f32_e32 v58, v56, v58
	v_lshlrev_b32_e32 v56, 16, v149
	v_mul_f32_e32 v56, v57, v56
	v_add_f32_e32 v57, 1.0, v59
	v_rcp_f32_e32 v57, v57
	v_lshlrev_b32_e32 v59, 16, v153
	v_mul_f32_e32 v59, v56, v59
	v_and_b32_e32 v56, 0xffff0000, v149
	v_mul_f32_e32 v56, v57, v56
	v_and_b32_e32 v57, 0xffff0000, v153
	v_mul_f32_e32 v139, v56, v57
	v_cvt_pk_bf16_f32 v56, v60, v61
	v_mad_i64_i32 v[60:61], s[14:15], v142, s66, v[144:145]
	v_lshl_add_u64 v[60:61], v[60:61], 0, v[208:209]
	v_cvt_pk_bf16_f32 v57, v62, v63
	v_cvt_pk_bf16_f32 v58, v137, v58
	v_cvt_pk_bf16_f32 v59, v59, v139
	global_store_dwordx4 v[60:61], v[56:59], off
	v_add_f32_e32 v48, 1.0, v48
	v_rcp_f32_e32 v48, v48
	s_waitcnt vmcnt(14)
	v_lshlrev_b32_e32 v56, 16, v132
	v_mul_f32_e32 v52, v52, v56
	s_waitcnt vmcnt(13)
	v_lshlrev_b32_e32 v56, 16, v128
	v_mul_f32_e32 v52, v52, v56
	v_and_b32_e32 v56, 0xffff0000, v132
	v_mul_f32_e32 v53, v53, v56
	v_and_b32_e32 v56, 0xffff0000, v128
	v_mul_f32_e32 v53, v53, v56
	v_lshlrev_b32_e32 v56, 16, v133
	v_mul_f32_e32 v54, v54, v56
	v_lshlrev_b32_e32 v56, 16, v129
	v_mul_f32_e32 v49, 0xbfb8aa3b, v49
	v_mul_f32_e32 v54, v54, v56
	v_and_b32_e32 v56, 0xffff0000, v133
	v_exp_f32_e32 v49, v49
	v_mul_f32_e32 v55, v55, v56
	v_and_b32_e32 v56, 0xffff0000, v129
	v_mul_f32_e32 v55, v55, v56
	v_lshlrev_b32_e32 v56, 16, v134
	v_pk_add_f32 v[50:51], v[50:51], v[66:67]
	v_mul_f32_e32 v48, v48, v56
	v_lshlrev_b32_e32 v56, 16, v130
	v_mul_f32_e32 v56, v48, v56
	v_add_f32_e32 v48, 1.0, v49
	v_mul_f32_e32 v49, 0xbfb8aa3b, v50
	v_exp_f32_e32 v49, v49
	v_rcp_f32_e32 v48, v48
	v_mul_f32_e32 v51, 0xbfb8aa3b, v51
	v_exp_f32_e32 v51, v51
	v_add_f32_e32 v49, 1.0, v49
	v_rcp_f32_e32 v49, v49
	v_and_b32_e32 v50, 0xffff0000, v134
	v_pk_add_f32 v[44:45], v[44:45], v[76:77]
	v_mul_f32_e32 v48, v48, v50
	v_and_b32_e32 v50, 0xffff0000, v130
	v_mul_f32_e32 v44, 0xbfb8aa3b, v44
	v_mul_f32_e32 v50, v48, v50
	v_lshlrev_b32_e32 v48, 16, v135
	v_exp_f32_e32 v44, v44
	v_mul_f32_e32 v48, v49, v48
	v_add_f32_e32 v49, 1.0, v51
	v_mul_f32_e32 v45, 0xbfb8aa3b, v45
	v_rcp_f32_e32 v49, v49
	v_pk_add_f32 v[46:47], v[46:47], v[78:79]
	v_exp_f32_e32 v45, v45
	v_mul_f32_e32 v46, 0xbfb8aa3b, v46
	v_lshlrev_b32_e32 v51, 16, v131
	v_add_f32_e32 v44, 1.0, v44
	v_exp_f32_e32 v46, v46
	v_mul_f32_e32 v51, v48, v51
	v_and_b32_e32 v48, 0xffff0000, v135
	v_rcp_f32_e32 v44, v44
	v_mul_f32_e32 v47, 0xbfb8aa3b, v47
	v_mul_f32_e32 v48, v49, v48
	v_and_b32_e32 v49, 0xffff0000, v131
	v_pk_add_f32 v[40:41], v[40:41], v[72:73]
	v_add_f32_e32 v45, 1.0, v45
	v_exp_f32_e32 v47, v47
	v_mul_f32_e32 v57, v48, v49
	v_cvt_pk_bf16_f32 v48, v52, v53
	v_rcp_f32_e32 v45, v45
	v_mul_f32_e32 v40, 0xbfb8aa3b, v40
	v_cvt_pk_bf16_f32 v49, v54, v55
	v_cvt_pk_bf16_f32 v50, v56, v50
	v_cvt_pk_bf16_f32 v51, v51, v57
	global_store_dwordx4 v[60:61], v[48:51], off offset:256
	v_add_f32_e32 v46, 1.0, v46
	v_exp_f32_e32 v40, v40
	s_waitcnt vmcnt(13)
	v_lshlrev_b32_e32 v48, 16, v120
	v_mul_f32_e32 v44, v44, v48
	s_waitcnt vmcnt(11)
	v_lshlrev_b32_e32 v48, 16, v124
	v_rcp_f32_e32 v46, v46
	v_mul_f32_e32 v44, v44, v48
	v_and_b32_e32 v48, 0xffff0000, v120
	v_add_f32_e32 v47, 1.0, v47
	v_mul_f32_e32 v45, v45, v48
	v_and_b32_e32 v48, 0xffff0000, v124
	v_rcp_f32_e32 v47, v47
	v_mul_f32_e32 v45, v45, v48
	v_lshlrev_b32_e32 v48, 16, v121
	v_add_f32_e32 v40, 1.0, v40
	v_mul_f32_e32 v46, v46, v48
	v_lshlrev_b32_e32 v48, 16, v125
	v_rcp_f32_e32 v40, v40
	v_mul_f32_e32 v41, 0xbfb8aa3b, v41
	v_mul_f32_e32 v46, v46, v48
	v_and_b32_e32 v48, 0xffff0000, v121
	v_exp_f32_e32 v41, v41
	v_mul_f32_e32 v47, v47, v48
	v_and_b32_e32 v48, 0xffff0000, v125
	v_mul_f32_e32 v47, v47, v48
	v_lshlrev_b32_e32 v48, 16, v122
	v_pk_add_f32 v[42:43], v[42:43], v[74:75]
	v_mul_f32_e32 v40, v40, v48
	v_lshlrev_b32_e32 v48, 16, v126
	v_mul_f32_e32 v48, v40, v48
	v_add_f32_e32 v40, 1.0, v41
	v_mul_f32_e32 v41, 0xbfb8aa3b, v42
	v_exp_f32_e32 v41, v41
	v_rcp_f32_e32 v40, v40
	v_mul_f32_e32 v43, 0xbfb8aa3b, v43
	v_exp_f32_e32 v43, v43
	v_add_f32_e32 v41, 1.0, v41
	v_rcp_f32_e32 v41, v41
	v_and_b32_e32 v42, 0xffff0000, v122
	v_mul_f32_e32 v40, v40, v42
	v_and_b32_e32 v42, 0xffff0000, v126
	v_pk_add_f32 v[36:37], v[36:37], v[68:69]
	v_mul_f32_e32 v42, v40, v42
	v_lshlrev_b32_e32 v40, 16, v123
	v_mul_f32_e32 v36, 0xbfb8aa3b, v36
	v_mul_f32_e32 v40, v41, v40
	v_add_f32_e32 v41, 1.0, v43
	v_exp_f32_e32 v36, v36
	v_rcp_f32_e32 v41, v41
	v_mul_f32_e32 v37, 0xbfb8aa3b, v37
	v_pk_add_f32 v[38:39], v[38:39], v[70:71]
	v_exp_f32_e32 v37, v37
	v_lshlrev_b32_e32 v43, 16, v127
	v_mul_f32_e32 v38, 0xbfb8aa3b, v38
	v_mul_f32_e32 v43, v40, v43
	v_and_b32_e32 v40, 0xffff0000, v123
	v_add_f32_e32 v36, 1.0, v36
	v_exp_f32_e32 v38, v38
	v_mul_f32_e32 v40, v41, v40
	v_and_b32_e32 v41, 0xffff0000, v127
	v_rcp_f32_e32 v36, v36
	v_mul_f32_e32 v39, 0xbfb8aa3b, v39
	v_mul_f32_e32 v49, v40, v41
	v_cvt_pk_bf16_f32 v40, v44, v45
	v_mad_i64_i32 v[44:45], s[14:15], v140, s66, v[144:145]
	v_pk_add_f32 v[32:33], v[32:33], v[64:65]
	v_add_f32_e32 v37, 1.0, v37
	v_exp_f32_e32 v39, v39
	v_lshl_add_u64 v[44:45], v[44:45], 0, v[208:209]
	v_rcp_f32_e32 v37, v37
	v_mul_f32_e32 v32, 0xbfb8aa3b, v32
	v_cvt_pk_bf16_f32 v41, v46, v47
	v_cvt_pk_bf16_f32 v42, v48, v42
	v_cvt_pk_bf16_f32 v43, v43, v49
	global_store_dwordx4 v[44:45], v[40:43], off
	v_add_f32_e32 v38, 1.0, v38
	v_exp_f32_e32 v32, v32
	v_lshlrev_b32_e32 v40, 16, v112
	v_mul_f32_e32 v36, v36, v40
	s_waitcnt vmcnt(11)
	v_lshlrev_b32_e32 v40, 16, v116
	v_rcp_f32_e32 v38, v38
	v_mul_f32_e32 v36, v36, v40
	v_and_b32_e32 v40, 0xffff0000, v112
	v_add_f32_e32 v39, 1.0, v39
	v_mul_f32_e32 v37, v37, v40
	v_and_b32_e32 v40, 0xffff0000, v116
	v_rcp_f32_e32 v39, v39
	v_mul_f32_e32 v37, v37, v40
	v_lshlrev_b32_e32 v40, 16, v113
	v_add_f32_e32 v32, 1.0, v32
	v_mul_f32_e32 v38, v38, v40
	v_lshlrev_b32_e32 v40, 16, v117
	v_rcp_f32_e32 v32, v32
	v_mul_f32_e32 v33, 0xbfb8aa3b, v33
	v_mul_f32_e32 v38, v38, v40
	v_and_b32_e32 v40, 0xffff0000, v113
	v_exp_f32_e32 v33, v33
	v_mul_f32_e32 v39, v39, v40
	v_and_b32_e32 v40, 0xffff0000, v117
	v_mul_f32_e32 v39, v39, v40
	v_lshlrev_b32_e32 v40, 16, v114
	v_pk_add_f32 v[34:35], v[34:35], v[66:67]
	v_mul_f32_e32 v32, v32, v40
	v_lshlrev_b32_e32 v40, 16, v118
	v_mul_f32_e32 v40, v32, v40
	v_add_f32_e32 v32, 1.0, v33
	v_mul_f32_e32 v33, 0xbfb8aa3b, v34
	v_exp_f32_e32 v33, v33
	v_rcp_f32_e32 v32, v32
	v_mul_f32_e32 v35, 0xbfb8aa3b, v35
	v_exp_f32_e32 v35, v35
	v_add_f32_e32 v33, 1.0, v33
	v_rcp_f32_e32 v33, v33
	v_and_b32_e32 v34, 0xffff0000, v114
	v_pk_add_f32 v[28:29], v[28:29], v[76:77]
	v_mul_f32_e32 v32, v32, v34
	v_and_b32_e32 v34, 0xffff0000, v118
	v_mul_f32_e32 v28, 0xbfb8aa3b, v28
	v_mul_f32_e32 v34, v32, v34
	v_lshlrev_b32_e32 v32, 16, v115
	v_exp_f32_e32 v28, v28
	v_mul_f32_e32 v32, v33, v32
	v_add_f32_e32 v33, 1.0, v35
	v_mul_f32_e32 v29, 0xbfb8aa3b, v29
	v_rcp_f32_e32 v33, v33
	v_pk_add_f32 v[30:31], v[30:31], v[78:79]
	v_exp_f32_e32 v29, v29
	v_mul_f32_e32 v30, 0xbfb8aa3b, v30
	v_lshlrev_b32_e32 v35, 16, v119
	v_add_f32_e32 v28, 1.0, v28
	v_exp_f32_e32 v30, v30
	v_mul_f32_e32 v35, v32, v35
	v_and_b32_e32 v32, 0xffff0000, v115
	v_rcp_f32_e32 v28, v28
	v_mul_f32_e32 v31, 0xbfb8aa3b, v31
	v_mul_f32_e32 v32, v33, v32
	v_and_b32_e32 v33, 0xffff0000, v119
	v_pk_add_f32 v[24:25], v[24:25], v[72:73]
	v_add_f32_e32 v29, 1.0, v29
	v_exp_f32_e32 v31, v31
	v_mul_f32_e32 v41, v32, v33
	v_cvt_pk_bf16_f32 v32, v36, v37
	v_rcp_f32_e32 v29, v29
	v_mul_f32_e32 v24, 0xbfb8aa3b, v24
	v_cvt_pk_bf16_f32 v33, v38, v39
	v_cvt_pk_bf16_f32 v34, v40, v34
	v_cvt_pk_bf16_f32 v35, v35, v41
	global_store_dwordx4 v[44:45], v[32:35], off offset:256
	v_add_f32_e32 v30, 1.0, v30
	v_exp_f32_e32 v24, v24
	s_waitcnt vmcnt(11)
	v_lshlrev_b32_e32 v32, 16, v104
	v_mul_f32_e32 v28, v28, v32
	s_waitcnt vmcnt(9)
	v_lshlrev_b32_e32 v32, 16, v108
	v_rcp_f32_e32 v30, v30
	v_mul_f32_e32 v28, v28, v32
	v_and_b32_e32 v32, 0xffff0000, v104
	v_add_f32_e32 v31, 1.0, v31
	v_mul_f32_e32 v29, v29, v32
	v_and_b32_e32 v32, 0xffff0000, v108
	v_rcp_f32_e32 v31, v31
	v_mul_f32_e32 v29, v29, v32
	v_lshlrev_b32_e32 v32, 16, v105
	v_add_f32_e32 v24, 1.0, v24
	v_mul_f32_e32 v30, v30, v32
	v_lshlrev_b32_e32 v32, 16, v109
	v_rcp_f32_e32 v24, v24
	v_mul_f32_e32 v25, 0xbfb8aa3b, v25
	v_mul_f32_e32 v30, v30, v32
	v_and_b32_e32 v32, 0xffff0000, v105
	v_exp_f32_e32 v25, v25
	v_mul_f32_e32 v31, v31, v32
	v_and_b32_e32 v32, 0xffff0000, v109
	v_mul_f32_e32 v31, v31, v32
	v_lshlrev_b32_e32 v32, 16, v106
	v_pk_add_f32 v[26:27], v[26:27], v[74:75]
	v_mul_f32_e32 v24, v24, v32
	v_lshlrev_b32_e32 v32, 16, v110
	v_mul_f32_e32 v32, v24, v32
	v_add_f32_e32 v24, 1.0, v25
	v_mul_f32_e32 v25, 0xbfb8aa3b, v26
	v_exp_f32_e32 v25, v25
	v_rcp_f32_e32 v24, v24
	v_mul_f32_e32 v27, 0xbfb8aa3b, v27
	v_exp_f32_e32 v27, v27
	v_add_f32_e32 v25, 1.0, v25
	v_rcp_f32_e32 v25, v25
	v_and_b32_e32 v26, 0xffff0000, v106
	v_mul_f32_e32 v24, v24, v26
	v_and_b32_e32 v26, 0xffff0000, v110
	v_pk_add_f32 v[20:21], v[20:21], v[68:69]
	v_mul_f32_e32 v26, v24, v26
	v_lshlrev_b32_e32 v24, 16, v107
	v_mul_f32_e32 v20, 0xbfb8aa3b, v20
	v_mul_f32_e32 v24, v25, v24
	v_add_f32_e32 v25, 1.0, v27
	v_exp_f32_e32 v20, v20
	v_rcp_f32_e32 v25, v25
	v_mul_f32_e32 v21, 0xbfb8aa3b, v21
	v_pk_add_f32 v[22:23], v[22:23], v[70:71]
	v_exp_f32_e32 v21, v21
	v_lshlrev_b32_e32 v27, 16, v111
	v_mul_f32_e32 v22, 0xbfb8aa3b, v22
	v_mul_f32_e32 v27, v24, v27
	v_and_b32_e32 v24, 0xffff0000, v107
	v_add_f32_e32 v20, 1.0, v20
	v_exp_f32_e32 v22, v22
	v_mul_f32_e32 v24, v25, v24
	v_and_b32_e32 v25, 0xffff0000, v111
	v_rcp_f32_e32 v20, v20
	v_mul_f32_e32 v23, 0xbfb8aa3b, v23
	v_mul_f32_e32 v33, v24, v25
	v_cvt_pk_bf16_f32 v24, v28, v29
	v_mad_i64_i32 v[28:29], s[14:15], v138, s66, v[144:145]
	v_pk_add_f32 v[16:17], v[16:17], v[64:65]
	v_add_f32_e32 v21, 1.0, v21
	v_exp_f32_e32 v23, v23
	v_lshl_add_u64 v[28:29], v[28:29], 0, v[208:209]
	v_rcp_f32_e32 v21, v21
	v_mul_f32_e32 v16, 0xbfb8aa3b, v16
	v_cvt_pk_bf16_f32 v25, v30, v31
	v_cvt_pk_bf16_f32 v26, v32, v26
	v_cvt_pk_bf16_f32 v27, v27, v33
	global_store_dwordx4 v[28:29], v[24:27], off
	v_add_f32_e32 v22, 1.0, v22
	v_exp_f32_e32 v16, v16
	v_lshlrev_b32_e32 v24, 16, v96
	v_mul_f32_e32 v20, v20, v24
	s_waitcnt vmcnt(9)
	v_lshlrev_b32_e32 v24, 16, v100
	v_rcp_f32_e32 v22, v22
	v_mul_f32_e32 v20, v20, v24
	v_and_b32_e32 v24, 0xffff0000, v96
	v_add_f32_e32 v23, 1.0, v23
	v_mul_f32_e32 v21, v21, v24
	v_and_b32_e32 v24, 0xffff0000, v100
	v_rcp_f32_e32 v23, v23
	v_mul_f32_e32 v21, v21, v24
	v_lshlrev_b32_e32 v24, 16, v97
	v_add_f32_e32 v16, 1.0, v16
	v_mul_f32_e32 v22, v22, v24
	v_lshlrev_b32_e32 v24, 16, v101
	v_rcp_f32_e32 v16, v16
	v_mul_f32_e32 v17, 0xbfb8aa3b, v17
	v_mul_f32_e32 v22, v22, v24
	v_and_b32_e32 v24, 0xffff0000, v97
	v_exp_f32_e32 v17, v17
	v_mul_f32_e32 v23, v23, v24
	v_and_b32_e32 v24, 0xffff0000, v101
	v_mul_f32_e32 v23, v23, v24
	v_lshlrev_b32_e32 v24, 16, v98
	v_pk_add_f32 v[18:19], v[18:19], v[66:67]
	v_mul_f32_e32 v16, v16, v24
	v_lshlrev_b32_e32 v24, 16, v102
	v_mul_f32_e32 v24, v16, v24
	v_add_f32_e32 v16, 1.0, v17
	v_mul_f32_e32 v17, 0xbfb8aa3b, v18
	v_exp_f32_e32 v17, v17
	v_rcp_f32_e32 v16, v16
	v_mul_f32_e32 v19, 0xbfb8aa3b, v19
	v_exp_f32_e32 v19, v19
	v_add_f32_e32 v17, 1.0, v17
	v_rcp_f32_e32 v17, v17
	v_and_b32_e32 v18, 0xffff0000, v98
	v_pk_add_f32 v[12:13], v[12:13], v[76:77]
	v_mul_f32_e32 v16, v16, v18
	v_and_b32_e32 v18, 0xffff0000, v102
	v_mul_f32_e32 v12, 0xbfb8aa3b, v12
	v_mul_f32_e32 v18, v16, v18
	v_lshlrev_b32_e32 v16, 16, v99
	v_exp_f32_e32 v12, v12
	v_mul_f32_e32 v16, v17, v16
	v_add_f32_e32 v17, 1.0, v19
	v_mul_f32_e32 v13, 0xbfb8aa3b, v13
	v_rcp_f32_e32 v17, v17
	v_pk_add_f32 v[14:15], v[14:15], v[78:79]
	v_exp_f32_e32 v13, v13
	v_mul_f32_e32 v14, 0xbfb8aa3b, v14
	v_lshlrev_b32_e32 v19, 16, v103
	v_add_f32_e32 v12, 1.0, v12
	v_exp_f32_e32 v14, v14
	v_mul_f32_e32 v19, v16, v19
	v_and_b32_e32 v16, 0xffff0000, v99
	v_rcp_f32_e32 v12, v12
	v_mul_f32_e32 v15, 0xbfb8aa3b, v15
	v_mul_f32_e32 v16, v17, v16
	v_and_b32_e32 v17, 0xffff0000, v103
	v_pk_add_f32 v[8:9], v[8:9], v[72:73]
	v_add_f32_e32 v13, 1.0, v13
	v_exp_f32_e32 v15, v15
	v_mul_f32_e32 v25, v16, v17
	v_cvt_pk_bf16_f32 v16, v20, v21
	v_rcp_f32_e32 v13, v13
	v_mul_f32_e32 v8, 0xbfb8aa3b, v8
	v_cvt_pk_bf16_f32 v17, v22, v23
	v_cvt_pk_bf16_f32 v18, v24, v18
	v_cvt_pk_bf16_f32 v19, v19, v25
	global_store_dwordx4 v[28:29], v[16:19], off offset:256
	v_add_f32_e32 v14, 1.0, v14
	v_exp_f32_e32 v8, v8
	s_waitcnt vmcnt(9)
	v_lshlrev_b32_e32 v16, 16, v88
	v_mul_f32_e32 v12, v12, v16
	s_waitcnt vmcnt(7)
	v_lshlrev_b32_e32 v16, 16, v92
	v_rcp_f32_e32 v14, v14
	v_mul_f32_e32 v12, v12, v16
	v_and_b32_e32 v16, 0xffff0000, v88
	v_add_f32_e32 v15, 1.0, v15
	v_mul_f32_e32 v13, v13, v16
	v_and_b32_e32 v16, 0xffff0000, v92
	v_rcp_f32_e32 v15, v15
	v_mul_f32_e32 v13, v13, v16
	v_lshlrev_b32_e32 v16, 16, v89
	v_add_f32_e32 v8, 1.0, v8
	v_mul_f32_e32 v14, v14, v16
	v_lshlrev_b32_e32 v16, 16, v93
	v_rcp_f32_e32 v8, v8
	v_mul_f32_e32 v9, 0xbfb8aa3b, v9
	v_mul_f32_e32 v14, v14, v16
	v_and_b32_e32 v16, 0xffff0000, v89
	v_exp_f32_e32 v9, v9
	v_mul_f32_e32 v15, v15, v16
	v_and_b32_e32 v16, 0xffff0000, v93
	v_mul_f32_e32 v15, v15, v16
	v_lshlrev_b32_e32 v16, 16, v90
	v_pk_add_f32 v[10:11], v[10:11], v[74:75]
	v_mul_f32_e32 v8, v8, v16
	v_lshlrev_b32_e32 v16, 16, v94
	v_mul_f32_e32 v16, v8, v16
	v_add_f32_e32 v8, 1.0, v9
	v_mul_f32_e32 v9, 0xbfb8aa3b, v10
	v_exp_f32_e32 v9, v9
	v_rcp_f32_e32 v8, v8
	v_mul_f32_e32 v11, 0xbfb8aa3b, v11
	v_exp_f32_e32 v11, v11
	v_add_f32_e32 v9, 1.0, v9
	v_rcp_f32_e32 v9, v9
	v_and_b32_e32 v10, 0xffff0000, v90
	v_mul_f32_e32 v8, v8, v10
	v_and_b32_e32 v10, 0xffff0000, v94
	v_pk_add_f32 v[4:5], v[4:5], v[68:69]
	v_mul_f32_e32 v10, v8, v10
	v_lshlrev_b32_e32 v8, 16, v91
	v_mul_f32_e32 v4, 0xbfb8aa3b, v4
	v_mul_f32_e32 v8, v9, v8
	v_add_f32_e32 v9, 1.0, v11
	v_exp_f32_e32 v4, v4
	v_rcp_f32_e32 v9, v9
	v_mul_f32_e32 v5, 0xbfb8aa3b, v5
	v_pk_add_f32 v[6:7], v[6:7], v[70:71]
	v_exp_f32_e32 v5, v5
	v_lshlrev_b32_e32 v11, 16, v95
	v_mul_f32_e32 v6, 0xbfb8aa3b, v6
	v_mul_f32_e32 v11, v8, v11
	v_and_b32_e32 v8, 0xffff0000, v91
	v_add_f32_e32 v4, 1.0, v4
	v_exp_f32_e32 v6, v6
	v_mul_f32_e32 v8, v9, v8
	v_and_b32_e32 v9, 0xffff0000, v95
	v_rcp_f32_e32 v4, v4
	v_mul_f32_e32 v7, 0xbfb8aa3b, v7
	v_mul_f32_e32 v17, v8, v9
	v_cvt_pk_bf16_f32 v8, v12, v13
	v_mad_i64_i32 v[12:13], s[14:15], v136, s66, v[144:145]
	v_pk_add_f32 v[0:1], v[0:1], v[64:65]
	v_add_f32_e32 v5, 1.0, v5
	v_exp_f32_e32 v7, v7
	v_lshl_add_u64 v[12:13], v[12:13], 0, v[208:209]
	v_rcp_f32_e32 v5, v5
	v_mul_f32_e32 v0, 0xbfb8aa3b, v0
	v_cvt_pk_bf16_f32 v9, v14, v15
	v_cvt_pk_bf16_f32 v10, v16, v10
	v_cvt_pk_bf16_f32 v11, v11, v17
	global_store_dwordx4 v[12:13], v[8:11], off
	v_add_f32_e32 v6, 1.0, v6
	v_exp_f32_e32 v0, v0
	v_lshlrev_b32_e32 v8, 16, v80
	v_mul_f32_e32 v4, v4, v8
	s_waitcnt vmcnt(7)
	v_lshlrev_b32_e32 v8, 16, v84
	v_rcp_f32_e32 v6, v6
	v_mul_f32_e32 v4, v4, v8
	v_and_b32_e32 v8, 0xffff0000, v80
	v_add_f32_e32 v7, 1.0, v7
	v_mul_f32_e32 v5, v5, v8
	v_and_b32_e32 v8, 0xffff0000, v84
	v_rcp_f32_e32 v7, v7
	v_mul_f32_e32 v5, v5, v8
	v_lshlrev_b32_e32 v8, 16, v81
	v_add_f32_e32 v0, 1.0, v0
	v_mul_f32_e32 v6, v6, v8
	v_lshlrev_b32_e32 v8, 16, v85
	v_rcp_f32_e32 v0, v0
	v_mul_f32_e32 v1, 0xbfb8aa3b, v1
	v_mul_f32_e32 v6, v6, v8
	v_and_b32_e32 v8, 0xffff0000, v81
	v_exp_f32_e32 v1, v1
	v_mul_f32_e32 v7, v7, v8
	v_and_b32_e32 v8, 0xffff0000, v85
	v_mul_f32_e32 v7, v7, v8
	v_lshlrev_b32_e32 v8, 16, v82
	v_pk_add_f32 v[2:3], v[2:3], v[66:67]
	v_mul_f32_e32 v0, v0, v8
	v_lshlrev_b32_e32 v8, 16, v86
	v_mul_f32_e32 v8, v0, v8
	v_add_f32_e32 v0, 1.0, v1
	v_mul_f32_e32 v1, 0xbfb8aa3b, v2
	v_exp_f32_e32 v1, v1
	v_rcp_f32_e32 v0, v0
	v_mul_f32_e32 v3, 0xbfb8aa3b, v3
	v_exp_f32_e32 v3, v3
	v_add_f32_e32 v1, 1.0, v1
	v_rcp_f32_e32 v1, v1
	v_and_b32_e32 v2, 0xffff0000, v82
	v_mul_f32_e32 v0, v0, v2
	v_and_b32_e32 v2, 0xffff0000, v86
	v_mul_f32_e32 v2, v0, v2
	v_lshlrev_b32_e32 v0, 16, v83
	v_mul_f32_e32 v0, v1, v0
	v_add_f32_e32 v1, 1.0, v3
	v_rcp_f32_e32 v1, v1
	v_lshlrev_b32_e32 v3, 16, v87
	v_mul_f32_e32 v3, v0, v3
	v_and_b32_e32 v0, 0xffff0000, v83
	v_mul_f32_e32 v0, v1, v0
	v_and_b32_e32 v1, 0xffff0000, v87
	s_mov_b64 s[14:15], s[34:35]
	v_mul_f32_e32 v9, v0, v1
	v_cvt_pk_bf16_f32 v0, v4, v5
	v_cvt_pk_bf16_f32 v1, v6, v7
	v_cvt_pk_bf16_f32 v2, v8, v2
	v_cvt_pk_bf16_f32 v3, v3, v9
	global_store_dwordx4 v[12:13], v[0:3], off offset:256
	s_cbranch_vccz .LBB0_433
	s_waitcnt vmcnt(0)
	s_cmpk_gt_u32 s52, 0xff
	s_cbranch_scc1 .LBB0_444
	s_barrier

.LBB0_519:
	s_add_u32 s6, s38, 0x100
	s_addc_u32 s7, s39, 0
	s_cmp_eq_u32 s76, 28
	s_cselect_b32 s43, s23, s7
	s_cselect_b32 s42, s22, s6
	s_cselect_b32 s41, s19, s75
	s_cselect_b32 s40, s73, s74
	s_add_i32 s77, 0, 0x14000
	v_add_u32_e32 v172, s77, v175
	ds_read_b128 v[128:131], v177
	ds_read_b128 v[132:135], v177 offset:1024
	ds_read_b128 v[136:139], v177 offset:2048
	ds_read_b128 v[140:143], v177 offset:3072
	ds_read_b128 v[144:147], v172
	ds_read_b128 v[164:167], v172 offset:1024
	ds_read_b128 v[168:171], v172 offset:2048
	ds_read_b128 v[180:183], v172 offset:3072
	s_add_i32 m0, s59, 0xc000
	ds_read_b128 v[184:187], v178
	ds_read_b128 v[188:191], v178 offset:1024
	ds_read_b128 v[192:195], v178 offset:2048
	ds_read_b128 v[196:199], v178 offset:3072
	ds_read_b128 v[200:203], v178 offset:4096
	ds_read_b128 v[204:207], v178 offset:5120
	ds_read_b128 v[208:211], v178 offset:6144
	ds_read_b128 v[212:215], v178 offset:7168
	global_load_lds_dwordx4 v158, s[38:39]
	s_add_i32 m0, s59, 0xe000
	s_nop 0
	global_load_lds_dwordx4 v156, s[38:39]
	s_waitcnt vmcnt(8)
	s_waitcnt lgkmcnt(0)
	s_barrier
	s_setprio 1
	s_waitcnt lgkmcnt(0)
	v_mfma_f32_16x16x32_bf16 v[124:127], v[128:131], v[184:187], v[124:127]
	v_mfma_f32_16x16x32_bf16 v[120:123], v[136:139], v[184:187], v[120:123]
	v_mfma_f32_16x16x32_bf16 v[116:119], v[128:131], v[192:195], v[116:119]
	v_mfma_f32_16x16x32_bf16 v[104:107], v[136:139], v[192:195], v[104:107]
	v_mfma_f32_16x16x32_bf16 v[92:95], v[128:131], v[200:203], v[92:95]
	v_mfma_f32_16x16x32_bf16 v[88:91], v[136:139], v[200:203], v[88:91]
	v_mfma_f32_16x16x32_bf16 v[76:79], v[128:131], v[208:211], v[76:79]
	v_mfma_f32_16x16x32_bf16 v[72:75], v[136:139], v[208:211], v[72:75]
	v_mfma_f32_16x16x32_bf16 v[124:127], v[132:135], v[188:191], v[124:127]
	v_mfma_f32_16x16x32_bf16 v[120:123], v[140:143], v[188:191], v[120:123]
	v_mfma_f32_16x16x32_bf16 v[116:119], v[132:135], v[196:199], v[116:119]
	v_mfma_f32_16x16x32_bf16 v[104:107], v[140:143], v[196:199], v[104:107]
	v_mfma_f32_16x16x32_bf16 v[92:95], v[132:135], v[204:207], v[92:95]
	v_mfma_f32_16x16x32_bf16 v[88:91], v[140:143], v[204:207], v[88:91]
	v_mfma_f32_16x16x32_bf16 v[76:79], v[132:135], v[212:215], v[76:79]
	v_mfma_f32_16x16x32_bf16 v[72:75], v[140:143], v[212:215], v[72:75]
	s_setprio 0
	s_setprio 1
	v_mfma_f32_16x16x32_bf16 v[112:115], v[144:147], v[184:187], v[112:115]
	v_mfma_f32_16x16x32_bf16 v[108:111], v[168:171], v[184:187], v[108:111]
	v_mfma_f32_16x16x32_bf16 v[100:103], v[144:147], v[192:195], v[100:103]
	v_mfma_f32_16x16x32_bf16 v[96:99], v[168:171], v[192:195], v[96:99]
	v_mfma_f32_16x16x32_bf16 v[84:87], v[144:147], v[200:203], v[84:87]
	v_mfma_f32_16x16x32_bf16 v[80:83], v[168:171], v[200:203], v[80:83]
	v_mfma_f32_16x16x32_bf16 v[68:71], v[144:147], v[208:211], v[68:71]
	v_mfma_f32_16x16x32_bf16 v[64:67], v[168:171], v[208:211], v[64:67]
	v_mfma_f32_16x16x32_bf16 v[112:115], v[164:167], v[188:191], v[112:115]
	v_mfma_f32_16x16x32_bf16 v[108:111], v[180:183], v[188:191], v[108:111]
	v_mfma_f32_16x16x32_bf16 v[100:103], v[164:167], v[196:199], v[100:103]
	v_mfma_f32_16x16x32_bf16 v[96:99], v[180:183], v[196:199], v[96:99]
	v_mfma_f32_16x16x32_bf16 v[84:87], v[164:167], v[204:207], v[84:87]
	v_mfma_f32_16x16x32_bf16 v[80:83], v[180:183], v[204:207], v[80:83]
	v_mfma_f32_16x16x32_bf16 v[68:71], v[164:167], v[212:215], v[68:71]
	v_mfma_f32_16x16x32_bf16 v[64:67], v[180:183], v[212:215], v[64:67]
	s_setprio 0
	s_barrier
	s_add_i32 s38, s67, s58
	s_mov_b64 s[98:99], s[40:41]
	s_mov_b32 m0, s38
	ds_read_b128 v[184:187], v178 offset:16384
	ds_read_b128 v[188:191], v178 offset:17408
	ds_read_b128 v[192:195], v178 offset:18432
	ds_read_b128 v[196:199], v178 offset:19456
	ds_read_b128 v[200:203], v178 offset:20480
	ds_read_b128 v[204:207], v178 offset:21504
	ds_read_b128 v[208:211], v178 offset:22528
	ds_read_b128 v[212:215], v178 offset:23552
	global_load_lds_dwordx4 v150, s[40:41]
	s_add_i32 m0, s38, 0x2000
	s_add_u32 s38, s40, 0x80000
	s_addc_u32 s39, s41, 0
	s_add_i32 s77, s77, s58
	global_load_lds_dwordx4 v154, s[40:41]
	s_mov_b32 m0, s77
	s_mov_b64 s[100:101], s[42:43]
	global_load_lds_dwordx4 v150, s[38:39]
	s_add_i32 m0, s77, 0x2000
	s_nop 0
	global_load_lds_dwordx4 v154, s[38:39]
	s_mov_b32 m0, s59
	s_nop 0
	global_load_lds_dwordx4 v148, s[42:43]
	s_mov_b32 m0, s60
	s_nop 0
	global_load_lds_dwordx4 v152, s[42:43]
	s_waitcnt vmcnt(8)
	s_waitcnt lgkmcnt(0)
	s_barrier
	s_setprio 1
	s_waitcnt lgkmcnt(0)
	v_mfma_f32_16x16x32_bf16 v[60:63], v[128:131], v[184:187], v[60:63]
	v_mfma_f32_16x16x32_bf16 v[56:59], v[136:139], v[184:187], v[56:59]
	v_mfma_f32_16x16x32_bf16 v[52:55], v[128:131], v[192:195], v[52:55]
	v_mfma_f32_16x16x32_bf16 v[40:43], v[136:139], v[192:195], v[40:43]
	v_mfma_f32_16x16x32_bf16 v[28:31], v[128:131], v[200:203], v[28:31]
	v_mfma_f32_16x16x32_bf16 v[24:27], v[136:139], v[200:203], v[24:27]
	v_mfma_f32_16x16x32_bf16 v[12:15], v[128:131], v[208:211], v[12:15]
	v_mfma_f32_16x16x32_bf16 v[8:11], v[136:139], v[208:211], v[8:11]
	v_mfma_f32_16x16x32_bf16 v[60:63], v[132:135], v[188:191], v[60:63]
	v_mfma_f32_16x16x32_bf16 v[56:59], v[140:143], v[188:191], v[56:59]
	v_mfma_f32_16x16x32_bf16 v[52:55], v[132:135], v[196:199], v[52:55]
	v_mfma_f32_16x16x32_bf16 v[40:43], v[140:143], v[196:199], v[40:43]
	v_mfma_f32_16x16x32_bf16 v[28:31], v[132:135], v[204:207], v[28:31]
	v_mfma_f32_16x16x32_bf16 v[24:27], v[140:143], v[204:207], v[24:27]
	v_mfma_f32_16x16x32_bf16 v[12:15], v[132:135], v[212:215], v[12:15]
	v_mfma_f32_16x16x32_bf16 v[8:11], v[140:143], v[212:215], v[8:11]
	s_setprio 0
	s_setprio 1
	v_mfma_f32_16x16x32_bf16 v[48:51], v[144:147], v[184:187], v[48:51]
	v_mfma_f32_16x16x32_bf16 v[44:47], v[168:171], v[184:187], v[44:47]
	v_mfma_f32_16x16x32_bf16 v[36:39], v[144:147], v[192:195], v[36:39]
	v_mfma_f32_16x16x32_bf16 v[32:35], v[168:171], v[192:195], v[32:35]
	v_mfma_f32_16x16x32_bf16 v[20:23], v[144:147], v[200:203], v[20:23]
	v_mfma_f32_16x16x32_bf16 v[16:19], v[168:171], v[200:203], v[16:19]
	v_mfma_f32_16x16x32_bf16 v[4:7], v[144:147], v[208:211], v[4:7]
	v_mfma_f32_16x16x32_bf16 v[0:3], v[168:171], v[208:211], v[0:3]
	v_mfma_f32_16x16x32_bf16 v[48:51], v[164:167], v[188:191], v[48:51]
	v_mfma_f32_16x16x32_bf16 v[44:47], v[180:183], v[188:191], v[44:47]
	v_mfma_f32_16x16x32_bf16 v[36:39], v[164:167], v[196:199], v[36:39]
	v_mfma_f32_16x16x32_bf16 v[32:35], v[180:183], v[196:199], v[32:35]
	v_mfma_f32_16x16x32_bf16 v[20:23], v[164:167], v[204:207], v[20:23]
	v_mfma_f32_16x16x32_bf16 v[16:19], v[180:183], v[204:207], v[16:19]
	v_mfma_f32_16x16x32_bf16 v[4:7], v[164:167], v[212:215], v[4:7]
	v_mfma_f32_16x16x32_bf16 v[0:3], v[180:183], v[212:215], v[0:3]
	s_setprio 0
	s_barrier
	s_add_i32 s77, 0, 0x18000
	s_add_i32 s78, 0, 0x1c000
	v_add_u32_e32 v140, s77, v175
	v_add_u32_e32 v180, s78, v175
	ds_read_b128 v[128:131], v140
	ds_read_b128 v[132:135], v140 offset:1024
	ds_read_b128 v[136:139], v140 offset:2048
	ds_read_b128 v[140:143], v140 offset:3072
	ds_read_b128 v[144:147], v180
	ds_read_b128 v[164:167], v180 offset:1024
	ds_read_b128 v[168:171], v180 offset:2048
	ds_read_b128 v[180:183], v180 offset:3072
	s_add_u32 s38, s42, 0x140000
	s_addc_u32 s39, s43, 0
	s_mov_b32 m0, s61
	ds_read_b128 v[184:187], v178 offset:32768
	ds_read_b128 v[188:191], v178 offset:33792
	ds_read_b128 v[192:195], v178 offset:34816
	ds_read_b128 v[196:199], v178 offset:35840
	ds_read_b128 v[200:203], v178 offset:36864
	ds_read_b128 v[204:207], v178 offset:37888
	ds_read_b128 v[208:211], v178 offset:38912
	ds_read_b128 v[212:215], v178 offset:39936
	global_load_lds_dwordx4 v148, s[38:39]
	s_mov_b32 m0, s62
	s_nop 0
	global_load_lds_dwordx4 v152, s[38:39]
	s_waitcnt vmcnt(8)
	s_waitcnt lgkmcnt(0)
	s_barrier
	s_setprio 1
	s_waitcnt lgkmcnt(0)
	v_mfma_f32_16x16x32_bf16 v[124:127], v[128:131], v[184:187], v[124:127]
	v_mfma_f32_16x16x32_bf16 v[120:123], v[136:139], v[184:187], v[120:123]
	v_mfma_f32_16x16x32_bf16 v[116:119], v[128:131], v[192:195], v[116:119]
	v_mfma_f32_16x16x32_bf16 v[104:107], v[136:139], v[192:195], v[104:107]
	v_mfma_f32_16x16x32_bf16 v[92:95], v[128:131], v[200:203], v[92:95]
	v_mfma_f32_16x16x32_bf16 v[88:91], v[136:139], v[200:203], v[88:91]
	v_mfma_f32_16x16x32_bf16 v[76:79], v[128:131], v[208:211], v[76:79]
	v_mfma_f32_16x16x32_bf16 v[72:75], v[136:139], v[208:211], v[72:75]
	v_mfma_f32_16x16x32_bf16 v[124:127], v[132:135], v[188:191], v[124:127]
	v_mfma_f32_16x16x32_bf16 v[120:123], v[140:143], v[188:191], v[120:123]
	v_mfma_f32_16x16x32_bf16 v[116:119], v[132:135], v[196:199], v[116:119]
	v_mfma_f32_16x16x32_bf16 v[104:107], v[140:143], v[196:199], v[104:107]
	v_mfma_f32_16x16x32_bf16 v[92:95], v[132:135], v[204:207], v[92:95]
	v_mfma_f32_16x16x32_bf16 v[88:91], v[140:143], v[204:207], v[88:91]
	v_mfma_f32_16x16x32_bf16 v[76:79], v[132:135], v[212:215], v[76:79]
	v_mfma_f32_16x16x32_bf16 v[72:75], v[140:143], v[212:215], v[72:75]
	s_setprio 0
	s_setprio 1
	v_mfma_f32_16x16x32_bf16 v[112:115], v[144:147], v[184:187], v[112:115]
	v_mfma_f32_16x16x32_bf16 v[108:111], v[168:171], v[184:187], v[108:111]
	v_mfma_f32_16x16x32_bf16 v[100:103], v[144:147], v[192:195], v[100:103]
	v_mfma_f32_16x16x32_bf16 v[96:99], v[168:171], v[192:195], v[96:99]
	v_mfma_f32_16x16x32_bf16 v[84:87], v[144:147], v[200:203], v[84:87]
	v_mfma_f32_16x16x32_bf16 v[80:83], v[168:171], v[200:203], v[80:83]
	v_mfma_f32_16x16x32_bf16 v[68:71], v[144:147], v[208:211], v[68:71]
	v_mfma_f32_16x16x32_bf16 v[64:67], v[168:171], v[208:211], v[64:67]
	v_mfma_f32_16x16x32_bf16 v[112:115], v[164:167], v[188:191], v[112:115]
	v_mfma_f32_16x16x32_bf16 v[108:111], v[180:183], v[188:191], v[108:111]
	v_mfma_f32_16x16x32_bf16 v[100:103], v[164:167], v[196:199], v[100:103]
	v_mfma_f32_16x16x32_bf16 v[96:99], v[180:183], v[196:199], v[96:99]
	v_mfma_f32_16x16x32_bf16 v[84:87], v[164:167], v[204:207], v[84:87]
	v_mfma_f32_16x16x32_bf16 v[80:83], v[180:183], v[204:207], v[80:83]
	v_mfma_f32_16x16x32_bf16 v[68:71], v[164:167], v[212:215], v[68:71]
	v_mfma_f32_16x16x32_bf16 v[64:67], v[180:183], v[212:215], v[64:67]
	s_setprio 0
	s_barrier
	s_add_i32 s38, s77, s58
	s_add_i32 m0, s38, 0xffffff80
	ds_read_b128 v[184:187], v178 offset:49152
	ds_read_b128 v[188:191], v178 offset:50176
	ds_read_b128 v[192:195], v178 offset:51200
	ds_read_b128 v[196:199], v178 offset:52224
	ds_read_b128 v[200:203], v178 offset:53248
	ds_read_b128 v[204:207], v178 offset:54272
	ds_read_b128 v[208:211], v178 offset:55296
	ds_read_b128 v[212:215], v178 offset:56320
	global_load_lds_dwordx4 v150, s[98:99] offset:128
	s_add_i32 m0, s38, 0x1f80
	s_add_u32 s38, s40, 0x80080
	s_addc_u32 s39, s41, 0
	s_add_i32 s40, s78, s58
	global_load_lds_dwordx4 v154, s[98:99] offset:128
	s_mov_b32 m0, s40
	s_nop 0
	global_load_lds_dwordx4 v150, s[38:39]
	s_add_i32 m0, s40, 0x2000
	s_nop 0
	global_load_lds_dwordx4 v154, s[38:39]
	s_add_i32 m0, s64, 0xffffff80
	s_nop 0
	global_load_lds_dwordx4 v148, s[100:101] offset:128
	s_add_i32 m0, s65, 0xffffff80
	s_nop 0
	global_load_lds_dwordx4 v152, s[100:101] offset:128
	s_waitcnt vmcnt(8)
	s_waitcnt lgkmcnt(0)
	s_barrier
	s_setprio 1
	s_waitcnt lgkmcnt(0)
	v_mfma_f32_16x16x32_bf16 v[60:63], v[128:131], v[184:187], v[60:63]
	v_mfma_f32_16x16x32_bf16 v[56:59], v[136:139], v[184:187], v[56:59]
	v_mfma_f32_16x16x32_bf16 v[52:55], v[128:131], v[192:195], v[52:55]
	v_mfma_f32_16x16x32_bf16 v[40:43], v[136:139], v[192:195], v[40:43]
	v_mfma_f32_16x16x32_bf16 v[28:31], v[128:131], v[200:203], v[28:31]
	v_mfma_f32_16x16x32_bf16 v[24:27], v[136:139], v[200:203], v[24:27]
	v_mfma_f32_16x16x32_bf16 v[12:15], v[128:131], v[208:211], v[12:15]
	v_mfma_f32_16x16x32_bf16 v[8:11], v[136:139], v[208:211], v[8:11]
	v_mfma_f32_16x16x32_bf16 v[60:63], v[132:135], v[188:191], v[60:63]
	v_mfma_f32_16x16x32_bf16 v[56:59], v[140:143], v[188:191], v[56:59]
	v_mfma_f32_16x16x32_bf16 v[52:55], v[132:135], v[196:199], v[52:55]
	v_mfma_f32_16x16x32_bf16 v[40:43], v[140:143], v[196:199], v[40:43]
	v_mfma_f32_16x16x32_bf16 v[28:31], v[132:135], v[204:207], v[28:31]
	v_mfma_f32_16x16x32_bf16 v[24:27], v[140:143], v[204:207], v[24:27]
	v_mfma_f32_16x16x32_bf16 v[12:15], v[132:135], v[212:215], v[12:15]
	v_mfma_f32_16x16x32_bf16 v[8:11], v[140:143], v[212:215], v[8:11]
	s_setprio 0
	s_setprio 1
	v_mfma_f32_16x16x32_bf16 v[48:51], v[144:147], v[184:187], v[48:51]
	v_mfma_f32_16x16x32_bf16 v[44:47], v[168:171], v[184:187], v[44:47]
	v_mfma_f32_16x16x32_bf16 v[36:39], v[144:147], v[192:195], v[36:39]
	v_mfma_f32_16x16x32_bf16 v[32:35], v[168:171], v[192:195], v[32:35]
	v_mfma_f32_16x16x32_bf16 v[20:23], v[144:147], v[200:203], v[20:23]
	v_mfma_f32_16x16x32_bf16 v[16:19], v[168:171], v[200:203], v[16:19]
	v_mfma_f32_16x16x32_bf16 v[4:7], v[144:147], v[208:211], v[4:7]
	v_mfma_f32_16x16x32_bf16 v[0:3], v[168:171], v[208:211], v[0:3]
	v_mfma_f32_16x16x32_bf16 v[48:51], v[164:167], v[188:191], v[48:51]
	v_mfma_f32_16x16x32_bf16 v[44:47], v[180:183], v[188:191], v[44:47]
	v_mfma_f32_16x16x32_bf16 v[36:39], v[164:167], v[196:199], v[36:39]
	v_mfma_f32_16x16x32_bf16 v[32:35], v[180:183], v[196:199], v[32:35]
	v_mfma_f32_16x16x32_bf16 v[20:23], v[164:167], v[204:207], v[20:23]
	v_mfma_f32_16x16x32_bf16 v[16:19], v[180:183], v[204:207], v[16:19]
	v_mfma_f32_16x16x32_bf16 v[4:7], v[164:167], v[212:215], v[4:7]
	v_mfma_f32_16x16x32_bf16 v[0:3], v[180:183], v[212:215], v[0:3]
	s_setprio 0
	s_barrier
	s_add_i32 s76, s76, 2
	s_add_u32 s74, s74, 0x100
	s_addc_u32 s75, s75, 0
	s_cmp_gt_u32 s76, 29
	s_mov_b64 s[38:39], s[6:7]
	s_cbranch_scc0 .LBB0_519
	s_and_b64 vcc, exec, s[16:17]
	s_cbranch_vccz .LBB0_522
	s_barrier

.LBB0_604:
	s_waitcnt vmcnt(0)
	ds_read_b128 v[24:27], v215
	ds_read_b128 v[32:35], v215 offset:1024
	ds_read_b128 v[40:43], v215 offset:2048
	ds_read_b128 v[44:47], v215 offset:3072
	ds_read_b128 v[56:59], v216
	ds_read_b128 v[60:63], v216 offset:1024
	ds_read_b128 v[64:67], v216 offset:2048
	ds_read_b128 v[68:71], v216 offset:3072
	s_add_u32 s10, s6, 0xfff80080
	s_addc_u32 s11, s7, -1
	s_cmp_eq_u32 s75, 28
	s_cselect_b32 s13, s5, s11
	s_cselect_b32 s12, s9, s10
	s_cselect_b32 s11, s33, s74
	s_cselect_b32 s10, s67, s69
	s_add_i32 m0, s62, 0xc000
	ds_read_b128 v[152:155], v217
	ds_read_b128 v[164:167], v217 offset:1024
	ds_read_b128 v[168:171], v217 offset:2048
	ds_read_b128 v[198:201], v217 offset:3072
	ds_read_b128 v[202:205], v217 offset:4096
	ds_read_b128 v[206:209], v217 offset:5120
	ds_read_b128 v[222:225], v217 offset:6144
	ds_read_b128 v[226:229], v217 offset:7168
	global_load_lds_dwordx4 v190, s[6:7]
	s_add_i32 m0, s62, 0xe000
	s_nop 0
	global_load_lds_dwordx4 v192, s[6:7]
	s_waitcnt vmcnt(8)
	s_waitcnt lgkmcnt(0)
	s_barrier
	s_setprio 1
	s_waitcnt lgkmcnt(0)
	v_mfma_f32_16x16x32_bf16 v[160:163], v[24:27], v[152:155], v[160:163]
	v_mfma_f32_16x16x32_bf16 v[156:159], v[40:43], v[152:155], v[156:159]
	v_mfma_f32_16x16x32_bf16 v[140:143], v[24:27], v[168:171], v[140:143]
	v_mfma_f32_16x16x32_bf16 v[136:139], v[40:43], v[168:171], v[136:139]
	v_mfma_f32_16x16x32_bf16 v[124:127], v[24:27], v[202:205], v[124:127]
	v_mfma_f32_16x16x32_bf16 v[120:123], v[40:43], v[202:205], v[120:123]
	v_mfma_f32_16x16x32_bf16 v[108:111], v[24:27], v[222:225], v[108:111]
	v_mfma_f32_16x16x32_bf16 v[104:107], v[40:43], v[222:225], v[104:107]
	v_mfma_f32_16x16x32_bf16 v[160:163], v[32:35], v[164:167], v[160:163]
	v_mfma_f32_16x16x32_bf16 v[156:159], v[44:47], v[164:167], v[156:159]
	v_mfma_f32_16x16x32_bf16 v[140:143], v[32:35], v[198:201], v[140:143]
	v_mfma_f32_16x16x32_bf16 v[136:139], v[44:47], v[198:201], v[136:139]
	v_mfma_f32_16x16x32_bf16 v[124:127], v[32:35], v[206:209], v[124:127]
	v_mfma_f32_16x16x32_bf16 v[120:123], v[44:47], v[206:209], v[120:123]
	v_mfma_f32_16x16x32_bf16 v[108:111], v[32:35], v[226:229], v[108:111]
	v_mfma_f32_16x16x32_bf16 v[104:107], v[44:47], v[226:229], v[104:107]
	s_setprio 0
	s_setprio 1
	v_mfma_f32_16x16x32_bf16 v[148:151], v[56:59], v[152:155], v[148:151]
	v_mfma_f32_16x16x32_bf16 v[144:147], v[64:67], v[152:155], v[144:147]
	v_mfma_f32_16x16x32_bf16 v[132:135], v[56:59], v[168:171], v[132:135]
	v_mfma_f32_16x16x32_bf16 v[128:131], v[64:67], v[168:171], v[128:131]
	v_mfma_f32_16x16x32_bf16 v[116:119], v[56:59], v[202:205], v[116:119]
	v_mfma_f32_16x16x32_bf16 v[112:115], v[64:67], v[202:205], v[112:115]
	v_mfma_f32_16x16x32_bf16 v[100:103], v[56:59], v[222:225], v[100:103]
	v_mfma_f32_16x16x32_bf16 v[96:99], v[64:67], v[222:225], v[96:99]
	v_mfma_f32_16x16x32_bf16 v[148:151], v[60:63], v[164:167], v[148:151]
	v_mfma_f32_16x16x32_bf16 v[144:147], v[68:71], v[164:167], v[144:147]
	v_mfma_f32_16x16x32_bf16 v[132:135], v[60:63], v[198:201], v[132:135]
	v_mfma_f32_16x16x32_bf16 v[128:131], v[68:71], v[198:201], v[128:131]
	v_mfma_f32_16x16x32_bf16 v[116:119], v[60:63], v[206:209], v[116:119]
	v_mfma_f32_16x16x32_bf16 v[112:115], v[68:71], v[206:209], v[112:115]
	v_mfma_f32_16x16x32_bf16 v[100:103], v[60:63], v[226:229], v[100:103]
	v_mfma_f32_16x16x32_bf16 v[96:99], v[68:71], v[226:229], v[96:99]
	s_setprio 0
	s_barrier
	s_add_i32 s87, s81, s61
	s_mov_b64 s[98:99], s[10:11]
	s_mov_b32 m0, s87
	ds_read_b128 v[152:155], v217 offset:16384
	ds_read_b128 v[164:167], v217 offset:17408
	ds_read_b128 v[168:171], v217 offset:18432
	ds_read_b128 v[198:201], v217 offset:19456
	ds_read_b128 v[202:205], v217 offset:20480
	ds_read_b128 v[206:209], v217 offset:21504
	ds_read_b128 v[222:225], v217 offset:22528
	ds_read_b128 v[226:229], v217 offset:23552
	global_load_lds_dwordx4 v174, s[10:11]
	s_add_i32 m0, s87, 0x2000
	s_add_u32 s88, s10, 0x80000
	s_addc_u32 s89, s11, 0
	s_add_i32 s87, s82, s61
	global_load_lds_dwordx4 v178, s[10:11]
	s_mov_b32 m0, s87
	s_mov_b64 s[100:101], s[12:13]
	global_load_lds_dwordx4 v174, s[88:89]
	s_add_i32 m0, s87, 0x2000
	s_nop 0
	global_load_lds_dwordx4 v178, s[88:89]
	s_mov_b32 m0, s62
	s_nop 0
	global_load_lds_dwordx4 v172, s[12:13]
	s_mov_b32 m0, s63
	s_nop 0
	global_load_lds_dwordx4 v176, s[12:13]
	s_waitcnt vmcnt(8)
	s_waitcnt lgkmcnt(0)
	s_barrier
	s_setprio 1
	s_waitcnt lgkmcnt(0)
	v_mfma_f32_16x16x32_bf16 v[92:95], v[24:27], v[152:155], v[92:95]
	v_mfma_f32_16x16x32_bf16 v[88:91], v[40:43], v[152:155], v[88:91]
	v_mfma_f32_16x16x32_bf16 v[76:79], v[24:27], v[168:171], v[76:79]
	v_mfma_f32_16x16x32_bf16 v[72:75], v[40:43], v[168:171], v[72:75]
	v_mfma_f32_16x16x32_bf16 v[36:39], v[24:27], v[202:205], v[36:39]
	v_mfma_f32_16x16x32_bf16 v[28:31], v[40:43], v[202:205], v[28:31]
	v_mfma_f32_16x16x32_bf16 v[12:15], v[24:27], v[222:225], v[12:15]
	v_mfma_f32_16x16x32_bf16 v[8:11], v[40:43], v[222:225], v[8:11]
	v_mfma_f32_16x16x32_bf16 v[92:95], v[32:35], v[164:167], v[92:95]
	v_mfma_f32_16x16x32_bf16 v[88:91], v[44:47], v[164:167], v[88:91]
	v_mfma_f32_16x16x32_bf16 v[76:79], v[32:35], v[198:201], v[76:79]
	v_mfma_f32_16x16x32_bf16 v[72:75], v[44:47], v[198:201], v[72:75]
	v_mfma_f32_16x16x32_bf16 v[36:39], v[32:35], v[206:209], v[36:39]
	v_mfma_f32_16x16x32_bf16 v[28:31], v[44:47], v[206:209], v[28:31]
	v_mfma_f32_16x16x32_bf16 v[12:15], v[32:35], v[226:229], v[12:15]
	v_mfma_f32_16x16x32_bf16 v[8:11], v[44:47], v[226:229], v[8:11]
	s_setprio 0
	s_setprio 1
	v_mfma_f32_16x16x32_bf16 v[20:23], v[56:59], v[202:205], v[20:23]
	v_mfma_f32_16x16x32_bf16 v[16:19], v[64:67], v[202:205], v[16:19]
	v_mfma_f32_16x16x32_bf16 v[4:7], v[56:59], v[222:225], v[4:7]
	v_mfma_f32_16x16x32_bf16 v[0:3], v[64:67], v[222:225], v[0:3]
	v_mfma_f32_16x16x32_bf16 v[24:27], v[56:59], v[152:155], v[84:87]
	v_mfma_f32_16x16x32_bf16 v[32:35], v[64:67], v[152:155], v[80:83]
	v_mfma_f32_16x16x32_bf16 v[40:43], v[56:59], v[168:171], v[52:55]
	v_mfma_f32_16x16x32_bf16 v[44:47], v[64:67], v[168:171], v[48:51]
	v_mfma_f32_16x16x32_bf16 v[20:23], v[60:63], v[206:209], v[20:23]
	v_mfma_f32_16x16x32_bf16 v[16:19], v[68:71], v[206:209], v[16:19]
	v_mfma_f32_16x16x32_bf16 v[4:7], v[60:63], v[226:229], v[4:7]
	v_mfma_f32_16x16x32_bf16 v[0:3], v[68:71], v[226:229], v[0:3]
	v_mfma_f32_16x16x32_bf16 v[24:27], v[60:63], v[164:167], v[24:27]
	v_mfma_f32_16x16x32_bf16 v[32:35], v[68:71], v[164:167], v[32:35]
	v_mfma_f32_16x16x32_bf16 v[40:43], v[60:63], v[198:201], v[40:43]
	v_mfma_f32_16x16x32_bf16 v[44:47], v[68:71], v[198:201], v[44:47]
	s_setprio 0
	s_barrier
	s_add_i32 s87, 0, 0x18000
	s_add_i32 s88, 0, 0x1c000
	v_add_u32_e32 v60, s87, v213
	v_add_u32_e32 v80, s88, v213
	ds_read_b128 v[48:51], v60
	ds_read_b128 v[52:55], v60 offset:1024
	ds_read_b128 v[56:59], v60 offset:2048
	ds_read_b128 v[60:63], v60 offset:3072
	ds_read_b128 v[64:67], v80
	ds_read_b128 v[68:71], v80 offset:1024
	ds_read_b128 v[152:155], v80 offset:2048
	ds_read_b128 v[164:167], v80 offset:3072
	s_add_u32 s12, s12, 0x80000
	s_addc_u32 s13, s13, 0
	s_mov_b32 m0, s64
	ds_read_b128 v[80:83], v217 offset:32768
	ds_read_b128 v[84:87], v217 offset:33792
	ds_read_b128 v[168:171], v217 offset:34816
	ds_read_b128 v[198:201], v217 offset:35840
	ds_read_b128 v[202:205], v217 offset:36864
	ds_read_b128 v[206:209], v217 offset:37888
	ds_read_b128 v[222:225], v217 offset:38912
	ds_read_b128 v[226:229], v217 offset:39936
	global_load_lds_dwordx4 v172, s[12:13]
	s_mov_b32 m0, s65
	s_nop 0
	global_load_lds_dwordx4 v176, s[12:13]
	s_waitcnt vmcnt(8)
	s_waitcnt lgkmcnt(0)
	s_barrier
	s_setprio 1
	s_waitcnt lgkmcnt(0)
	v_mfma_f32_16x16x32_bf16 v[160:163], v[48:51], v[80:83], v[160:163]
	v_mfma_f32_16x16x32_bf16 v[156:159], v[56:59], v[80:83], v[156:159]
	v_mfma_f32_16x16x32_bf16 v[140:143], v[48:51], v[168:171], v[140:143]
	v_mfma_f32_16x16x32_bf16 v[136:139], v[56:59], v[168:171], v[136:139]
	v_mfma_f32_16x16x32_bf16 v[124:127], v[48:51], v[202:205], v[124:127]
	v_mfma_f32_16x16x32_bf16 v[120:123], v[56:59], v[202:205], v[120:123]
	v_mfma_f32_16x16x32_bf16 v[108:111], v[48:51], v[222:225], v[108:111]
	v_mfma_f32_16x16x32_bf16 v[104:107], v[56:59], v[222:225], v[104:107]
	v_mfma_f32_16x16x32_bf16 v[160:163], v[52:55], v[84:87], v[160:163]
	v_mfma_f32_16x16x32_bf16 v[156:159], v[60:63], v[84:87], v[156:159]
	v_mfma_f32_16x16x32_bf16 v[140:143], v[52:55], v[198:201], v[140:143]
	v_mfma_f32_16x16x32_bf16 v[136:139], v[60:63], v[198:201], v[136:139]
	v_mfma_f32_16x16x32_bf16 v[124:127], v[52:55], v[206:209], v[124:127]
	v_mfma_f32_16x16x32_bf16 v[120:123], v[60:63], v[206:209], v[120:123]
	v_mfma_f32_16x16x32_bf16 v[108:111], v[52:55], v[226:229], v[108:111]
	v_mfma_f32_16x16x32_bf16 v[104:107], v[60:63], v[226:229], v[104:107]
	s_setprio 0
	s_setprio 1
	v_mfma_f32_16x16x32_bf16 v[148:151], v[64:67], v[80:83], v[148:151]
	v_mfma_f32_16x16x32_bf16 v[80:83], v[152:155], v[80:83], v[144:147]
	v_mfma_f32_16x16x32_bf16 v[144:147], v[164:167], v[84:87], v[80:83]
	v_mfma_f32_16x16x32_bf16 v[80:83], v[64:67], v[168:171], v[132:135]
	v_mfma_f32_16x16x32_bf16 v[132:135], v[68:71], v[198:201], v[80:83]
	v_mfma_f32_16x16x32_bf16 v[80:83], v[152:155], v[168:171], v[128:131]
	v_mfma_f32_16x16x32_bf16 v[128:131], v[164:167], v[198:201], v[80:83]
	v_mfma_f32_16x16x32_bf16 v[80:83], v[64:67], v[202:205], v[116:119]
	v_mfma_f32_16x16x32_bf16 v[116:119], v[68:71], v[206:209], v[80:83]
	v_mfma_f32_16x16x32_bf16 v[80:83], v[152:155], v[202:205], v[112:115]
	v_mfma_f32_16x16x32_bf16 v[112:115], v[164:167], v[206:209], v[80:83]
	v_mfma_f32_16x16x32_bf16 v[80:83], v[64:67], v[222:225], v[100:103]
	v_mfma_f32_16x16x32_bf16 v[100:103], v[68:71], v[226:229], v[80:83]
	v_mfma_f32_16x16x32_bf16 v[80:83], v[152:155], v[222:225], v[96:99]
	v_mfma_f32_16x16x32_bf16 v[148:151], v[68:71], v[84:87], v[148:151]
	v_mfma_f32_16x16x32_bf16 v[96:99], v[164:167], v[226:229], v[80:83]
	s_setprio 0
	s_barrier
	s_add_i32 s12, s87, s61
	s_add_i32 m0, s12, 0xffffff80
	s_nop 0
	ds_read_b128 v[80:83], v217 offset:49152
	ds_read_b128 v[168:171], v217 offset:50176
	ds_read_b128 v[198:201], v217 offset:51200
	ds_read_b128 v[202:205], v217 offset:52224
	ds_read_b128 v[206:209], v217 offset:53248
	ds_read_b128 v[222:225], v217 offset:54272
	ds_read_b128 v[226:229], v217 offset:55296
	ds_read_b128 v[230:233], v217 offset:56320
	global_load_lds_dwordx4 v174, s[98:99] offset:128
	s_add_i32 m0, s12, 0x1f80
	s_add_u32 s10, s10, 0x80080
	s_addc_u32 s11, s11, 0
	s_add_i32 s12, s88, s61
	global_load_lds_dwordx4 v178, s[98:99] offset:128
	s_mov_b32 m0, s12
	s_nop 0
	global_load_lds_dwordx4 v174, s[10:11]
	s_add_i32 m0, s12, 0x2000
	s_nop 0
	global_load_lds_dwordx4 v178, s[10:11]
	s_add_i32 m0, s77, 0xffffff80
	s_nop 0
	global_load_lds_dwordx4 v172, s[100:101] offset:128
	s_add_i32 m0, s78, 0xffffff80
	s_nop 0
	global_load_lds_dwordx4 v176, s[100:101] offset:128
	s_waitcnt vmcnt(8)
	s_waitcnt lgkmcnt(0)
	s_barrier
	s_setprio 1
	s_waitcnt lgkmcnt(0)
	v_mfma_f32_16x16x32_bf16 v[84:87], v[48:51], v[80:83], v[92:95]
	v_mfma_f32_16x16x32_bf16 v[92:95], v[52:55], v[168:171], v[84:87]
	v_mfma_f32_16x16x32_bf16 v[84:87], v[56:59], v[80:83], v[88:91]
	v_mfma_f32_16x16x32_bf16 v[76:79], v[48:51], v[198:201], v[76:79]
	v_mfma_f32_16x16x32_bf16 v[72:75], v[56:59], v[198:201], v[72:75]
	v_mfma_f32_16x16x32_bf16 v[36:39], v[48:51], v[206:209], v[36:39]
	v_mfma_f32_16x16x32_bf16 v[28:31], v[56:59], v[206:209], v[28:31]
	v_mfma_f32_16x16x32_bf16 v[12:15], v[48:51], v[226:229], v[12:15]
	v_mfma_f32_16x16x32_bf16 v[8:11], v[56:59], v[226:229], v[8:11]
	v_mfma_f32_16x16x32_bf16 v[88:91], v[60:63], v[168:171], v[84:87]
	v_mfma_f32_16x16x32_bf16 v[76:79], v[52:55], v[202:205], v[76:79]
	v_mfma_f32_16x16x32_bf16 v[72:75], v[60:63], v[202:205], v[72:75]
	v_mfma_f32_16x16x32_bf16 v[36:39], v[52:55], v[222:225], v[36:39]
	v_mfma_f32_16x16x32_bf16 v[28:31], v[60:63], v[222:225], v[28:31]
	v_mfma_f32_16x16x32_bf16 v[12:15], v[52:55], v[230:233], v[12:15]
	v_mfma_f32_16x16x32_bf16 v[8:11], v[60:63], v[230:233], v[8:11]
	s_setprio 0
	s_setprio 1
	v_mfma_f32_16x16x32_bf16 v[24:27], v[64:67], v[80:83], v[24:27]
	v_mfma_f32_16x16x32_bf16 v[84:87], v[68:71], v[168:171], v[24:27]
	v_mfma_f32_16x16x32_bf16 v[24:27], v[152:155], v[80:83], v[32:35]
	v_mfma_f32_16x16x32_bf16 v[80:83], v[164:167], v[168:171], v[24:27]
	v_mfma_f32_16x16x32_bf16 v[24:27], v[64:67], v[198:201], v[40:43]
	v_mfma_f32_16x16x32_bf16 v[52:55], v[68:71], v[202:205], v[24:27]
	v_mfma_f32_16x16x32_bf16 v[24:27], v[152:155], v[198:201], v[44:47]
	v_mfma_f32_16x16x32_bf16 v[20:23], v[64:67], v[206:209], v[20:23]
	v_mfma_f32_16x16x32_bf16 v[16:19], v[152:155], v[206:209], v[16:19]
	v_mfma_f32_16x16x32_bf16 v[4:7], v[64:67], v[226:229], v[4:7]
	v_mfma_f32_16x16x32_bf16 v[0:3], v[152:155], v[226:229], v[0:3]
	v_mfma_f32_16x16x32_bf16 v[48:51], v[164:167], v[202:205], v[24:27]
	v_mfma_f32_16x16x32_bf16 v[20:23], v[68:71], v[222:225], v[20:23]
	v_mfma_f32_16x16x32_bf16 v[16:19], v[164:167], v[222:225], v[16:19]
	v_mfma_f32_16x16x32_bf16 v[4:7], v[68:71], v[230:233], v[4:7]
	v_mfma_f32_16x16x32_bf16 v[0:3], v[164:167], v[230:233], v[0:3]
	s_setprio 0
	s_barrier
	s_add_i32 s75, s75, 2
	s_add_u32 s6, s6, 0x100
	s_addc_u32 s7, s7, 0
	s_add_u32 s69, s69, 0x100
	s_addc_u32 s74, s74, 0
	s_cmp_gt_u32 s75, 29
	s_cbranch_scc0 .LBB0_604
	s_and_b64 vcc, exec, s[40:41]
	s_cbranch_vccz .LBB0_607
	s_barrier

.LBB0_992:
	ds_read_b128 v[128:131], v183
	ds_read_b128 v[132:135], v183 offset:1024
	ds_read_b128 v[136:139], v183 offset:2048
	ds_read_b128 v[140:143], v183 offset:3072
	ds_read_b128 v[144:147], v184
	ds_read_b128 v[164:167], v184 offset:1024
	ds_read_b128 v[168:171], v184 offset:2048
	ds_read_b128 v[172:175], v184 offset:3072
	s_add_u32 s42, s40, 0xffe00080
	s_addc_u32 s43, s41, -1
	s_cmp_eq_u32 s75, 28
	s_cselect_b32 s53, s19, s43
	s_cselect_b32 s52, s71, s42
	s_cselect_b32 s43, s17, s74
	s_cselect_b32 s42, s72, s73
	s_add_i32 m0, s61, 0xc000
	ds_read_b128 v[176:179], v185
	ds_read_b128 v[188:191], v185 offset:1024
	ds_read_b128 v[192:195], v185 offset:2048
	ds_read_b128 v[196:199], v185 offset:3072
	ds_read_b128 v[200:203], v185 offset:4096
	ds_read_b128 v[204:207], v185 offset:5120
	ds_read_b128 v[208:211], v185 offset:6144
	ds_read_b128 v[212:215], v185 offset:7168
	global_load_lds_dwordx4 v158, s[40:41]
	s_add_i32 m0, s61, 0xe000
	s_nop 0
	global_load_lds_dwordx4 v156, s[40:41]
	s_waitcnt vmcnt(8)
	s_waitcnt lgkmcnt(0)
	s_barrier
	s_setprio 1
	s_waitcnt lgkmcnt(0)
	v_mfma_f32_16x16x32_bf16 v[124:127], v[128:131], v[176:179], v[124:127]
	v_mfma_f32_16x16x32_bf16 v[120:123], v[136:139], v[176:179], v[120:123]
	v_mfma_f32_16x16x32_bf16 v[116:119], v[128:131], v[192:195], v[116:119]
	v_mfma_f32_16x16x32_bf16 v[104:107], v[136:139], v[192:195], v[104:107]
	v_mfma_f32_16x16x32_bf16 v[92:95], v[128:131], v[200:203], v[92:95]
	v_mfma_f32_16x16x32_bf16 v[88:91], v[136:139], v[200:203], v[88:91]
	v_mfma_f32_16x16x32_bf16 v[76:79], v[128:131], v[208:211], v[76:79]
	v_mfma_f32_16x16x32_bf16 v[72:75], v[136:139], v[208:211], v[72:75]
	v_mfma_f32_16x16x32_bf16 v[124:127], v[132:135], v[188:191], v[124:127]
	v_mfma_f32_16x16x32_bf16 v[120:123], v[140:143], v[188:191], v[120:123]
	v_mfma_f32_16x16x32_bf16 v[116:119], v[132:135], v[196:199], v[116:119]
	v_mfma_f32_16x16x32_bf16 v[104:107], v[140:143], v[196:199], v[104:107]
	v_mfma_f32_16x16x32_bf16 v[92:95], v[132:135], v[204:207], v[92:95]
	v_mfma_f32_16x16x32_bf16 v[88:91], v[140:143], v[204:207], v[88:91]
	v_mfma_f32_16x16x32_bf16 v[76:79], v[132:135], v[212:215], v[76:79]
	v_mfma_f32_16x16x32_bf16 v[72:75], v[140:143], v[212:215], v[72:75]
	s_setprio 0
	s_setprio 1
	v_mfma_f32_16x16x32_bf16 v[112:115], v[144:147], v[176:179], v[112:115]
	v_mfma_f32_16x16x32_bf16 v[108:111], v[168:171], v[176:179], v[108:111]
	v_mfma_f32_16x16x32_bf16 v[100:103], v[144:147], v[192:195], v[100:103]
	v_mfma_f32_16x16x32_bf16 v[96:99], v[168:171], v[192:195], v[96:99]
	v_mfma_f32_16x16x32_bf16 v[84:87], v[144:147], v[200:203], v[84:87]
	v_mfma_f32_16x16x32_bf16 v[80:83], v[168:171], v[200:203], v[80:83]
	v_mfma_f32_16x16x32_bf16 v[68:71], v[144:147], v[208:211], v[68:71]
	v_mfma_f32_16x16x32_bf16 v[64:67], v[168:171], v[208:211], v[64:67]
	v_mfma_f32_16x16x32_bf16 v[112:115], v[164:167], v[188:191], v[112:115]
	v_mfma_f32_16x16x32_bf16 v[108:111], v[172:175], v[188:191], v[108:111]
	v_mfma_f32_16x16x32_bf16 v[100:103], v[164:167], v[196:199], v[100:103]
	v_mfma_f32_16x16x32_bf16 v[96:99], v[172:175], v[196:199], v[96:99]
	v_mfma_f32_16x16x32_bf16 v[84:87], v[164:167], v[204:207], v[84:87]
	v_mfma_f32_16x16x32_bf16 v[80:83], v[172:175], v[204:207], v[80:83]
	v_mfma_f32_16x16x32_bf16 v[68:71], v[164:167], v[212:215], v[68:71]
	v_mfma_f32_16x16x32_bf16 v[64:67], v[172:175], v[212:215], v[64:67]
	s_setprio 0
	s_barrier
	s_add_i32 s76, s69, s60
	s_mov_b64 s[98:99], s[42:43]
	s_mov_b32 m0, s76
	ds_read_b128 v[176:179], v185 offset:16384
	ds_read_b128 v[188:191], v185 offset:17408
	ds_read_b128 v[192:195], v185 offset:18432
	ds_read_b128 v[196:199], v185 offset:19456
	ds_read_b128 v[200:203], v185 offset:20480
	ds_read_b128 v[204:207], v185 offset:21504
	ds_read_b128 v[208:211], v185 offset:22528
	ds_read_b128 v[212:215], v185 offset:23552
	global_load_lds_dwordx4 v150, s[42:43]
	s_add_i32 m0, s76, 0x2000
	s_add_u32 s76, s42, 0x80000
	s_addc_u32 s77, s43, 0
	s_add_i32 s78, s70, s60
	global_load_lds_dwordx4 v154, s[42:43]
	s_mov_b32 m0, s78
	s_mov_b64 s[100:101], s[52:53]
	global_load_lds_dwordx4 v150, s[76:77]
	s_add_i32 m0, s78, 0x2000
	s_nop 0
	global_load_lds_dwordx4 v154, s[76:77]
	s_mov_b32 m0, s61
	s_nop 0
	global_load_lds_dwordx4 v148, s[52:53]
	s_mov_b32 m0, s62
	s_nop 0
	global_load_lds_dwordx4 v152, s[52:53]
	s_waitcnt vmcnt(8)
	s_waitcnt lgkmcnt(0)
	s_barrier
	s_setprio 1
	s_waitcnt lgkmcnt(0)
	v_mfma_f32_16x16x32_bf16 v[60:63], v[128:131], v[176:179], v[60:63]
	v_mfma_f32_16x16x32_bf16 v[56:59], v[136:139], v[176:179], v[56:59]
	v_mfma_f32_16x16x32_bf16 v[52:55], v[128:131], v[192:195], v[52:55]
	v_mfma_f32_16x16x32_bf16 v[40:43], v[136:139], v[192:195], v[40:43]
	v_mfma_f32_16x16x32_bf16 v[28:31], v[128:131], v[200:203], v[28:31]
	v_mfma_f32_16x16x32_bf16 v[24:27], v[136:139], v[200:203], v[24:27]
	v_mfma_f32_16x16x32_bf16 v[12:15], v[128:131], v[208:211], v[12:15]
	v_mfma_f32_16x16x32_bf16 v[8:11], v[136:139], v[208:211], v[8:11]
	v_mfma_f32_16x16x32_bf16 v[60:63], v[132:135], v[188:191], v[60:63]
	v_mfma_f32_16x16x32_bf16 v[56:59], v[140:143], v[188:191], v[56:59]
	v_mfma_f32_16x16x32_bf16 v[52:55], v[132:135], v[196:199], v[52:55]
	v_mfma_f32_16x16x32_bf16 v[40:43], v[140:143], v[196:199], v[40:43]
	v_mfma_f32_16x16x32_bf16 v[28:31], v[132:135], v[204:207], v[28:31]
	v_mfma_f32_16x16x32_bf16 v[24:27], v[140:143], v[204:207], v[24:27]
	v_mfma_f32_16x16x32_bf16 v[12:15], v[132:135], v[212:215], v[12:15]
	v_mfma_f32_16x16x32_bf16 v[8:11], v[140:143], v[212:215], v[8:11]
	s_setprio 0
	s_setprio 1
	v_mfma_f32_16x16x32_bf16 v[48:51], v[144:147], v[176:179], v[48:51]
	v_mfma_f32_16x16x32_bf16 v[44:47], v[168:171], v[176:179], v[44:47]
	v_mfma_f32_16x16x32_bf16 v[36:39], v[144:147], v[192:195], v[36:39]
	v_mfma_f32_16x16x32_bf16 v[32:35], v[168:171], v[192:195], v[32:35]
	v_mfma_f32_16x16x32_bf16 v[20:23], v[144:147], v[200:203], v[20:23]
	v_mfma_f32_16x16x32_bf16 v[16:19], v[168:171], v[200:203], v[16:19]
	v_mfma_f32_16x16x32_bf16 v[4:7], v[144:147], v[208:211], v[4:7]
	v_mfma_f32_16x16x32_bf16 v[0:3], v[168:171], v[208:211], v[0:3]
	v_mfma_f32_16x16x32_bf16 v[48:51], v[164:167], v[188:191], v[48:51]
	v_mfma_f32_16x16x32_bf16 v[44:47], v[172:175], v[188:191], v[44:47]
	v_mfma_f32_16x16x32_bf16 v[36:39], v[164:167], v[196:199], v[36:39]
	v_mfma_f32_16x16x32_bf16 v[32:35], v[172:175], v[196:199], v[32:35]
	v_mfma_f32_16x16x32_bf16 v[20:23], v[164:167], v[204:207], v[20:23]
	v_mfma_f32_16x16x32_bf16 v[16:19], v[172:175], v[204:207], v[16:19]
	v_mfma_f32_16x16x32_bf16 v[4:7], v[164:167], v[212:215], v[4:7]
	v_mfma_f32_16x16x32_bf16 v[0:3], v[172:175], v[212:215], v[0:3]
	s_setprio 0
	s_barrier
	s_add_i32 s76, 0, 0x18000
	s_add_i32 s77, 0, 0x1c000
	v_add_u32_e32 v140, s76, v181
	v_add_u32_e32 v172, s77, v181
	ds_read_b128 v[128:131], v140
	ds_read_b128 v[132:135], v140 offset:1024
	ds_read_b128 v[136:139], v140 offset:2048
	ds_read_b128 v[140:143], v140 offset:3072
	ds_read_b128 v[144:147], v172
	ds_read_b128 v[164:167], v172 offset:1024
	ds_read_b128 v[168:171], v172 offset:2048
	ds_read_b128 v[172:175], v172 offset:3072
	s_add_u32 s52, s52, 0x200000
	s_addc_u32 s53, s53, 0
	s_mov_b32 m0, s63
	ds_read_b128 v[176:179], v185 offset:32768
	ds_read_b128 v[188:191], v185 offset:33792
	ds_read_b128 v[192:195], v185 offset:34816
	ds_read_b128 v[196:199], v185 offset:35840
	ds_read_b128 v[200:203], v185 offset:36864
	ds_read_b128 v[204:207], v185 offset:37888
	ds_read_b128 v[208:211], v185 offset:38912
	ds_read_b128 v[212:215], v185 offset:39936
	global_load_lds_dwordx4 v148, s[52:53]
	s_mov_b32 m0, s64
	s_nop 0
	global_load_lds_dwordx4 v152, s[52:53]
	s_waitcnt vmcnt(8)
	s_waitcnt lgkmcnt(0)
	s_barrier
	s_setprio 1
	s_waitcnt lgkmcnt(0)
	v_mfma_f32_16x16x32_bf16 v[124:127], v[128:131], v[176:179], v[124:127]
	v_mfma_f32_16x16x32_bf16 v[120:123], v[136:139], v[176:179], v[120:123]
	v_mfma_f32_16x16x32_bf16 v[116:119], v[128:131], v[192:195], v[116:119]
	v_mfma_f32_16x16x32_bf16 v[104:107], v[136:139], v[192:195], v[104:107]
	v_mfma_f32_16x16x32_bf16 v[92:95], v[128:131], v[200:203], v[92:95]
	v_mfma_f32_16x16x32_bf16 v[88:91], v[136:139], v[200:203], v[88:91]
	v_mfma_f32_16x16x32_bf16 v[76:79], v[128:131], v[208:211], v[76:79]
	v_mfma_f32_16x16x32_bf16 v[72:75], v[136:139], v[208:211], v[72:75]
	v_mfma_f32_16x16x32_bf16 v[124:127], v[132:135], v[188:191], v[124:127]
	v_mfma_f32_16x16x32_bf16 v[120:123], v[140:143], v[188:191], v[120:123]
	v_mfma_f32_16x16x32_bf16 v[116:119], v[132:135], v[196:199], v[116:119]
	v_mfma_f32_16x16x32_bf16 v[104:107], v[140:143], v[196:199], v[104:107]
	v_mfma_f32_16x16x32_bf16 v[92:95], v[132:135], v[204:207], v[92:95]
	v_mfma_f32_16x16x32_bf16 v[88:91], v[140:143], v[204:207], v[88:91]
	v_mfma_f32_16x16x32_bf16 v[76:79], v[132:135], v[212:215], v[76:79]
	v_mfma_f32_16x16x32_bf16 v[72:75], v[140:143], v[212:215], v[72:75]
	s_setprio 0
	s_setprio 1
	v_mfma_f32_16x16x32_bf16 v[112:115], v[144:147], v[176:179], v[112:115]
	v_mfma_f32_16x16x32_bf16 v[108:111], v[168:171], v[176:179], v[108:111]
	v_mfma_f32_16x16x32_bf16 v[100:103], v[144:147], v[192:195], v[100:103]
	v_mfma_f32_16x16x32_bf16 v[96:99], v[168:171], v[192:195], v[96:99]
	v_mfma_f32_16x16x32_bf16 v[84:87], v[144:147], v[200:203], v[84:87]
	v_mfma_f32_16x16x32_bf16 v[80:83], v[168:171], v[200:203], v[80:83]
	v_mfma_f32_16x16x32_bf16 v[68:71], v[144:147], v[208:211], v[68:71]
	v_mfma_f32_16x16x32_bf16 v[64:67], v[168:171], v[208:211], v[64:67]
	v_mfma_f32_16x16x32_bf16 v[112:115], v[164:167], v[188:191], v[112:115]
	v_mfma_f32_16x16x32_bf16 v[108:111], v[172:175], v[188:191], v[108:111]
	v_mfma_f32_16x16x32_bf16 v[100:103], v[164:167], v[196:199], v[100:103]
	v_mfma_f32_16x16x32_bf16 v[96:99], v[172:175], v[196:199], v[96:99]
	v_mfma_f32_16x16x32_bf16 v[84:87], v[164:167], v[204:207], v[84:87]
	v_mfma_f32_16x16x32_bf16 v[80:83], v[172:175], v[204:207], v[80:83]
	v_mfma_f32_16x16x32_bf16 v[68:71], v[164:167], v[212:215], v[68:71]
	v_mfma_f32_16x16x32_bf16 v[64:67], v[172:175], v[212:215], v[64:67]
	s_setprio 0
	s_barrier
	s_add_i32 s52, s76, s60
	s_add_i32 m0, s52, 0xffffff80
	ds_read_b128 v[176:179], v185 offset:49152
	ds_read_b128 v[188:191], v185 offset:50176
	ds_read_b128 v[192:195], v185 offset:51200
	ds_read_b128 v[196:199], v185 offset:52224
	ds_read_b128 v[200:203], v185 offset:53248
	ds_read_b128 v[204:207], v185 offset:54272
	ds_read_b128 v[208:211], v185 offset:55296
	ds_read_b128 v[212:215], v185 offset:56320
	global_load_lds_dwordx4 v150, s[98:99] offset:128
	s_add_i32 m0, s52, 0x1f80
	s_add_u32 s42, s42, 0x80080
	s_addc_u32 s43, s43, 0
	s_add_i32 s52, s77, s60
	global_load_lds_dwordx4 v154, s[98:99] offset:128
	s_mov_b32 m0, s52
	s_nop 0
	global_load_lds_dwordx4 v150, s[42:43]
	s_add_i32 m0, s52, 0x2000
	s_nop 0
	global_load_lds_dwordx4 v154, s[42:43]
	s_add_i32 m0, s66, 0xffffff80
	s_nop 0
	global_load_lds_dwordx4 v148, s[100:101] offset:128
	s_add_i32 m0, s67, 0xffffff80
	s_nop 0
	global_load_lds_dwordx4 v152, s[100:101] offset:128
	s_waitcnt vmcnt(8)
	s_waitcnt lgkmcnt(0)
	s_barrier
	s_setprio 1
	s_waitcnt lgkmcnt(0)
	v_mfma_f32_16x16x32_bf16 v[60:63], v[128:131], v[176:179], v[60:63]
	v_mfma_f32_16x16x32_bf16 v[56:59], v[136:139], v[176:179], v[56:59]
	v_mfma_f32_16x16x32_bf16 v[52:55], v[128:131], v[192:195], v[52:55]
	v_mfma_f32_16x16x32_bf16 v[40:43], v[136:139], v[192:195], v[40:43]
	v_mfma_f32_16x16x32_bf16 v[28:31], v[128:131], v[200:203], v[28:31]
	v_mfma_f32_16x16x32_bf16 v[24:27], v[136:139], v[200:203], v[24:27]
	v_mfma_f32_16x16x32_bf16 v[12:15], v[128:131], v[208:211], v[12:15]
	v_mfma_f32_16x16x32_bf16 v[8:11], v[136:139], v[208:211], v[8:11]
	v_mfma_f32_16x16x32_bf16 v[60:63], v[132:135], v[188:191], v[60:63]
	v_mfma_f32_16x16x32_bf16 v[56:59], v[140:143], v[188:191], v[56:59]
	v_mfma_f32_16x16x32_bf16 v[52:55], v[132:135], v[196:199], v[52:55]
	v_mfma_f32_16x16x32_bf16 v[40:43], v[140:143], v[196:199], v[40:43]
	v_mfma_f32_16x16x32_bf16 v[28:31], v[132:135], v[204:207], v[28:31]
	v_mfma_f32_16x16x32_bf16 v[24:27], v[140:143], v[204:207], v[24:27]
	v_mfma_f32_16x16x32_bf16 v[12:15], v[132:135], v[212:215], v[12:15]
	v_mfma_f32_16x16x32_bf16 v[8:11], v[140:143], v[212:215], v[8:11]
	s_setprio 0
	s_setprio 1
	v_mfma_f32_16x16x32_bf16 v[48:51], v[144:147], v[176:179], v[48:51]
	v_mfma_f32_16x16x32_bf16 v[44:47], v[168:171], v[176:179], v[44:47]
	v_mfma_f32_16x16x32_bf16 v[36:39], v[144:147], v[192:195], v[36:39]
	v_mfma_f32_16x16x32_bf16 v[32:35], v[168:171], v[192:195], v[32:35]
	v_mfma_f32_16x16x32_bf16 v[20:23], v[144:147], v[200:203], v[20:23]
	v_mfma_f32_16x16x32_bf16 v[16:19], v[168:171], v[200:203], v[16:19]
	v_mfma_f32_16x16x32_bf16 v[4:7], v[144:147], v[208:211], v[4:7]
	v_mfma_f32_16x16x32_bf16 v[0:3], v[168:171], v[208:211], v[0:3]
	v_mfma_f32_16x16x32_bf16 v[48:51], v[164:167], v[188:191], v[48:51]
	v_mfma_f32_16x16x32_bf16 v[44:47], v[172:175], v[188:191], v[44:47]
	v_mfma_f32_16x16x32_bf16 v[36:39], v[164:167], v[196:199], v[36:39]
	v_mfma_f32_16x16x32_bf16 v[32:35], v[172:175], v[196:199], v[32:35]
	v_mfma_f32_16x16x32_bf16 v[20:23], v[164:167], v[204:207], v[20:23]
	v_mfma_f32_16x16x32_bf16 v[16:19], v[172:175], v[204:207], v[16:19]
	v_mfma_f32_16x16x32_bf16 v[4:7], v[164:167], v[212:215], v[4:7]
	v_mfma_f32_16x16x32_bf16 v[0:3], v[172:175], v[212:215], v[0:3]
	s_setprio 0
	s_barrier
	s_add_i32 s75, s75, 2
	s_add_u32 s40, s40, 0x100
	s_addc_u32 s41, s41, 0
	s_add_u32 s73, s73, 0x100
	s_addc_u32 s74, s74, 0
	s_cmp_gt_u32 s75, 29
	s_cbranch_scc0 .LBB0_992
	s_and_b64 vcc, exec, s[14:15]
	s_cbranch_vccz .LBB0_995
	s_barrier

.LBB0_1069:
	ds_read_b128 v[128:131], v172
	ds_read_b128 v[132:135], v172 offset:1024
	ds_read_b128 v[156:159], v172 offset:2048
	ds_read_b128 v[160:163], v172 offset:3072
	ds_read_b128 v[164:167], v173
	ds_read_b128 v[176:179], v173 offset:1024
	ds_read_b128 v[180:183], v173 offset:2048
	ds_read_b128 v[184:187], v173 offset:3072
	s_add_u32 s18, s14, 0xfff80080
	s_addc_u32 s19, s15, -1
	s_cmp_eq_u32 s79, 28
	s_cselect_b32 s55, s5, s19
	s_cselect_b32 s54, s13, s18
	s_cselect_b32 s19, s33, s78
	s_cselect_b32 s18, s39, s41
	s_add_i32 m0, s63, 0xc000
	ds_read_b128 v[188:191], v174
	ds_read_b128 v[192:195], v174 offset:1024
	ds_read_b128 v[196:199], v174 offset:2048
	ds_read_b128 v[200:203], v174 offset:3072
	ds_read_b128 v[204:207], v174 offset:4096
	ds_read_b128 v[208:211], v174 offset:5120
	ds_read_b128 v[212:215], v174 offset:6144
	ds_read_b128 v[216:219], v174 offset:7168
	global_load_lds_dwordx4 v148, s[14:15]
	s_add_i32 m0, s63, 0xe000
	s_nop 0
	global_load_lds_dwordx4 v150, s[14:15]
	s_waitcnt vmcnt(8)
	s_waitcnt lgkmcnt(0)
	s_barrier
	s_setprio 1
	s_waitcnt lgkmcnt(0)
	v_mfma_f32_16x16x32_bf16 v[124:127], v[128:131], v[188:191], v[124:127]
	v_mfma_f32_16x16x32_bf16 v[120:123], v[156:159], v[188:191], v[120:123]
	v_mfma_f32_16x16x32_bf16 v[108:111], v[128:131], v[196:199], v[108:111]
	v_mfma_f32_16x16x32_bf16 v[104:107], v[156:159], v[196:199], v[104:107]
	v_mfma_f32_16x16x32_bf16 v[92:95], v[128:131], v[204:207], v[92:95]
	v_mfma_f32_16x16x32_bf16 v[88:91], v[156:159], v[204:207], v[88:91]
	v_mfma_f32_16x16x32_bf16 v[76:79], v[128:131], v[212:215], v[76:79]
	v_mfma_f32_16x16x32_bf16 v[72:75], v[156:159], v[212:215], v[72:75]
	v_mfma_f32_16x16x32_bf16 v[124:127], v[132:135], v[192:195], v[124:127]
	v_mfma_f32_16x16x32_bf16 v[120:123], v[160:163], v[192:195], v[120:123]
	v_mfma_f32_16x16x32_bf16 v[108:111], v[132:135], v[200:203], v[108:111]
	v_mfma_f32_16x16x32_bf16 v[104:107], v[160:163], v[200:203], v[104:107]
	v_mfma_f32_16x16x32_bf16 v[92:95], v[132:135], v[208:211], v[92:95]
	v_mfma_f32_16x16x32_bf16 v[88:91], v[160:163], v[208:211], v[88:91]
	v_mfma_f32_16x16x32_bf16 v[76:79], v[132:135], v[216:219], v[76:79]
	v_mfma_f32_16x16x32_bf16 v[72:75], v[160:163], v[216:219], v[72:75]
	s_setprio 0
	s_setprio 1
	v_mfma_f32_16x16x32_bf16 v[116:119], v[164:167], v[188:191], v[116:119]
	v_mfma_f32_16x16x32_bf16 v[112:115], v[180:183], v[188:191], v[112:115]
	v_mfma_f32_16x16x32_bf16 v[100:103], v[164:167], v[196:199], v[100:103]
	v_mfma_f32_16x16x32_bf16 v[96:99], v[180:183], v[196:199], v[96:99]
	v_mfma_f32_16x16x32_bf16 v[84:87], v[164:167], v[204:207], v[84:87]
	v_mfma_f32_16x16x32_bf16 v[80:83], v[180:183], v[204:207], v[80:83]
	v_mfma_f32_16x16x32_bf16 v[68:71], v[164:167], v[212:215], v[68:71]
	v_mfma_f32_16x16x32_bf16 v[64:67], v[180:183], v[212:215], v[64:67]
	v_mfma_f32_16x16x32_bf16 v[116:119], v[176:179], v[192:195], v[116:119]
	v_mfma_f32_16x16x32_bf16 v[112:115], v[184:187], v[192:195], v[112:115]
	v_mfma_f32_16x16x32_bf16 v[100:103], v[176:179], v[200:203], v[100:103]
	v_mfma_f32_16x16x32_bf16 v[96:99], v[184:187], v[200:203], v[96:99]
	v_mfma_f32_16x16x32_bf16 v[84:87], v[176:179], v[208:211], v[84:87]
	v_mfma_f32_16x16x32_bf16 v[80:83], v[184:187], v[208:211], v[80:83]
	v_mfma_f32_16x16x32_bf16 v[68:71], v[176:179], v[216:219], v[68:71]
	v_mfma_f32_16x16x32_bf16 v[64:67], v[184:187], v[216:219], v[64:67]
	s_setprio 0
	s_barrier
	s_add_i32 s80, s74, s62
	s_mov_b64 s[98:99], s[18:19]
	s_mov_b32 m0, s80
	ds_read_b128 v[188:191], v174 offset:16384
	ds_read_b128 v[192:195], v174 offset:17408
	ds_read_b128 v[196:199], v174 offset:18432
	ds_read_b128 v[200:203], v174 offset:19456
	ds_read_b128 v[204:207], v174 offset:20480
	ds_read_b128 v[208:211], v174 offset:21504
	ds_read_b128 v[212:215], v174 offset:22528
	ds_read_b128 v[216:219], v174 offset:23552
	global_load_lds_dwordx4 v138, s[18:19]
	s_add_i32 m0, s80, 0x2000
	s_add_u32 s80, s18, 0x80000
	s_addc_u32 s81, s19, 0
	s_add_i32 s82, s75, s62
	global_load_lds_dwordx4 v142, s[18:19]
	s_mov_b32 m0, s82
	s_mov_b64 s[100:101], s[54:55]
	global_load_lds_dwordx4 v138, s[80:81]
	s_add_i32 m0, s82, 0x2000
	s_nop 0
	global_load_lds_dwordx4 v142, s[80:81]
	s_mov_b32 m0, s63
	s_nop 0
	global_load_lds_dwordx4 v136, s[54:55]
	s_mov_b32 m0, s64
	s_nop 0
	global_load_lds_dwordx4 v140, s[54:55]
	s_waitcnt vmcnt(8)
	s_waitcnt lgkmcnt(0)
	s_barrier
	s_setprio 1
	s_waitcnt lgkmcnt(0)
	v_mfma_f32_16x16x32_bf16 v[60:63], v[128:131], v[188:191], v[60:63]
	v_mfma_f32_16x16x32_bf16 v[56:59], v[156:159], v[188:191], v[56:59]
	v_mfma_f32_16x16x32_bf16 v[44:47], v[128:131], v[196:199], v[44:47]
	v_mfma_f32_16x16x32_bf16 v[40:43], v[156:159], v[196:199], v[40:43]
	v_mfma_f32_16x16x32_bf16 v[28:31], v[128:131], v[204:207], v[28:31]
	v_mfma_f32_16x16x32_bf16 v[24:27], v[156:159], v[204:207], v[24:27]
	v_mfma_f32_16x16x32_bf16 v[12:15], v[128:131], v[212:215], v[12:15]
	v_mfma_f32_16x16x32_bf16 v[8:11], v[156:159], v[212:215], v[8:11]
	v_mfma_f32_16x16x32_bf16 v[60:63], v[132:135], v[192:195], v[60:63]
	v_mfma_f32_16x16x32_bf16 v[56:59], v[160:163], v[192:195], v[56:59]
	v_mfma_f32_16x16x32_bf16 v[44:47], v[132:135], v[200:203], v[44:47]
	v_mfma_f32_16x16x32_bf16 v[40:43], v[160:163], v[200:203], v[40:43]
	v_mfma_f32_16x16x32_bf16 v[28:31], v[132:135], v[208:211], v[28:31]
	v_mfma_f32_16x16x32_bf16 v[24:27], v[160:163], v[208:211], v[24:27]
	v_mfma_f32_16x16x32_bf16 v[12:15], v[132:135], v[216:219], v[12:15]
	v_mfma_f32_16x16x32_bf16 v[8:11], v[160:163], v[216:219], v[8:11]
	s_setprio 0
	s_setprio 1
	v_mfma_f32_16x16x32_bf16 v[52:55], v[164:167], v[188:191], v[52:55]
	v_mfma_f32_16x16x32_bf16 v[48:51], v[180:183], v[188:191], v[48:51]
	v_mfma_f32_16x16x32_bf16 v[36:39], v[164:167], v[196:199], v[36:39]
	v_mfma_f32_16x16x32_bf16 v[32:35], v[180:183], v[196:199], v[32:35]
	v_mfma_f32_16x16x32_bf16 v[20:23], v[164:167], v[204:207], v[20:23]
	v_mfma_f32_16x16x32_bf16 v[16:19], v[180:183], v[204:207], v[16:19]
	v_mfma_f32_16x16x32_bf16 v[4:7], v[164:167], v[212:215], v[4:7]
	v_mfma_f32_16x16x32_bf16 v[0:3], v[180:183], v[212:215], v[0:3]
	v_mfma_f32_16x16x32_bf16 v[52:55], v[176:179], v[192:195], v[52:55]
	v_mfma_f32_16x16x32_bf16 v[48:51], v[184:187], v[192:195], v[48:51]
	v_mfma_f32_16x16x32_bf16 v[36:39], v[176:179], v[200:203], v[36:39]
	v_mfma_f32_16x16x32_bf16 v[32:35], v[184:187], v[200:203], v[32:35]
	v_mfma_f32_16x16x32_bf16 v[20:23], v[176:179], v[208:211], v[20:23]
	v_mfma_f32_16x16x32_bf16 v[16:19], v[184:187], v[208:211], v[16:19]
	v_mfma_f32_16x16x32_bf16 v[4:7], v[176:179], v[216:219], v[4:7]
	v_mfma_f32_16x16x32_bf16 v[0:3], v[184:187], v[216:219], v[0:3]
	s_setprio 0
	s_barrier
	s_add_i32 s80, 0, 0x18000
	v_add_u32_e32 v144, s80, v170
	s_add_i32 s81, 0, 0x1c000
	ds_read_b128 v[128:131], v144
	ds_read_b128 v[132:135], v144 offset:1024
	ds_read_b128 v[156:159], v144 offset:2048
	ds_read_b128 v[160:163], v144 offset:3072
	v_add_u32_e32 v144, s81, v170
	ds_read_b128 v[164:167], v144
	ds_read_b128 v[176:179], v144 offset:1024
	ds_read_b128 v[180:183], v144 offset:2048
	ds_read_b128 v[184:187], v144 offset:3072
	s_add_u32 s54, s54, 0x80000
	s_addc_u32 s55, s55, 0
	s_mov_b32 m0, s65
	ds_read_b128 v[188:191], v174 offset:32768
	ds_read_b128 v[192:195], v174 offset:33792
	ds_read_b128 v[196:199], v174 offset:34816
	ds_read_b128 v[200:203], v174 offset:35840
	ds_read_b128 v[204:207], v174 offset:36864
	ds_read_b128 v[208:211], v174 offset:37888
	ds_read_b128 v[212:215], v174 offset:38912
	ds_read_b128 v[216:219], v174 offset:39936
	global_load_lds_dwordx4 v136, s[54:55]
	s_mov_b32 m0, s66
	s_nop 0
	global_load_lds_dwordx4 v140, s[54:55]
	s_waitcnt vmcnt(8)
	s_waitcnt lgkmcnt(0)
	s_barrier
	s_setprio 1
	s_waitcnt lgkmcnt(0)
	v_mfma_f32_16x16x32_bf16 v[124:127], v[128:131], v[188:191], v[124:127]
	v_mfma_f32_16x16x32_bf16 v[120:123], v[156:159], v[188:191], v[120:123]
	v_mfma_f32_16x16x32_bf16 v[108:111], v[128:131], v[196:199], v[108:111]
	v_mfma_f32_16x16x32_bf16 v[104:107], v[156:159], v[196:199], v[104:107]
	v_mfma_f32_16x16x32_bf16 v[92:95], v[128:131], v[204:207], v[92:95]
	v_mfma_f32_16x16x32_bf16 v[88:91], v[156:159], v[204:207], v[88:91]
	v_mfma_f32_16x16x32_bf16 v[76:79], v[128:131], v[212:215], v[76:79]
	v_mfma_f32_16x16x32_bf16 v[72:75], v[156:159], v[212:215], v[72:75]
	v_mfma_f32_16x16x32_bf16 v[124:127], v[132:135], v[192:195], v[124:127]
	v_mfma_f32_16x16x32_bf16 v[120:123], v[160:163], v[192:195], v[120:123]
	v_mfma_f32_16x16x32_bf16 v[108:111], v[132:135], v[200:203], v[108:111]
	v_mfma_f32_16x16x32_bf16 v[104:107], v[160:163], v[200:203], v[104:107]
	v_mfma_f32_16x16x32_bf16 v[92:95], v[132:135], v[208:211], v[92:95]
	v_mfma_f32_16x16x32_bf16 v[88:91], v[160:163], v[208:211], v[88:91]
	v_mfma_f32_16x16x32_bf16 v[76:79], v[132:135], v[216:219], v[76:79]
	v_mfma_f32_16x16x32_bf16 v[72:75], v[160:163], v[216:219], v[72:75]
	s_setprio 0
	s_setprio 1
	v_mfma_f32_16x16x32_bf16 v[116:119], v[164:167], v[188:191], v[116:119]
	v_mfma_f32_16x16x32_bf16 v[112:115], v[180:183], v[188:191], v[112:115]
	v_mfma_f32_16x16x32_bf16 v[100:103], v[164:167], v[196:199], v[100:103]
	v_mfma_f32_16x16x32_bf16 v[96:99], v[180:183], v[196:199], v[96:99]
	v_mfma_f32_16x16x32_bf16 v[84:87], v[164:167], v[204:207], v[84:87]
	v_mfma_f32_16x16x32_bf16 v[80:83], v[180:183], v[204:207], v[80:83]
	v_mfma_f32_16x16x32_bf16 v[68:71], v[164:167], v[212:215], v[68:71]
	v_mfma_f32_16x16x32_bf16 v[64:67], v[180:183], v[212:215], v[64:67]
	v_mfma_f32_16x16x32_bf16 v[116:119], v[176:179], v[192:195], v[116:119]
	v_mfma_f32_16x16x32_bf16 v[112:115], v[184:187], v[192:195], v[112:115]
	v_mfma_f32_16x16x32_bf16 v[100:103], v[176:179], v[200:203], v[100:103]
	v_mfma_f32_16x16x32_bf16 v[96:99], v[184:187], v[200:203], v[96:99]
	v_mfma_f32_16x16x32_bf16 v[84:87], v[176:179], v[208:211], v[84:87]
	v_mfma_f32_16x16x32_bf16 v[80:83], v[184:187], v[208:211], v[80:83]
	v_mfma_f32_16x16x32_bf16 v[68:71], v[176:179], v[216:219], v[68:71]
	v_mfma_f32_16x16x32_bf16 v[64:67], v[184:187], v[216:219], v[64:67]
	s_setprio 0
	s_barrier
	s_add_i32 s54, s80, s62
	s_add_i32 m0, s54, 0xffffff80
	ds_read_b128 v[188:191], v174 offset:49152
	ds_read_b128 v[192:195], v174 offset:50176
	ds_read_b128 v[196:199], v174 offset:51200
	ds_read_b128 v[200:203], v174 offset:52224
	ds_read_b128 v[204:207], v174 offset:53248
	ds_read_b128 v[208:211], v174 offset:54272
	ds_read_b128 v[212:215], v174 offset:55296
	ds_read_b128 v[216:219], v174 offset:56320
	global_load_lds_dwordx4 v138, s[98:99] offset:128
	s_add_i32 m0, s54, 0x1f80
	s_add_u32 s18, s18, 0x80080
	s_addc_u32 s19, s19, 0
	s_add_i32 s54, s81, s62
	global_load_lds_dwordx4 v142, s[98:99] offset:128
	s_mov_b32 m0, s54
	s_nop 0
	global_load_lds_dwordx4 v138, s[18:19]
	s_add_i32 m0, s54, 0x2000
	s_nop 0
	global_load_lds_dwordx4 v142, s[18:19]
	s_add_i32 m0, s69, 0xffffff80
	s_nop 0
	global_load_lds_dwordx4 v136, s[100:101] offset:128
	s_add_i32 m0, s70, 0xffffff80
	s_nop 0
	global_load_lds_dwordx4 v140, s[100:101] offset:128
	s_waitcnt vmcnt(8)
	s_waitcnt lgkmcnt(0)
	s_barrier
	s_setprio 1
	s_waitcnt lgkmcnt(0)
	v_mfma_f32_16x16x32_bf16 v[60:63], v[128:131], v[188:191], v[60:63]
	v_mfma_f32_16x16x32_bf16 v[56:59], v[156:159], v[188:191], v[56:59]
	v_mfma_f32_16x16x32_bf16 v[44:47], v[128:131], v[196:199], v[44:47]
	v_mfma_f32_16x16x32_bf16 v[40:43], v[156:159], v[196:199], v[40:43]
	v_mfma_f32_16x16x32_bf16 v[28:31], v[128:131], v[204:207], v[28:31]
	v_mfma_f32_16x16x32_bf16 v[24:27], v[156:159], v[204:207], v[24:27]
	v_mfma_f32_16x16x32_bf16 v[12:15], v[128:131], v[212:215], v[12:15]
	v_mfma_f32_16x16x32_bf16 v[8:11], v[156:159], v[212:215], v[8:11]
	v_mfma_f32_16x16x32_bf16 v[60:63], v[132:135], v[192:195], v[60:63]
	v_mfma_f32_16x16x32_bf16 v[56:59], v[160:163], v[192:195], v[56:59]
	v_mfma_f32_16x16x32_bf16 v[44:47], v[132:135], v[200:203], v[44:47]
	v_mfma_f32_16x16x32_bf16 v[40:43], v[160:163], v[200:203], v[40:43]
	v_mfma_f32_16x16x32_bf16 v[28:31], v[132:135], v[208:211], v[28:31]
	v_mfma_f32_16x16x32_bf16 v[24:27], v[160:163], v[208:211], v[24:27]
	v_mfma_f32_16x16x32_bf16 v[12:15], v[132:135], v[216:219], v[12:15]
	v_mfma_f32_16x16x32_bf16 v[8:11], v[160:163], v[216:219], v[8:11]
	s_setprio 0
	s_setprio 1
	v_mfma_f32_16x16x32_bf16 v[52:55], v[164:167], v[188:191], v[52:55]
	v_mfma_f32_16x16x32_bf16 v[48:51], v[180:183], v[188:191], v[48:51]
	v_mfma_f32_16x16x32_bf16 v[36:39], v[164:167], v[196:199], v[36:39]
	v_mfma_f32_16x16x32_bf16 v[32:35], v[180:183], v[196:199], v[32:35]
	v_mfma_f32_16x16x32_bf16 v[20:23], v[164:167], v[204:207], v[20:23]
	v_mfma_f32_16x16x32_bf16 v[16:19], v[180:183], v[204:207], v[16:19]
	v_mfma_f32_16x16x32_bf16 v[4:7], v[164:167], v[212:215], v[4:7]
	v_mfma_f32_16x16x32_bf16 v[0:3], v[180:183], v[212:215], v[0:3]
	v_mfma_f32_16x16x32_bf16 v[52:55], v[176:179], v[192:195], v[52:55]
	v_mfma_f32_16x16x32_bf16 v[48:51], v[184:187], v[192:195], v[48:51]
	v_mfma_f32_16x16x32_bf16 v[36:39], v[176:179], v[200:203], v[36:39]
	v_mfma_f32_16x16x32_bf16 v[32:35], v[184:187], v[200:203], v[32:35]
	v_mfma_f32_16x16x32_bf16 v[20:23], v[176:179], v[208:211], v[20:23]
	v_mfma_f32_16x16x32_bf16 v[16:19], v[184:187], v[208:211], v[16:19]
	v_mfma_f32_16x16x32_bf16 v[4:7], v[176:179], v[216:219], v[4:7]
	v_mfma_f32_16x16x32_bf16 v[0:3], v[184:187], v[216:219], v[0:3]
	s_setprio 0
	s_barrier
	s_add_i32 s79, s79, 2
	s_add_u32 s14, s14, 0x100
	s_addc_u32 s15, s15, 0
	s_add_u32 s41, s41, 0x100
	s_addc_u32 s78, s78, 0
	s_cmp_gt_u32 s79, 29
	s_cbranch_scc0 .LBB0_1069
	s_and_b64 vcc, exec, s[34:35]
	s_cbranch_vccz .LBB0_1072
	s_barrier

.LBB0_1394:
	ds_read_b128 v[64:67], v224
	ds_read_b128 v[68:71], v224 offset:1024
	ds_read_b128 v[72:75], v224 offset:2048
	ds_read_b128 v[76:79], v224 offset:3072
	ds_read_b128 v[136:139], v225
	ds_read_b128 v[140:143], v225 offset:1024
	ds_read_b128 v[144:147], v225 offset:2048
	ds_read_b128 v[152:155], v225 offset:3072
	s_add_u32 s18, s14, 0xfffc0080
	s_addc_u32 s19, s15, -1
	s_cmp_eq_u32 s71, 12
	s_cselect_b32 s41, s35, s19
	s_cselect_b32 s40, s67, s18
	s_cselect_b32 s19, s23, s70
	s_cselect_b32 s18, s68, s69
	s_add_i32 m0, s13, 0xc000
	ds_read_b128 v[160:163], v226
	ds_read_b128 v[164:167], v226 offset:1024
	ds_read_b128 v[168:171], v226 offset:2048
	ds_read_b128 v[172:175], v226 offset:3072
	ds_read_b128 v[176:179], v226 offset:4096
	ds_read_b128 v[180:183], v226 offset:5120
	ds_read_b128 v[184:187], v226 offset:6144
	ds_read_b128 v[188:191], v226 offset:7168
	global_load_lds_dwordx4 v200, s[14:15]
	s_add_i32 m0, s13, 0xe000
	s_nop 0
	global_load_lds_dwordx4 v202, s[14:15]
	s_waitcnt vmcnt(8)
	s_waitcnt lgkmcnt(0)
	s_barrier
	s_setprio 1
	s_waitcnt lgkmcnt(0)
	v_mfma_f32_16x16x32_bf16 v[156:159], v[64:67], v[160:163], v[156:159]
	v_mfma_f32_16x16x32_bf16 v[148:151], v[72:75], v[160:163], v[148:151]
	v_mfma_f32_16x16x32_bf16 v[124:127], v[64:67], v[168:171], v[124:127]
	v_mfma_f32_16x16x32_bf16 v[120:123], v[72:75], v[168:171], v[120:123]
	v_mfma_f32_16x16x32_bf16 v[108:111], v[64:67], v[176:179], v[108:111]
	v_mfma_f32_16x16x32_bf16 v[104:107], v[72:75], v[176:179], v[104:107]
	v_mfma_f32_16x16x32_bf16 v[92:95], v[64:67], v[184:187], v[92:95]
	v_mfma_f32_16x16x32_bf16 v[88:91], v[72:75], v[184:187], v[88:91]
	v_mfma_f32_16x16x32_bf16 v[156:159], v[68:71], v[164:167], v[156:159]
	v_mfma_f32_16x16x32_bf16 v[148:151], v[76:79], v[164:167], v[148:151]
	v_mfma_f32_16x16x32_bf16 v[124:127], v[68:71], v[172:175], v[124:127]
	v_mfma_f32_16x16x32_bf16 v[120:123], v[76:79], v[172:175], v[120:123]
	v_mfma_f32_16x16x32_bf16 v[108:111], v[68:71], v[180:183], v[108:111]
	v_mfma_f32_16x16x32_bf16 v[104:107], v[76:79], v[180:183], v[104:107]
	v_mfma_f32_16x16x32_bf16 v[92:95], v[68:71], v[188:191], v[92:95]
	v_mfma_f32_16x16x32_bf16 v[88:91], v[76:79], v[188:191], v[88:91]
	s_setprio 0
	s_setprio 1
	v_mfma_f32_16x16x32_bf16 v[132:135], v[136:139], v[160:163], v[132:135]
	v_mfma_f32_16x16x32_bf16 v[128:131], v[144:147], v[160:163], v[128:131]
	v_mfma_f32_16x16x32_bf16 v[116:119], v[136:139], v[168:171], v[116:119]
	v_mfma_f32_16x16x32_bf16 v[112:115], v[144:147], v[168:171], v[112:115]
	v_mfma_f32_16x16x32_bf16 v[100:103], v[136:139], v[176:179], v[100:103]
	v_mfma_f32_16x16x32_bf16 v[96:99], v[144:147], v[176:179], v[96:99]
	v_mfma_f32_16x16x32_bf16 v[84:87], v[136:139], v[184:187], v[84:87]
	v_mfma_f32_16x16x32_bf16 v[80:83], v[144:147], v[184:187], v[80:83]
	v_mfma_f32_16x16x32_bf16 v[132:135], v[140:143], v[164:167], v[132:135]
	v_mfma_f32_16x16x32_bf16 v[128:131], v[152:155], v[164:167], v[128:131]
	v_mfma_f32_16x16x32_bf16 v[116:119], v[140:143], v[172:175], v[116:119]
	v_mfma_f32_16x16x32_bf16 v[112:115], v[152:155], v[172:175], v[112:115]
	v_mfma_f32_16x16x32_bf16 v[100:103], v[140:143], v[180:183], v[100:103]
	v_mfma_f32_16x16x32_bf16 v[96:99], v[152:155], v[180:183], v[96:99]
	v_mfma_f32_16x16x32_bf16 v[84:87], v[140:143], v[188:191], v[84:87]
	v_mfma_f32_16x16x32_bf16 v[80:83], v[152:155], v[188:191], v[80:83]
	s_setprio 0
	s_barrier
	s_add_i32 s72, s64, s56
	s_mov_b64 s[98:99], s[18:19]
	s_mov_b32 m0, s72
	ds_read_b128 v[160:163], v226 offset:16384
	ds_read_b128 v[164:167], v226 offset:17408
	ds_read_b128 v[168:171], v226 offset:18432
	ds_read_b128 v[172:175], v226 offset:19456
	ds_read_b128 v[176:179], v226 offset:20480
	ds_read_b128 v[180:183], v226 offset:21504
	ds_read_b128 v[184:187], v226 offset:22528
	ds_read_b128 v[188:191], v226 offset:23552
	global_load_lds_dwordx4 v194, s[18:19]
	s_add_i32 m0, s72, 0x2000
	s_add_u32 s72, s18, 0x40000
	s_addc_u32 s73, s19, 0
	s_add_i32 s74, s65, s56
	global_load_lds_dwordx4 v198, s[18:19]
	s_mov_b32 m0, s74
	s_mov_b64 s[100:101], s[40:41]
	global_load_lds_dwordx4 v194, s[72:73]
	s_add_i32 m0, s74, 0x2000
	s_nop 0
	global_load_lds_dwordx4 v198, s[72:73]
	s_mov_b32 m0, s13
	s_nop 0
	global_load_lds_dwordx4 v192, s[40:41]
	s_mov_b32 m0, s57
	s_nop 0
	global_load_lds_dwordx4 v196, s[40:41]
	s_waitcnt vmcnt(8)
	s_waitcnt lgkmcnt(0)
	s_barrier
	s_setprio 1
	s_waitcnt lgkmcnt(0)
	v_mfma_f32_16x16x32_bf16 v[60:63], v[64:67], v[160:163], v[60:63]
	v_mfma_f32_16x16x32_bf16 v[56:59], v[72:75], v[160:163], v[56:59]
	v_mfma_f32_16x16x32_bf16 v[44:47], v[64:67], v[168:171], v[44:47]
	v_mfma_f32_16x16x32_bf16 v[40:43], v[72:75], v[168:171], v[40:43]
	v_mfma_f32_16x16x32_bf16 v[28:31], v[64:67], v[176:179], v[28:31]
	v_mfma_f32_16x16x32_bf16 v[24:27], v[72:75], v[176:179], v[24:27]
	v_mfma_f32_16x16x32_bf16 v[12:15], v[64:67], v[184:187], v[12:15]
	v_mfma_f32_16x16x32_bf16 v[8:11], v[72:75], v[184:187], v[8:11]
	v_mfma_f32_16x16x32_bf16 v[60:63], v[68:71], v[164:167], v[60:63]
	v_mfma_f32_16x16x32_bf16 v[56:59], v[76:79], v[164:167], v[56:59]
	v_mfma_f32_16x16x32_bf16 v[44:47], v[68:71], v[172:175], v[44:47]
	v_mfma_f32_16x16x32_bf16 v[40:43], v[76:79], v[172:175], v[40:43]
	v_mfma_f32_16x16x32_bf16 v[28:31], v[68:71], v[180:183], v[28:31]
	v_mfma_f32_16x16x32_bf16 v[24:27], v[76:79], v[180:183], v[24:27]
	v_mfma_f32_16x16x32_bf16 v[12:15], v[68:71], v[188:191], v[12:15]
	v_mfma_f32_16x16x32_bf16 v[8:11], v[76:79], v[188:191], v[8:11]
	s_setprio 0
	s_setprio 1
	v_mfma_f32_16x16x32_bf16 v[52:55], v[136:139], v[160:163], v[52:55]
	v_mfma_f32_16x16x32_bf16 v[48:51], v[144:147], v[160:163], v[48:51]
	v_mfma_f32_16x16x32_bf16 v[36:39], v[136:139], v[168:171], v[36:39]
	v_mfma_f32_16x16x32_bf16 v[32:35], v[144:147], v[168:171], v[32:35]
	v_mfma_f32_16x16x32_bf16 v[20:23], v[136:139], v[176:179], v[20:23]
	v_mfma_f32_16x16x32_bf16 v[16:19], v[144:147], v[176:179], v[16:19]
	v_mfma_f32_16x16x32_bf16 v[4:7], v[136:139], v[184:187], v[4:7]
	v_mfma_f32_16x16x32_bf16 v[0:3], v[144:147], v[184:187], v[0:3]
	v_mfma_f32_16x16x32_bf16 v[52:55], v[140:143], v[164:167], v[52:55]
	v_mfma_f32_16x16x32_bf16 v[48:51], v[152:155], v[164:167], v[48:51]
	v_mfma_f32_16x16x32_bf16 v[36:39], v[140:143], v[172:175], v[36:39]
	v_mfma_f32_16x16x32_bf16 v[32:35], v[152:155], v[172:175], v[32:35]
	v_mfma_f32_16x16x32_bf16 v[20:23], v[140:143], v[180:183], v[20:23]
	v_mfma_f32_16x16x32_bf16 v[16:19], v[152:155], v[180:183], v[16:19]
	v_mfma_f32_16x16x32_bf16 v[4:7], v[140:143], v[188:191], v[4:7]
	v_mfma_f32_16x16x32_bf16 v[0:3], v[152:155], v[188:191], v[0:3]
	s_setprio 0
	s_barrier
	s_add_i32 s72, 0, 0x18000
	s_add_i32 s73, 0, 0x1c000
	v_add_u32_e32 v76, s72, v222
	v_add_u32_e32 v152, s73, v222
	ds_read_b128 v[64:67], v76
	ds_read_b128 v[68:71], v76 offset:1024
	ds_read_b128 v[72:75], v76 offset:2048
	ds_read_b128 v[76:79], v76 offset:3072
	ds_read_b128 v[136:139], v152
	ds_read_b128 v[140:143], v152 offset:1024
	ds_read_b128 v[144:147], v152 offset:2048
	ds_read_b128 v[152:155], v152 offset:3072
	s_add_u32 s40, s40, 0x40000
	s_addc_u32 s41, s41, 0
	s_mov_b32 m0, s58
	ds_read_b128 v[160:163], v226 offset:32768
	ds_read_b128 v[164:167], v226 offset:33792
	ds_read_b128 v[168:171], v226 offset:34816
	ds_read_b128 v[172:175], v226 offset:35840
	ds_read_b128 v[176:179], v226 offset:36864
	ds_read_b128 v[180:183], v226 offset:37888
	ds_read_b128 v[184:187], v226 offset:38912
	ds_read_b128 v[188:191], v226 offset:39936
	global_load_lds_dwordx4 v192, s[40:41]
	s_mov_b32 m0, s59
	s_nop 0
	global_load_lds_dwordx4 v196, s[40:41]
	s_waitcnt vmcnt(8)
	s_waitcnt lgkmcnt(0)
	s_barrier
	s_setprio 1
	s_waitcnt lgkmcnt(0)
	v_mfma_f32_16x16x32_bf16 v[156:159], v[64:67], v[160:163], v[156:159]
	v_mfma_f32_16x16x32_bf16 v[148:151], v[72:75], v[160:163], v[148:151]
	v_mfma_f32_16x16x32_bf16 v[124:127], v[64:67], v[168:171], v[124:127]
	v_mfma_f32_16x16x32_bf16 v[120:123], v[72:75], v[168:171], v[120:123]
	v_mfma_f32_16x16x32_bf16 v[108:111], v[64:67], v[176:179], v[108:111]
	v_mfma_f32_16x16x32_bf16 v[104:107], v[72:75], v[176:179], v[104:107]
	v_mfma_f32_16x16x32_bf16 v[92:95], v[64:67], v[184:187], v[92:95]
	v_mfma_f32_16x16x32_bf16 v[88:91], v[72:75], v[184:187], v[88:91]
	v_mfma_f32_16x16x32_bf16 v[156:159], v[68:71], v[164:167], v[156:159]
	v_mfma_f32_16x16x32_bf16 v[148:151], v[76:79], v[164:167], v[148:151]
	v_mfma_f32_16x16x32_bf16 v[124:127], v[68:71], v[172:175], v[124:127]
	v_mfma_f32_16x16x32_bf16 v[120:123], v[76:79], v[172:175], v[120:123]
	v_mfma_f32_16x16x32_bf16 v[108:111], v[68:71], v[180:183], v[108:111]
	v_mfma_f32_16x16x32_bf16 v[104:107], v[76:79], v[180:183], v[104:107]
	v_mfma_f32_16x16x32_bf16 v[92:95], v[68:71], v[188:191], v[92:95]
	v_mfma_f32_16x16x32_bf16 v[88:91], v[76:79], v[188:191], v[88:91]
	s_setprio 0
	s_setprio 1
	v_mfma_f32_16x16x32_bf16 v[132:135], v[136:139], v[160:163], v[132:135]
	v_mfma_f32_16x16x32_bf16 v[128:131], v[144:147], v[160:163], v[128:131]
	v_mfma_f32_16x16x32_bf16 v[116:119], v[136:139], v[168:171], v[116:119]
	v_mfma_f32_16x16x32_bf16 v[112:115], v[144:147], v[168:171], v[112:115]
	v_mfma_f32_16x16x32_bf16 v[100:103], v[136:139], v[176:179], v[100:103]
	v_mfma_f32_16x16x32_bf16 v[96:99], v[144:147], v[176:179], v[96:99]
	v_mfma_f32_16x16x32_bf16 v[84:87], v[136:139], v[184:187], v[84:87]
	v_mfma_f32_16x16x32_bf16 v[80:83], v[144:147], v[184:187], v[80:83]
	v_mfma_f32_16x16x32_bf16 v[132:135], v[140:143], v[164:167], v[132:135]
	v_mfma_f32_16x16x32_bf16 v[128:131], v[152:155], v[164:167], v[128:131]
	v_mfma_f32_16x16x32_bf16 v[116:119], v[140:143], v[172:175], v[116:119]
	v_mfma_f32_16x16x32_bf16 v[112:115], v[152:155], v[172:175], v[112:115]
	v_mfma_f32_16x16x32_bf16 v[100:103], v[140:143], v[180:183], v[100:103]
	v_mfma_f32_16x16x32_bf16 v[96:99], v[152:155], v[180:183], v[96:99]
	v_mfma_f32_16x16x32_bf16 v[84:87], v[140:143], v[188:191], v[84:87]
	v_mfma_f32_16x16x32_bf16 v[80:83], v[152:155], v[188:191], v[80:83]
	s_setprio 0
	s_barrier
	s_add_i32 s40, s72, s56
	s_add_i32 m0, s40, 0xffffff80
	ds_read_b128 v[160:163], v226 offset:49152
	ds_read_b128 v[164:167], v226 offset:50176
	ds_read_b128 v[168:171], v226 offset:51200
	ds_read_b128 v[172:175], v226 offset:52224
	ds_read_b128 v[176:179], v226 offset:53248
	ds_read_b128 v[180:183], v226 offset:54272
	ds_read_b128 v[184:187], v226 offset:55296
	ds_read_b128 v[188:191], v226 offset:56320
	global_load_lds_dwordx4 v194, s[98:99] offset:128
	s_add_i32 m0, s40, 0x1f80
	s_add_u32 s18, s18, 0x40080
	s_addc_u32 s19, s19, 0
	s_add_i32 s40, s73, s56
	global_load_lds_dwordx4 v198, s[98:99] offset:128
	s_mov_b32 m0, s40
	s_nop 0
	global_load_lds_dwordx4 v194, s[18:19]
	s_add_i32 m0, s40, 0x2000
	s_nop 0
	global_load_lds_dwordx4 v198, s[18:19]
	s_add_i32 m0, s61, 0xffffff80
	s_nop 0
	global_load_lds_dwordx4 v192, s[100:101] offset:128
	s_add_i32 m0, s62, 0xffffff80
	s_nop 0
	global_load_lds_dwordx4 v196, s[100:101] offset:128
	s_waitcnt vmcnt(8)
	s_waitcnt lgkmcnt(0)
	s_barrier
	s_setprio 1
	s_waitcnt lgkmcnt(0)
	v_mfma_f32_16x16x32_bf16 v[60:63], v[64:67], v[160:163], v[60:63]
	v_mfma_f32_16x16x32_bf16 v[56:59], v[72:75], v[160:163], v[56:59]
	v_mfma_f32_16x16x32_bf16 v[44:47], v[64:67], v[168:171], v[44:47]
	v_mfma_f32_16x16x32_bf16 v[40:43], v[72:75], v[168:171], v[40:43]
	v_mfma_f32_16x16x32_bf16 v[28:31], v[64:67], v[176:179], v[28:31]
	v_mfma_f32_16x16x32_bf16 v[24:27], v[72:75], v[176:179], v[24:27]
	v_mfma_f32_16x16x32_bf16 v[12:15], v[64:67], v[184:187], v[12:15]
	v_mfma_f32_16x16x32_bf16 v[8:11], v[72:75], v[184:187], v[8:11]
	v_mfma_f32_16x16x32_bf16 v[60:63], v[68:71], v[164:167], v[60:63]
	v_mfma_f32_16x16x32_bf16 v[56:59], v[76:79], v[164:167], v[56:59]
	v_mfma_f32_16x16x32_bf16 v[44:47], v[68:71], v[172:175], v[44:47]
	v_mfma_f32_16x16x32_bf16 v[40:43], v[76:79], v[172:175], v[40:43]
	v_mfma_f32_16x16x32_bf16 v[28:31], v[68:71], v[180:183], v[28:31]
	v_mfma_f32_16x16x32_bf16 v[24:27], v[76:79], v[180:183], v[24:27]
	v_mfma_f32_16x16x32_bf16 v[12:15], v[68:71], v[188:191], v[12:15]
	v_mfma_f32_16x16x32_bf16 v[8:11], v[76:79], v[188:191], v[8:11]
	s_setprio 0
	s_setprio 1
	v_mfma_f32_16x16x32_bf16 v[52:55], v[136:139], v[160:163], v[52:55]
	v_mfma_f32_16x16x32_bf16 v[48:51], v[144:147], v[160:163], v[48:51]
	v_mfma_f32_16x16x32_bf16 v[36:39], v[136:139], v[168:171], v[36:39]
	v_mfma_f32_16x16x32_bf16 v[32:35], v[144:147], v[168:171], v[32:35]
	v_mfma_f32_16x16x32_bf16 v[20:23], v[136:139], v[176:179], v[20:23]
	v_mfma_f32_16x16x32_bf16 v[16:19], v[144:147], v[176:179], v[16:19]
	v_mfma_f32_16x16x32_bf16 v[4:7], v[136:139], v[184:187], v[4:7]
	v_mfma_f32_16x16x32_bf16 v[0:3], v[144:147], v[184:187], v[0:3]
	v_mfma_f32_16x16x32_bf16 v[52:55], v[140:143], v[164:167], v[52:55]
	v_mfma_f32_16x16x32_bf16 v[48:51], v[152:155], v[164:167], v[48:51]
	v_mfma_f32_16x16x32_bf16 v[36:39], v[140:143], v[172:175], v[36:39]
	v_mfma_f32_16x16x32_bf16 v[32:35], v[152:155], v[172:175], v[32:35]
	v_mfma_f32_16x16x32_bf16 v[20:23], v[140:143], v[180:183], v[20:23]
	v_mfma_f32_16x16x32_bf16 v[16:19], v[152:155], v[180:183], v[16:19]
	v_mfma_f32_16x16x32_bf16 v[4:7], v[140:143], v[188:191], v[4:7]
	v_mfma_f32_16x16x32_bf16 v[0:3], v[152:155], v[188:191], v[0:3]
	s_setprio 0
	s_barrier
	s_add_i32 s71, s71, 2
	s_add_u32 s14, s14, 0x100
	s_addc_u32 s15, s15, 0
	s_add_u32 s69, s69, 0x100
	s_addc_u32 s70, s70, 0
	s_cmp_gt_u32 s71, 13
	s_cbranch_scc0 .LBB0_1394
	v_lshl_or_b32 v64, s33, 8, v223
	v_ashrrev_i32_e32 v65, 31, v64
	v_lshl_add_u64 v[68:69], v[64:65], 2, s[8:9]
	global_load_dwordx4 v[72:75], v[68:69], off offset:16
	global_load_dwordx4 v[76:79], v[68:69], off
	v_lshl_add_u32 v210, s12, 8, v221
	v_ashrrev_i32_e32 v211, 31, v210
	v_mov_b64_e32 v[212:213], s[6:7]
	v_lshlrev_b64 v[208:209], 1, v[64:65]
	v_lshlrev_b64 v[64:65], 11, v[210:211]
	v_mad_i64_i32 v[66:67], s[14:15], v210, s66, v[212:213]
	v_lshl_add_u64 v[64:65], s[4:5], 0, v[64:65]
	v_lshl_add_u64 v[136:137], v[66:67], 0, v[208:209]
	v_lshl_add_u64 v[140:141], v[64:65], 0, v[208:209]
	global_load_dwordx4 v[228:231], v[136:137], off offset:2048
	global_load_dwordx4 v[232:235], v[140:141], off
	global_load_dwordx4 v[64:67], v[68:69], off offset:528
	s_nop 0
	global_load_dwordx4 v[68:71], v[68:69], off offset:512
	v_or_b32_e32 v218, 16, v210
	v_or_b32_e32 v216, 32, v210
	v_or_b32_e32 v214, 48, v210
	v_ashrrev_i32_e32 v219, 31, v218
	v_mad_i64_i32 v[138:139], s[14:15], v218, s66, v[212:213]
	v_mad_i64_i32 v[142:143], s[14:15], v216, s66, v[212:213]
	v_mad_i64_i32 v[144:145], s[14:15], v214, s66, v[212:213]
	v_lshlrev_b64 v[146:147], 11, v[218:219]
	v_lshl_add_u64 v[138:139], v[138:139], 0, v[208:209]
	v_lshl_add_u64 v[142:143], v[142:143], 0, v[208:209]
	v_lshl_add_u64 v[164:165], v[144:145], 0, v[208:209]
	global_load_dwordx4 v[236:239], v[136:137], off offset:2304
	v_lshl_add_u64 v[166:167], s[4:5], 0, v[146:147]
	global_load_dwordx4 v[184:187], v[138:139], off offset:2048
	global_load_dwordx4 v[176:179], v[138:139], off offset:2304
	global_load_dwordx4 v[168:171], v[142:143], off offset:2048
	global_load_dwordx4 v[160:163], v[142:143], off offset:2304
	global_load_dwordx4 v[144:147], v[164:165], off offset:2048
	s_nop 0
	global_load_dwordx4 v[136:139], v[164:165], off offset:2304
	global_load_dwordx4 v[240:243], v[140:141], off offset:256
	v_ashrrev_i32_e32 v217, 31, v216
	v_ashrrev_i32_e32 v215, 31, v214
	v_lshlrev_b64 v[152:153], 11, v[216:217]
	v_lshlrev_b64 v[154:155], 11, v[214:215]
	v_lshl_add_u64 v[152:153], s[4:5], 0, v[152:153]
	v_lshl_add_u64 v[142:143], s[4:5], 0, v[154:155]
	v_lshl_add_u64 v[140:141], v[166:167], 0, v[208:209]
	v_lshl_add_u64 v[152:153], v[152:153], 0, v[208:209]
	v_lshl_add_u64 v[142:143], v[142:143], 0, v[208:209]
	global_load_dwordx4 v[188:191], v[140:141], off
	global_load_dwordx4 v[180:183], v[140:141], off offset:256
	global_load_dwordx4 v[172:175], v[152:153], off
	global_load_dwordx4 v[164:167], v[152:153], off offset:256
	s_nop 0
	global_load_dwordx4 v[152:155], v[142:143], off
	s_nop 0
	global_load_dwordx4 v[140:143], v[142:143], off offset:256
	s_and_b64 vcc, exec, s[2:3]
	s_mov_b32 s33, s22
	s_mov_b32 s12, s34
	s_mov_b64 s[18:19], s[38:39]
	s_waitcnt vmcnt(0)
	v_pk_add_f32 v[148:149], v[148:149], v[72:73]
	v_pk_add_f32 v[156:157], v[156:157], v[76:77]
	v_mul_f32_e32 v148, 0xbfb8aa3b, v148
	v_mul_f32_e32 v156, 0xbfb8aa3b, v156
	v_exp_f32_e32 v156, v156
	v_exp_f32_e32 v148, v148
	v_mul_f32_e32 v149, 0xbfb8aa3b, v149
	v_pk_add_f32 v[150:151], v[150:151], v[74:75]
	v_add_f32_e32 v156, 1.0, v156
	v_exp_f32_e32 v149, v149
	v_pk_add_f32 v[158:159], v[158:159], v[78:79]
	v_rcp_f32_e32 v156, v156
	v_mul_f32_e32 v150, 0xbfb8aa3b, v150
	v_mul_f32_e32 v157, 0xbfb8aa3b, v157
	v_mul_f32_e32 v158, 0xbfb8aa3b, v158
	v_add_f32_e32 v148, 1.0, v148
	v_exp_f32_e32 v150, v150
	v_mul_f32_e32 v159, 0xbfb8aa3b, v159
	v_exp_f32_e32 v157, v157
	v_exp_f32_e32 v158, v158
	v_rcp_f32_e32 v148, v148
	v_mul_f32_e32 v151, 0xbfb8aa3b, v151
	v_lshlrev_b32_e32 v227, 16, v232
	v_exp_f32_e32 v159, v159
	v_add_f32_e32 v149, 1.0, v149
	v_exp_f32_e32 v151, v151
	v_lshlrev_b32_e32 v211, 16, v228
	v_mul_f32_e32 v156, v156, v227
	v_rcp_f32_e32 v149, v149
	v_mul_f32_e32 v156, v156, v211
	v_lshlrev_b32_e32 v211, 16, v234
	v_add_f32_e32 v150, 1.0, v150
	v_add_f32_e32 v157, 1.0, v157
	v_add_f32_e32 v158, 1.0, v158
	v_mul_f32_e32 v148, v148, v211
	v_lshlrev_b32_e32 v211, 16, v230
	v_rcp_f32_e32 v150, v150
	v_pk_add_f32 v[132:133], v[132:133], v[68:69]
	v_add_f32_e32 v159, 1.0, v159
	v_rcp_f32_e32 v157, v157
	v_rcp_f32_e32 v158, v158
	v_mul_f32_e32 v148, v148, v211
	v_and_b32_e32 v211, 0xffff0000, v234
	v_add_f32_e32 v151, 1.0, v151
	v_mul_f32_e32 v132, 0xbfb8aa3b, v132
	v_rcp_f32_e32 v159, v159
	v_mul_f32_e32 v149, v149, v211
	v_and_b32_e32 v211, 0xffff0000, v230
	v_rcp_f32_e32 v151, v151
	v_exp_f32_e32 v132, v132
	v_mul_f32_e32 v149, v149, v211
	v_lshlrev_b32_e32 v211, 16, v235
	v_mul_f32_e32 v133, 0xbfb8aa3b, v133
	v_and_b32_e32 v215, 0xffff0000, v228
	v_lshlrev_b32_e32 v217, 16, v229
	v_and_b32_e32 v219, 0xffff0000, v229
	v_and_b32_e32 v228, 0xffff0000, v232
	v_lshlrev_b32_e32 v229, 16, v233
	v_mul_f32_e32 v150, v150, v211
	v_lshlrev_b32_e32 v211, 16, v231
	v_pk_add_f32 v[134:135], v[134:135], v[70:71]
	v_exp_f32_e32 v133, v133
	v_and_b32_e32 v232, 0xffff0000, v233
	v_mul_f32_e32 v157, v157, v228
	v_mul_f32_e32 v158, v158, v229
	v_mul_f32_e32 v150, v150, v211
	v_and_b32_e32 v211, 0xffff0000, v235
	v_mul_f32_e32 v134, 0xbfb8aa3b, v134
	v_mul_f32_e32 v159, v159, v232
	v_mul_f32_e32 v157, v157, v215
	v_mul_f32_e32 v158, v158, v217
	v_mul_f32_e32 v151, v151, v211
	v_and_b32_e32 v211, 0xffff0000, v231
	v_add_f32_e32 v132, 1.0, v132
	v_exp_f32_e32 v134, v134
	v_mul_f32_e32 v159, v159, v219
	v_mul_f32_e32 v151, v151, v211
	v_cvt_pk_bf16_f32 v156, v156, v157
	v_cvt_pk_bf16_f32 v157, v158, v159
	v_cvt_pk_bf16_f32 v158, v148, v149
	v_mov_b64_e32 v[148:149], s[10:11]
	v_rcp_f32_e32 v132, v132
	v_mul_f32_e32 v135, 0xbfb8aa3b, v135
	v_cvt_pk_bf16_f32 v159, v150, v151
	v_mad_i64_i32 v[150:151], s[14:15], v210, s66, v[148:149]
	v_pk_add_f32 v[128:129], v[128:129], v[64:65]
	v_add_f32_e32 v133, 1.0, v133
	v_exp_f32_e32 v135, v135
	v_lshl_add_u64 v[150:151], v[150:151], 0, v[208:209]
	v_rcp_f32_e32 v133, v133
	v_mul_f32_e32 v128, 0xbfb8aa3b, v128
	global_store_dwordx4 v[150:151], v[156:159], off
	v_add_f32_e32 v134, 1.0, v134
	v_exp_f32_e32 v128, v128
	v_lshlrev_b32_e32 v156, 16, v240
	v_mul_f32_e32 v132, v132, v156
	v_lshlrev_b32_e32 v156, 16, v236
	v_rcp_f32_e32 v134, v134
	v_mul_f32_e32 v132, v132, v156
	v_and_b32_e32 v156, 0xffff0000, v240
	v_add_f32_e32 v135, 1.0, v135
	v_mul_f32_e32 v133, v133, v156
	v_and_b32_e32 v156, 0xffff0000, v236
	v_rcp_f32_e32 v135, v135
	v_mul_f32_e32 v133, v133, v156
	v_lshlrev_b32_e32 v156, 16, v241
	v_add_f32_e32 v128, 1.0, v128
	v_mul_f32_e32 v134, v134, v156
	v_lshlrev_b32_e32 v156, 16, v237
	v_rcp_f32_e32 v128, v128
	v_mul_f32_e32 v129, 0xbfb8aa3b, v129
	v_mul_f32_e32 v134, v134, v156
	v_and_b32_e32 v156, 0xffff0000, v241
	v_exp_f32_e32 v129, v129
	v_mul_f32_e32 v135, v135, v156
	v_and_b32_e32 v156, 0xffff0000, v237
	v_mul_f32_e32 v135, v135, v156
	v_lshlrev_b32_e32 v156, 16, v242
	v_pk_add_f32 v[130:131], v[130:131], v[66:67]
	v_mul_f32_e32 v128, v128, v156
	v_lshlrev_b32_e32 v156, 16, v238
	v_mul_f32_e32 v156, v128, v156
	v_add_f32_e32 v128, 1.0, v129
	v_mul_f32_e32 v129, 0xbfb8aa3b, v130
	v_exp_f32_e32 v129, v129
	v_rcp_f32_e32 v128, v128
	v_mul_f32_e32 v131, 0xbfb8aa3b, v131
	v_exp_f32_e32 v131, v131
	v_add_f32_e32 v129, 1.0, v129
	v_rcp_f32_e32 v129, v129
	v_and_b32_e32 v130, 0xffff0000, v242
	v_pk_add_f32 v[124:125], v[124:125], v[76:77]
	v_mul_f32_e32 v128, v128, v130
	v_and_b32_e32 v130, 0xffff0000, v238
	v_mul_f32_e32 v124, 0xbfb8aa3b, v124
	v_mul_f32_e32 v130, v128, v130
	v_lshlrev_b32_e32 v128, 16, v243
	v_exp_f32_e32 v124, v124
	v_mul_f32_e32 v128, v129, v128
	v_add_f32_e32 v129, 1.0, v131
	v_mul_f32_e32 v125, 0xbfb8aa3b, v125
	v_rcp_f32_e32 v129, v129
	v_pk_add_f32 v[126:127], v[126:127], v[78:79]
	v_exp_f32_e32 v125, v125
	v_mul_f32_e32 v126, 0xbfb8aa3b, v126
	v_lshlrev_b32_e32 v131, 16, v239
	v_add_f32_e32 v124, 1.0, v124
	v_exp_f32_e32 v126, v126
	v_mul_f32_e32 v131, v128, v131
	v_and_b32_e32 v128, 0xffff0000, v243
	v_rcp_f32_e32 v124, v124
	v_mul_f32_e32 v127, 0xbfb8aa3b, v127
	v_mul_f32_e32 v128, v129, v128
	v_and_b32_e32 v129, 0xffff0000, v239
	v_pk_add_f32 v[120:121], v[120:121], v[72:73]
	v_add_f32_e32 v125, 1.0, v125
	v_exp_f32_e32 v127, v127
	v_mul_f32_e32 v157, v128, v129
	v_cvt_pk_bf16_f32 v128, v132, v133
	v_rcp_f32_e32 v125, v125
	v_mul_f32_e32 v120, 0xbfb8aa3b, v120
	v_cvt_pk_bf16_f32 v129, v134, v135
	v_cvt_pk_bf16_f32 v130, v156, v130
	v_cvt_pk_bf16_f32 v131, v131, v157
	global_store_dwordx4 v[150:151], v[128:131], off offset:256
	v_add_f32_e32 v126, 1.0, v126
	v_exp_f32_e32 v120, v120
	v_lshlrev_b32_e32 v128, 16, v188
	v_mul_f32_e32 v124, v124, v128
	v_lshlrev_b32_e32 v128, 16, v184
	v_rcp_f32_e32 v126, v126
	v_mul_f32_e32 v124, v124, v128
	v_and_b32_e32 v128, 0xffff0000, v188
	v_add_f32_e32 v127, 1.0, v127
	v_mul_f32_e32 v125, v125, v128
	v_and_b32_e32 v128, 0xffff0000, v184
	v_rcp_f32_e32 v127, v127
	v_mul_f32_e32 v125, v125, v128
	v_lshlrev_b32_e32 v128, 16, v189
	v_add_f32_e32 v120, 1.0, v120
	v_mul_f32_e32 v126, v126, v128
	v_lshlrev_b32_e32 v128, 16, v185
	v_rcp_f32_e32 v120, v120
	v_mul_f32_e32 v121, 0xbfb8aa3b, v121
	v_mul_f32_e32 v126, v126, v128
	v_and_b32_e32 v128, 0xffff0000, v189
	v_exp_f32_e32 v121, v121
	v_mul_f32_e32 v127, v127, v128
	v_and_b32_e32 v128, 0xffff0000, v185
	v_mul_f32_e32 v127, v127, v128
	v_lshlrev_b32_e32 v128, 16, v190
	v_pk_add_f32 v[122:123], v[122:123], v[74:75]
	v_mul_f32_e32 v120, v120, v128
	v_lshlrev_b32_e32 v128, 16, v186
	v_mul_f32_e32 v128, v120, v128
	v_add_f32_e32 v120, 1.0, v121
	v_mul_f32_e32 v121, 0xbfb8aa3b, v122
	v_exp_f32_e32 v121, v121
	v_rcp_f32_e32 v120, v120
	v_mul_f32_e32 v123, 0xbfb8aa3b, v123
	v_exp_f32_e32 v123, v123
	v_add_f32_e32 v121, 1.0, v121
	v_rcp_f32_e32 v121, v121
	v_and_b32_e32 v122, 0xffff0000, v190
	v_mul_f32_e32 v120, v120, v122
	v_and_b32_e32 v122, 0xffff0000, v186
	v_pk_add_f32 v[116:117], v[116:117], v[68:69]
	v_mul_f32_e32 v122, v120, v122
	v_lshlrev_b32_e32 v120, 16, v191
	v_mul_f32_e32 v116, 0xbfb8aa3b, v116
	v_mul_f32_e32 v120, v121, v120
	v_add_f32_e32 v121, 1.0, v123
	v_exp_f32_e32 v116, v116
	v_rcp_f32_e32 v121, v121
	v_mul_f32_e32 v117, 0xbfb8aa3b, v117
	v_pk_add_f32 v[118:119], v[118:119], v[70:71]
	v_exp_f32_e32 v117, v117
	v_lshlrev_b32_e32 v123, 16, v187
	v_mul_f32_e32 v118, 0xbfb8aa3b, v118
	v_mul_f32_e32 v123, v120, v123
	v_and_b32_e32 v120, 0xffff0000, v191
	v_add_f32_e32 v116, 1.0, v116
	v_exp_f32_e32 v118, v118
	v_mul_f32_e32 v120, v121, v120
	v_and_b32_e32 v121, 0xffff0000, v187
	v_rcp_f32_e32 v116, v116
	v_mul_f32_e32 v119, 0xbfb8aa3b, v119
	v_mul_f32_e32 v129, v120, v121
	v_cvt_pk_bf16_f32 v120, v124, v125
	v_mad_i64_i32 v[124:125], s[14:15], v218, s66, v[148:149]
	v_pk_add_f32 v[112:113], v[112:113], v[64:65]
	v_add_f32_e32 v117, 1.0, v117
	v_exp_f32_e32 v119, v119
	v_lshl_add_u64 v[124:125], v[124:125], 0, v[208:209]
	v_rcp_f32_e32 v117, v117
	v_mul_f32_e32 v112, 0xbfb8aa3b, v112
	v_cvt_pk_bf16_f32 v121, v126, v127
	v_cvt_pk_bf16_f32 v122, v128, v122
	v_cvt_pk_bf16_f32 v123, v123, v129
	global_store_dwordx4 v[124:125], v[120:123], off
	v_add_f32_e32 v118, 1.0, v118
	v_exp_f32_e32 v112, v112
	v_lshlrev_b32_e32 v120, 16, v180
	v_mul_f32_e32 v116, v116, v120
	v_lshlrev_b32_e32 v120, 16, v176
	v_rcp_f32_e32 v118, v118
	v_mul_f32_e32 v116, v116, v120
	v_and_b32_e32 v120, 0xffff0000, v180
	v_add_f32_e32 v119, 1.0, v119
	v_mul_f32_e32 v117, v117, v120
	v_and_b32_e32 v120, 0xffff0000, v176
	v_rcp_f32_e32 v119, v119
	v_mul_f32_e32 v117, v117, v120
	v_lshlrev_b32_e32 v120, 16, v181
	v_add_f32_e32 v112, 1.0, v112
	v_mul_f32_e32 v118, v118, v120
	v_lshlrev_b32_e32 v120, 16, v177
	v_rcp_f32_e32 v112, v112
	v_mul_f32_e32 v113, 0xbfb8aa3b, v113
	v_mul_f32_e32 v118, v118, v120
	v_and_b32_e32 v120, 0xffff0000, v181
	v_exp_f32_e32 v113, v113
	v_mul_f32_e32 v119, v119, v120
	v_and_b32_e32 v120, 0xffff0000, v177
	v_mul_f32_e32 v119, v119, v120
	v_lshlrev_b32_e32 v120, 16, v182
	v_pk_add_f32 v[114:115], v[114:115], v[66:67]
	v_mul_f32_e32 v112, v112, v120
	v_lshlrev_b32_e32 v120, 16, v178
	v_mul_f32_e32 v120, v112, v120
	v_add_f32_e32 v112, 1.0, v113
	v_mul_f32_e32 v113, 0xbfb8aa3b, v114
	v_exp_f32_e32 v113, v113
	v_rcp_f32_e32 v112, v112
	v_mul_f32_e32 v115, 0xbfb8aa3b, v115
	v_exp_f32_e32 v115, v115
	v_add_f32_e32 v113, 1.0, v113
	v_rcp_f32_e32 v113, v113
	v_and_b32_e32 v114, 0xffff0000, v182
	v_pk_add_f32 v[108:109], v[108:109], v[76:77]
	v_mul_f32_e32 v112, v112, v114
	v_and_b32_e32 v114, 0xffff0000, v178
	v_mul_f32_e32 v108, 0xbfb8aa3b, v108
	v_mul_f32_e32 v114, v112, v114
	v_lshlrev_b32_e32 v112, 16, v183
	v_exp_f32_e32 v108, v108
	v_mul_f32_e32 v112, v113, v112
	v_add_f32_e32 v113, 1.0, v115
	v_mul_f32_e32 v109, 0xbfb8aa3b, v109
	v_rcp_f32_e32 v113, v113
	v_pk_add_f32 v[110:111], v[110:111], v[78:79]
	v_exp_f32_e32 v109, v109
	v_mul_f32_e32 v110, 0xbfb8aa3b, v110
	v_lshlrev_b32_e32 v115, 16, v179
	v_add_f32_e32 v108, 1.0, v108
	v_exp_f32_e32 v110, v110
	v_mul_f32_e32 v115, v112, v115
	v_and_b32_e32 v112, 0xffff0000, v183
	v_rcp_f32_e32 v108, v108
	v_mul_f32_e32 v111, 0xbfb8aa3b, v111
	v_mul_f32_e32 v112, v113, v112
	v_and_b32_e32 v113, 0xffff0000, v179
	v_pk_add_f32 v[104:105], v[104:105], v[72:73]
	v_add_f32_e32 v109, 1.0, v109
	v_exp_f32_e32 v111, v111
	v_mul_f32_e32 v121, v112, v113
	v_cvt_pk_bf16_f32 v112, v116, v117
	v_rcp_f32_e32 v109, v109
	v_mul_f32_e32 v104, 0xbfb8aa3b, v104
	v_cvt_pk_bf16_f32 v113, v118, v119
	v_cvt_pk_bf16_f32 v114, v120, v114
	v_cvt_pk_bf16_f32 v115, v115, v121
	global_store_dwordx4 v[124:125], v[112:115], off offset:256
	v_add_f32_e32 v110, 1.0, v110
	v_exp_f32_e32 v104, v104
	v_lshlrev_b32_e32 v112, 16, v172
	v_mul_f32_e32 v108, v108, v112
	v_lshlrev_b32_e32 v112, 16, v168
	v_rcp_f32_e32 v110, v110
	v_mul_f32_e32 v108, v108, v112
	v_and_b32_e32 v112, 0xffff0000, v172
	v_add_f32_e32 v111, 1.0, v111
	v_mul_f32_e32 v109, v109, v112
	v_and_b32_e32 v112, 0xffff0000, v168
	v_rcp_f32_e32 v111, v111
	v_mul_f32_e32 v109, v109, v112
	v_lshlrev_b32_e32 v112, 16, v173
	v_add_f32_e32 v104, 1.0, v104
	v_mul_f32_e32 v110, v110, v112
	v_lshlrev_b32_e32 v112, 16, v169
	v_rcp_f32_e32 v104, v104
	v_mul_f32_e32 v105, 0xbfb8aa3b, v105
	v_mul_f32_e32 v110, v110, v112
	v_and_b32_e32 v112, 0xffff0000, v173
	v_exp_f32_e32 v105, v105
	v_mul_f32_e32 v111, v111, v112
	v_and_b32_e32 v112, 0xffff0000, v169
	v_mul_f32_e32 v111, v111, v112
	v_lshlrev_b32_e32 v112, 16, v174
	v_pk_add_f32 v[106:107], v[106:107], v[74:75]
	v_mul_f32_e32 v104, v104, v112
	v_lshlrev_b32_e32 v112, 16, v170
	v_mul_f32_e32 v112, v104, v112
	v_add_f32_e32 v104, 1.0, v105
	v_mul_f32_e32 v105, 0xbfb8aa3b, v106
	v_exp_f32_e32 v105, v105
	v_rcp_f32_e32 v104, v104
	v_mul_f32_e32 v107, 0xbfb8aa3b, v107
	v_exp_f32_e32 v107, v107
	v_add_f32_e32 v105, 1.0, v105
	v_rcp_f32_e32 v105, v105
	v_and_b32_e32 v106, 0xffff0000, v174
	v_mul_f32_e32 v104, v104, v106
	v_and_b32_e32 v106, 0xffff0000, v170
	v_pk_add_f32 v[100:101], v[100:101], v[68:69]
	v_mul_f32_e32 v106, v104, v106
	v_lshlrev_b32_e32 v104, 16, v175
	v_mul_f32_e32 v100, 0xbfb8aa3b, v100
	v_mul_f32_e32 v104, v105, v104
	v_add_f32_e32 v105, 1.0, v107
	v_exp_f32_e32 v100, v100
	v_rcp_f32_e32 v105, v105
	v_mul_f32_e32 v101, 0xbfb8aa3b, v101
	v_pk_add_f32 v[102:103], v[102:103], v[70:71]
	v_exp_f32_e32 v101, v101
	v_lshlrev_b32_e32 v107, 16, v171
	v_mul_f32_e32 v102, 0xbfb8aa3b, v102
	v_mul_f32_e32 v107, v104, v107
	v_and_b32_e32 v104, 0xffff0000, v175
	v_add_f32_e32 v100, 1.0, v100
	v_exp_f32_e32 v102, v102
	v_mul_f32_e32 v104, v105, v104
	v_and_b32_e32 v105, 0xffff0000, v171
	v_rcp_f32_e32 v100, v100
	v_mul_f32_e32 v103, 0xbfb8aa3b, v103
	v_mul_f32_e32 v113, v104, v105
	v_cvt_pk_bf16_f32 v104, v108, v109
	v_mad_i64_i32 v[108:109], s[14:15], v216, s66, v[148:149]
	v_pk_add_f32 v[96:97], v[96:97], v[64:65]
	v_add_f32_e32 v101, 1.0, v101
	v_exp_f32_e32 v103, v103
	v_lshl_add_u64 v[108:109], v[108:109], 0, v[208:209]
	v_rcp_f32_e32 v101, v101
	v_mul_f32_e32 v96, 0xbfb8aa3b, v96
	v_cvt_pk_bf16_f32 v105, v110, v111
	v_cvt_pk_bf16_f32 v106, v112, v106
	v_cvt_pk_bf16_f32 v107, v107, v113
	global_store_dwordx4 v[108:109], v[104:107], off
	v_add_f32_e32 v102, 1.0, v102
	v_exp_f32_e32 v96, v96
	v_lshlrev_b32_e32 v104, 16, v164
	v_mul_f32_e32 v100, v100, v104
	v_lshlrev_b32_e32 v104, 16, v160
	v_rcp_f32_e32 v102, v102
	v_mul_f32_e32 v100, v100, v104
	v_and_b32_e32 v104, 0xffff0000, v164
	v_add_f32_e32 v103, 1.0, v103
	v_mul_f32_e32 v101, v101, v104
	v_and_b32_e32 v104, 0xffff0000, v160
	v_rcp_f32_e32 v103, v103
	v_mul_f32_e32 v101, v101, v104
	v_lshlrev_b32_e32 v104, 16, v165
	v_add_f32_e32 v96, 1.0, v96
	v_mul_f32_e32 v102, v102, v104
	v_lshlrev_b32_e32 v104, 16, v161
	v_rcp_f32_e32 v96, v96
	v_mul_f32_e32 v97, 0xbfb8aa3b, v97
	v_mul_f32_e32 v102, v102, v104
	v_and_b32_e32 v104, 0xffff0000, v165
	v_exp_f32_e32 v97, v97
	v_mul_f32_e32 v103, v103, v104
	v_and_b32_e32 v104, 0xffff0000, v161
	v_mul_f32_e32 v103, v103, v104
	v_lshlrev_b32_e32 v104, 16, v166
	v_pk_add_f32 v[98:99], v[98:99], v[66:67]
	v_mul_f32_e32 v96, v96, v104
	v_lshlrev_b32_e32 v104, 16, v162
	v_mul_f32_e32 v104, v96, v104
	v_add_f32_e32 v96, 1.0, v97
	v_mul_f32_e32 v97, 0xbfb8aa3b, v98
	v_exp_f32_e32 v97, v97
	v_rcp_f32_e32 v96, v96
	v_mul_f32_e32 v99, 0xbfb8aa3b, v99
	v_exp_f32_e32 v99, v99
	v_add_f32_e32 v97, 1.0, v97
	v_rcp_f32_e32 v97, v97
	v_and_b32_e32 v98, 0xffff0000, v166
	v_pk_add_f32 v[92:93], v[92:93], v[76:77]
	v_mul_f32_e32 v96, v96, v98
	v_and_b32_e32 v98, 0xffff0000, v162
	v_mul_f32_e32 v92, 0xbfb8aa3b, v92
	v_mul_f32_e32 v98, v96, v98
	v_lshlrev_b32_e32 v96, 16, v167
	v_exp_f32_e32 v92, v92
	v_mul_f32_e32 v96, v97, v96
	v_add_f32_e32 v97, 1.0, v99
	v_mul_f32_e32 v93, 0xbfb8aa3b, v93
	v_rcp_f32_e32 v97, v97
	v_pk_add_f32 v[94:95], v[94:95], v[78:79]
	v_exp_f32_e32 v93, v93
	v_mul_f32_e32 v94, 0xbfb8aa3b, v94
	v_lshlrev_b32_e32 v99, 16, v163
	v_add_f32_e32 v92, 1.0, v92
	v_exp_f32_e32 v94, v94
	v_mul_f32_e32 v99, v96, v99
	v_and_b32_e32 v96, 0xffff0000, v167
	v_rcp_f32_e32 v92, v92
	v_mul_f32_e32 v95, 0xbfb8aa3b, v95
	v_mul_f32_e32 v96, v97, v96
	v_and_b32_e32 v97, 0xffff0000, v163
	v_pk_add_f32 v[88:89], v[88:89], v[72:73]
	v_add_f32_e32 v93, 1.0, v93
	v_exp_f32_e32 v95, v95
	v_mul_f32_e32 v105, v96, v97
	v_cvt_pk_bf16_f32 v96, v100, v101
	v_rcp_f32_e32 v93, v93
	v_mul_f32_e32 v88, 0xbfb8aa3b, v88
	v_cvt_pk_bf16_f32 v97, v102, v103
	v_cvt_pk_bf16_f32 v98, v104, v98
	v_cvt_pk_bf16_f32 v99, v99, v105
	global_store_dwordx4 v[108:109], v[96:99], off offset:256
	v_add_f32_e32 v94, 1.0, v94
	v_exp_f32_e32 v88, v88
	v_lshlrev_b32_e32 v96, 16, v152
	v_mul_f32_e32 v92, v92, v96
	v_lshlrev_b32_e32 v96, 16, v144
	v_rcp_f32_e32 v94, v94
	v_mul_f32_e32 v92, v92, v96
	v_and_b32_e32 v96, 0xffff0000, v152
	v_add_f32_e32 v95, 1.0, v95
	v_mul_f32_e32 v93, v93, v96
	v_and_b32_e32 v96, 0xffff0000, v144
	v_rcp_f32_e32 v95, v95
	v_mul_f32_e32 v93, v93, v96
	v_lshlrev_b32_e32 v96, 16, v153
	v_add_f32_e32 v88, 1.0, v88
	v_mul_f32_e32 v94, v94, v96
	v_lshlrev_b32_e32 v96, 16, v145
	v_rcp_f32_e32 v88, v88
	v_mul_f32_e32 v89, 0xbfb8aa3b, v89
	v_mul_f32_e32 v94, v94, v96
	v_and_b32_e32 v96, 0xffff0000, v153
	v_exp_f32_e32 v89, v89
	v_mul_f32_e32 v95, v95, v96
	v_and_b32_e32 v96, 0xffff0000, v145
	v_mul_f32_e32 v95, v95, v96
	v_lshlrev_b32_e32 v96, 16, v154
	v_pk_add_f32 v[90:91], v[90:91], v[74:75]
	v_mul_f32_e32 v88, v88, v96
	v_lshlrev_b32_e32 v96, 16, v146
	v_mul_f32_e32 v96, v88, v96
	v_add_f32_e32 v88, 1.0, v89
	v_mul_f32_e32 v89, 0xbfb8aa3b, v90
	v_exp_f32_e32 v89, v89
	v_rcp_f32_e32 v88, v88
	v_mul_f32_e32 v91, 0xbfb8aa3b, v91
	v_exp_f32_e32 v91, v91
	v_add_f32_e32 v89, 1.0, v89
	v_rcp_f32_e32 v89, v89
	v_and_b32_e32 v90, 0xffff0000, v154
	v_mul_f32_e32 v88, v88, v90
	v_and_b32_e32 v90, 0xffff0000, v146
	v_pk_add_f32 v[84:85], v[84:85], v[68:69]
	v_mul_f32_e32 v90, v88, v90
	v_lshlrev_b32_e32 v88, 16, v155
	v_mul_f32_e32 v84, 0xbfb8aa3b, v84
	v_mul_f32_e32 v88, v89, v88
	v_add_f32_e32 v89, 1.0, v91
	v_exp_f32_e32 v84, v84
	v_rcp_f32_e32 v89, v89
	v_mul_f32_e32 v85, 0xbfb8aa3b, v85
	v_pk_add_f32 v[86:87], v[86:87], v[70:71]
	v_exp_f32_e32 v85, v85
	v_lshlrev_b32_e32 v91, 16, v147
	v_mul_f32_e32 v86, 0xbfb8aa3b, v86
	v_mul_f32_e32 v91, v88, v91
	v_and_b32_e32 v88, 0xffff0000, v155
	v_add_f32_e32 v84, 1.0, v84
	v_exp_f32_e32 v86, v86
	v_mul_f32_e32 v88, v89, v88
	v_and_b32_e32 v89, 0xffff0000, v147
	v_rcp_f32_e32 v84, v84
	v_mul_f32_e32 v87, 0xbfb8aa3b, v87
	v_mul_f32_e32 v97, v88, v89
	v_cvt_pk_bf16_f32 v88, v92, v93
	v_mad_i64_i32 v[92:93], s[14:15], v214, s66, v[148:149]
	v_pk_add_f32 v[80:81], v[80:81], v[64:65]
	v_add_f32_e32 v85, 1.0, v85
	v_exp_f32_e32 v87, v87
	v_lshl_add_u64 v[92:93], v[92:93], 0, v[208:209]
	v_rcp_f32_e32 v85, v85
	v_mul_f32_e32 v80, 0xbfb8aa3b, v80
	v_cvt_pk_bf16_f32 v89, v94, v95
	v_cvt_pk_bf16_f32 v90, v96, v90
	v_cvt_pk_bf16_f32 v91, v91, v97
	global_store_dwordx4 v[92:93], v[88:91], off
	v_add_f32_e32 v86, 1.0, v86
	v_exp_f32_e32 v80, v80
	v_lshlrev_b32_e32 v88, 16, v140
	v_mul_f32_e32 v84, v84, v88
	v_lshlrev_b32_e32 v88, 16, v136
	v_rcp_f32_e32 v86, v86
	v_mul_f32_e32 v84, v84, v88
	v_and_b32_e32 v88, 0xffff0000, v140
	v_add_f32_e32 v87, 1.0, v87
	v_mul_f32_e32 v85, v85, v88
	v_and_b32_e32 v88, 0xffff0000, v136
	v_rcp_f32_e32 v87, v87
	v_mul_f32_e32 v85, v85, v88
	v_lshlrev_b32_e32 v88, 16, v141
	v_add_f32_e32 v80, 1.0, v80
	v_mul_f32_e32 v86, v86, v88
	v_lshlrev_b32_e32 v88, 16, v137
	v_rcp_f32_e32 v80, v80
	v_mul_f32_e32 v81, 0xbfb8aa3b, v81
	v_mul_f32_e32 v86, v86, v88
	v_and_b32_e32 v88, 0xffff0000, v141
	v_exp_f32_e32 v81, v81
	v_mul_f32_e32 v87, v87, v88
	v_and_b32_e32 v88, 0xffff0000, v137
	v_mul_f32_e32 v87, v87, v88
	v_lshlrev_b32_e32 v88, 16, v142
	v_pk_add_f32 v[82:83], v[82:83], v[66:67]
	v_mul_f32_e32 v80, v80, v88
	v_lshlrev_b32_e32 v88, 16, v138
	v_mul_f32_e32 v88, v80, v88
	v_add_f32_e32 v80, 1.0, v81
	v_mul_f32_e32 v81, 0xbfb8aa3b, v82
	v_exp_f32_e32 v81, v81
	v_rcp_f32_e32 v80, v80
	v_mul_f32_e32 v83, 0xbfb8aa3b, v83
	v_exp_f32_e32 v83, v83
	v_add_f32_e32 v81, 1.0, v81
	v_rcp_f32_e32 v81, v81
	v_and_b32_e32 v82, 0xffff0000, v142
	v_mul_f32_e32 v80, v80, v82
	v_and_b32_e32 v82, 0xffff0000, v138
	v_mul_f32_e32 v82, v80, v82
	v_lshlrev_b32_e32 v80, 16, v143
	v_mul_f32_e32 v80, v81, v80
	v_add_f32_e32 v81, 1.0, v83
	v_rcp_f32_e32 v81, v81
	v_lshlrev_b32_e32 v83, 16, v139
	v_mul_f32_e32 v83, v80, v83
	v_and_b32_e32 v80, 0xffff0000, v143
	v_add_u32_e32 v146, 0x80, v210
	v_mul_f32_e32 v80, v81, v80
	v_and_b32_e32 v81, 0xffff0000, v139
	v_ashrrev_i32_e32 v147, 31, v146
	v_mul_f32_e32 v89, v80, v81
	v_cvt_pk_bf16_f32 v80, v84, v85
	v_lshlrev_b64 v[84:85], 11, v[146:147]
	v_lshl_add_u64 v[84:85], s[4:5], 0, v[84:85]
	v_cvt_pk_bf16_f32 v81, v86, v87
	v_lshl_add_u64 v[84:85], v[84:85], 0, v[208:209]
	v_mad_i64_i32 v[86:87], s[14:15], v146, s66, v[212:213]
	v_cvt_pk_bf16_f32 v82, v88, v82
	v_cvt_pk_bf16_f32 v83, v83, v89
	global_load_dwordx4 v[142:145], v[84:85], off
	v_lshl_add_u64 v[86:87], v[86:87], 0, v[208:209]
	global_load_dwordx4 v[150:153], v[86:87], off offset:2048
	v_add_u32_e32 v140, 0x90, v210
	global_store_dwordx4 v[92:93], v[80:83], off offset:256
	global_load_dwordx4 v[132:135], v[84:85], off offset:256
	global_load_dwordx4 v[128:131], v[86:87], off offset:2304
	v_ashrrev_i32_e32 v141, 31, v140
	v_lshlrev_b64 v[80:81], 11, v[140:141]
	v_lshl_add_u64 v[80:81], s[4:5], 0, v[80:81]
	v_mad_i64_i32 v[82:83], s[14:15], v140, s66, v[212:213]
	v_lshl_add_u64 v[80:81], v[80:81], 0, v[208:209]
	v_lshl_add_u64 v[82:83], v[82:83], 0, v[208:209]
	global_load_dwordx4 v[120:123], v[80:81], off
	global_load_dwordx4 v[112:115], v[80:81], off offset:256
	global_load_dwordx4 v[124:127], v[82:83], off offset:2048
	global_load_dwordx4 v[116:119], v[82:83], off offset:2304
	v_pk_add_f32 v[60:61], v[60:61], v[76:77]
	v_pk_add_f32 v[62:63], v[62:63], v[78:79]
	v_mul_f32_e32 v60, 0xbfb8aa3b, v60
	v_exp_f32_e32 v60, v60
	v_mul_f32_e32 v61, 0xbfb8aa3b, v61
	v_exp_f32_e32 v61, v61
	v_add_u32_e32 v138, 0xa0, v210
	v_mul_f32_e32 v62, 0xbfb8aa3b, v62
	v_ashrrev_i32_e32 v139, 31, v138
	v_add_f32_e32 v60, 1.0, v60
	v_exp_f32_e32 v62, v62
	v_lshlrev_b64 v[80:81], 11, v[138:139]
	v_rcp_f32_e32 v60, v60
	v_mul_f32_e32 v63, 0xbfb8aa3b, v63
	v_lshl_add_u64 v[80:81], s[4:5], 0, v[80:81]
	v_add_u32_e32 v136, 0xb0, v210
	v_pk_add_f32 v[56:57], v[56:57], v[72:73]
	v_add_f32_e32 v61, 1.0, v61
	v_exp_f32_e32 v63, v63
	v_mad_i64_i32 v[82:83], s[14:15], v138, s66, v[212:213]
	v_lshl_add_u64 v[80:81], v[80:81], 0, v[208:209]
	v_ashrrev_i32_e32 v137, 31, v136
	v_rcp_f32_e32 v61, v61
	v_mul_f32_e32 v56, 0xbfb8aa3b, v56
	v_lshl_add_u64 v[82:83], v[82:83], 0, v[208:209]
	global_load_dwordx4 v[104:107], v[80:81], off
	global_load_dwordx4 v[96:99], v[80:81], off offset:256
	global_load_dwordx4 v[108:111], v[82:83], off offset:2048
	global_load_dwordx4 v[100:103], v[82:83], off offset:2304
	v_lshlrev_b64 v[80:81], 11, v[136:137]
	v_add_f32_e32 v62, 1.0, v62
	v_exp_f32_e32 v56, v56
	v_rcp_f32_e32 v62, v62
	v_add_f32_e32 v63, 1.0, v63
	v_rcp_f32_e32 v63, v63
	v_add_f32_e32 v56, 1.0, v56
	v_rcp_f32_e32 v56, v56
	v_mul_f32_e32 v57, 0xbfb8aa3b, v57
	v_exp_f32_e32 v57, v57
	v_pk_add_f32 v[58:59], v[58:59], v[74:75]
	v_pk_add_f32 v[52:53], v[52:53], v[68:69]
	v_mul_f32_e32 v59, 0xbfb8aa3b, v59
	v_exp_f32_e32 v59, v59
	v_mul_f32_e32 v52, 0xbfb8aa3b, v52
	v_exp_f32_e32 v52, v52
	v_mul_f32_e32 v53, 0xbfb8aa3b, v53
	v_pk_add_f32 v[54:55], v[54:55], v[70:71]
	v_exp_f32_e32 v53, v53
	v_mul_f32_e32 v54, 0xbfb8aa3b, v54
	v_lshl_add_u64 v[80:81], s[4:5], 0, v[80:81]
	v_mad_i64_i32 v[82:83], s[14:15], v136, s66, v[212:213]
	v_add_f32_e32 v52, 1.0, v52
	v_exp_f32_e32 v54, v54
	v_lshl_add_u64 v[80:81], v[80:81], 0, v[208:209]
	v_lshl_add_u64 v[84:85], v[82:83], 0, v[208:209]
	v_rcp_f32_e32 v52, v52
	v_mul_f32_e32 v55, 0xbfb8aa3b, v55
	global_load_dwordx4 v[88:91], v[80:81], off
	s_nop 0
	global_load_dwordx4 v[80:83], v[80:81], off offset:256
	s_nop 0
	global_load_dwordx4 v[92:95], v[84:85], off offset:2048
	s_nop 0
	global_load_dwordx4 v[84:87], v[84:85], off offset:2304
	v_pk_add_f32 v[48:49], v[48:49], v[64:65]
	v_add_f32_e32 v53, 1.0, v53
	v_exp_f32_e32 v55, v55
	v_rcp_f32_e32 v53, v53
	v_mul_f32_e32 v48, 0xbfb8aa3b, v48
	v_add_f32_e32 v54, 1.0, v54
	v_exp_f32_e32 v48, v48
	v_rcp_f32_e32 v54, v54
	v_add_f32_e32 v55, 1.0, v55
	s_waitcnt vmcnt(16)
	v_lshlrev_b32_e32 v137, 16, v142
	v_mul_f32_e32 v60, v60, v137
	s_waitcnt vmcnt(15)
	v_lshlrev_b32_e32 v137, 16, v150
	v_mul_f32_e32 v60, v60, v137
	v_and_b32_e32 v137, 0xffff0000, v142
	v_mul_f32_e32 v61, v61, v137
	v_and_b32_e32 v137, 0xffff0000, v150
	v_mul_f32_e32 v61, v61, v137
	v_lshlrev_b32_e32 v137, 16, v143
	v_mul_f32_e32 v62, v62, v137
	v_lshlrev_b32_e32 v137, 16, v151
	v_mul_f32_e32 v62, v62, v137
	v_and_b32_e32 v137, 0xffff0000, v143
	v_mul_f32_e32 v63, v63, v137
	v_and_b32_e32 v137, 0xffff0000, v151
	v_mul_f32_e32 v63, v63, v137
	v_lshlrev_b32_e32 v137, 16, v144
	v_mul_f32_e32 v56, v56, v137
	v_lshlrev_b32_e32 v137, 16, v152
	v_mul_f32_e32 v137, v56, v137
	v_add_f32_e32 v56, 1.0, v57
	v_mul_f32_e32 v57, 0xbfb8aa3b, v58
	v_exp_f32_e32 v57, v57
	v_rcp_f32_e32 v56, v56
	v_and_b32_e32 v58, 0xffff0000, v144
	v_rcp_f32_e32 v55, v55
	v_add_f32_e32 v57, 1.0, v57
	v_rcp_f32_e32 v57, v57
	v_mul_f32_e32 v56, v56, v58
	v_and_b32_e32 v58, 0xffff0000, v152
	v_mul_f32_e32 v58, v56, v58
	v_lshlrev_b32_e32 v56, 16, v145
	v_mul_f32_e32 v56, v57, v56
	v_add_f32_e32 v57, 1.0, v59
	v_rcp_f32_e32 v57, v57
	v_lshlrev_b32_e32 v59, 16, v153
	v_mul_f32_e32 v59, v56, v59
	v_and_b32_e32 v56, 0xffff0000, v145
	v_mul_f32_e32 v56, v57, v56
	v_and_b32_e32 v57, 0xffff0000, v153
	v_mul_f32_e32 v139, v56, v57
	v_cvt_pk_bf16_f32 v56, v60, v61
	v_mad_i64_i32 v[60:61], s[14:15], v146, s66, v[148:149]
	v_lshl_add_u64 v[60:61], v[60:61], 0, v[208:209]
	v_cvt_pk_bf16_f32 v57, v62, v63
	v_cvt_pk_bf16_f32 v58, v137, v58
	v_cvt_pk_bf16_f32 v59, v59, v139
	global_store_dwordx4 v[60:61], v[56:59], off
	v_add_f32_e32 v48, 1.0, v48
	v_rcp_f32_e32 v48, v48
	s_waitcnt vmcnt(14)
	v_lshlrev_b32_e32 v56, 16, v132
	v_mul_f32_e32 v52, v52, v56
	s_waitcnt vmcnt(13)
	v_lshlrev_b32_e32 v56, 16, v128
	v_mul_f32_e32 v52, v52, v56
	v_and_b32_e32 v56, 0xffff0000, v132
	v_mul_f32_e32 v53, v53, v56
	v_and_b32_e32 v56, 0xffff0000, v128
	v_mul_f32_e32 v53, v53, v56
	v_lshlrev_b32_e32 v56, 16, v133
	v_mul_f32_e32 v54, v54, v56
	v_lshlrev_b32_e32 v56, 16, v129
	v_mul_f32_e32 v49, 0xbfb8aa3b, v49
	v_mul_f32_e32 v54, v54, v56
	v_and_b32_e32 v56, 0xffff0000, v133
	v_exp_f32_e32 v49, v49
	v_mul_f32_e32 v55, v55, v56
	v_and_b32_e32 v56, 0xffff0000, v129
	v_mul_f32_e32 v55, v55, v56
	v_lshlrev_b32_e32 v56, 16, v134
	v_pk_add_f32 v[50:51], v[50:51], v[66:67]
	v_mul_f32_e32 v48, v48, v56
	v_lshlrev_b32_e32 v56, 16, v130
	v_mul_f32_e32 v56, v48, v56
	v_add_f32_e32 v48, 1.0, v49
	v_mul_f32_e32 v49, 0xbfb8aa3b, v50
	v_exp_f32_e32 v49, v49
	v_rcp_f32_e32 v48, v48
	v_mul_f32_e32 v51, 0xbfb8aa3b, v51
	v_exp_f32_e32 v51, v51
	v_add_f32_e32 v49, 1.0, v49
	v_rcp_f32_e32 v49, v49
	v_and_b32_e32 v50, 0xffff0000, v134
	v_pk_add_f32 v[44:45], v[44:45], v[76:77]
	v_mul_f32_e32 v48, v48, v50
	v_and_b32_e32 v50, 0xffff0000, v130
	v_mul_f32_e32 v44, 0xbfb8aa3b, v44
	v_mul_f32_e32 v50, v48, v50
	v_lshlrev_b32_e32 v48, 16, v135
	v_exp_f32_e32 v44, v44
	v_mul_f32_e32 v48, v49, v48
	v_add_f32_e32 v49, 1.0, v51
	v_mul_f32_e32 v45, 0xbfb8aa3b, v45
	v_rcp_f32_e32 v49, v49
	v_pk_add_f32 v[46:47], v[46:47], v[78:79]
	v_exp_f32_e32 v45, v45
	v_mul_f32_e32 v46, 0xbfb8aa3b, v46
	v_lshlrev_b32_e32 v51, 16, v131
	v_add_f32_e32 v44, 1.0, v44
	v_exp_f32_e32 v46, v46
	v_mul_f32_e32 v51, v48, v51
	v_and_b32_e32 v48, 0xffff0000, v135
	v_rcp_f32_e32 v44, v44
	v_mul_f32_e32 v47, 0xbfb8aa3b, v47
	v_mul_f32_e32 v48, v49, v48
	v_and_b32_e32 v49, 0xffff0000, v131
	v_pk_add_f32 v[40:41], v[40:41], v[72:73]
	v_add_f32_e32 v45, 1.0, v45
	v_exp_f32_e32 v47, v47
	v_mul_f32_e32 v57, v48, v49
	v_cvt_pk_bf16_f32 v48, v52, v53
	v_rcp_f32_e32 v45, v45
	v_mul_f32_e32 v40, 0xbfb8aa3b, v40
	v_cvt_pk_bf16_f32 v49, v54, v55
	v_cvt_pk_bf16_f32 v50, v56, v50
	v_cvt_pk_bf16_f32 v51, v51, v57
	global_store_dwordx4 v[60:61], v[48:51], off offset:256
	v_add_f32_e32 v46, 1.0, v46
	v_exp_f32_e32 v40, v40
	s_waitcnt vmcnt(13)
	v_lshlrev_b32_e32 v48, 16, v120
	v_mul_f32_e32 v44, v44, v48
	s_waitcnt vmcnt(11)
	v_lshlrev_b32_e32 v48, 16, v124
	v_rcp_f32_e32 v46, v46
	v_mul_f32_e32 v44, v44, v48
	v_and_b32_e32 v48, 0xffff0000, v120
	v_add_f32_e32 v47, 1.0, v47
	v_mul_f32_e32 v45, v45, v48
	v_and_b32_e32 v48, 0xffff0000, v124
	v_rcp_f32_e32 v47, v47
	v_mul_f32_e32 v45, v45, v48
	v_lshlrev_b32_e32 v48, 16, v121
	v_add_f32_e32 v40, 1.0, v40
	v_mul_f32_e32 v46, v46, v48
	v_lshlrev_b32_e32 v48, 16, v125
	v_rcp_f32_e32 v40, v40
	v_mul_f32_e32 v41, 0xbfb8aa3b, v41
	v_mul_f32_e32 v46, v46, v48
	v_and_b32_e32 v48, 0xffff0000, v121
	v_exp_f32_e32 v41, v41
	v_mul_f32_e32 v47, v47, v48
	v_and_b32_e32 v48, 0xffff0000, v125
	v_mul_f32_e32 v47, v47, v48
	v_lshlrev_b32_e32 v48, 16, v122
	v_pk_add_f32 v[42:43], v[42:43], v[74:75]
	v_mul_f32_e32 v40, v40, v48
	v_lshlrev_b32_e32 v48, 16, v126
	v_mul_f32_e32 v48, v40, v48
	v_add_f32_e32 v40, 1.0, v41
	v_mul_f32_e32 v41, 0xbfb8aa3b, v42
	v_exp_f32_e32 v41, v41
	v_rcp_f32_e32 v40, v40
	v_mul_f32_e32 v43, 0xbfb8aa3b, v43
	v_exp_f32_e32 v43, v43
	v_add_f32_e32 v41, 1.0, v41
	v_rcp_f32_e32 v41, v41
	v_and_b32_e32 v42, 0xffff0000, v122
	v_mul_f32_e32 v40, v40, v42
	v_and_b32_e32 v42, 0xffff0000, v126
	v_pk_add_f32 v[36:37], v[36:37], v[68:69]
	v_mul_f32_e32 v42, v40, v42
	v_lshlrev_b32_e32 v40, 16, v123
	v_mul_f32_e32 v36, 0xbfb8aa3b, v36
	v_mul_f32_e32 v40, v41, v40
	v_add_f32_e32 v41, 1.0, v43
	v_exp_f32_e32 v36, v36
	v_rcp_f32_e32 v41, v41
	v_mul_f32_e32 v37, 0xbfb8aa3b, v37
	v_pk_add_f32 v[38:39], v[38:39], v[70:71]
	v_exp_f32_e32 v37, v37
	v_lshlrev_b32_e32 v43, 16, v127
	v_mul_f32_e32 v38, 0xbfb8aa3b, v38
	v_mul_f32_e32 v43, v40, v43
	v_and_b32_e32 v40, 0xffff0000, v123
	v_add_f32_e32 v36, 1.0, v36
	v_exp_f32_e32 v38, v38
	v_mul_f32_e32 v40, v41, v40
	v_and_b32_e32 v41, 0xffff0000, v127
	v_rcp_f32_e32 v36, v36
	v_mul_f32_e32 v39, 0xbfb8aa3b, v39
	v_mul_f32_e32 v49, v40, v41
	v_cvt_pk_bf16_f32 v40, v44, v45
	v_mad_i64_i32 v[44:45], s[14:15], v140, s66, v[148:149]
	v_pk_add_f32 v[32:33], v[32:33], v[64:65]
	v_add_f32_e32 v37, 1.0, v37
	v_exp_f32_e32 v39, v39
	v_lshl_add_u64 v[44:45], v[44:45], 0, v[208:209]
	v_rcp_f32_e32 v37, v37
	v_mul_f32_e32 v32, 0xbfb8aa3b, v32
	v_cvt_pk_bf16_f32 v41, v46, v47
	v_cvt_pk_bf16_f32 v42, v48, v42
	v_cvt_pk_bf16_f32 v43, v43, v49
	global_store_dwordx4 v[44:45], v[40:43], off
	v_add_f32_e32 v38, 1.0, v38
	v_exp_f32_e32 v32, v32
	v_lshlrev_b32_e32 v40, 16, v112
	v_mul_f32_e32 v36, v36, v40
	s_waitcnt vmcnt(11)
	v_lshlrev_b32_e32 v40, 16, v116
	v_rcp_f32_e32 v38, v38
	v_mul_f32_e32 v36, v36, v40
	v_and_b32_e32 v40, 0xffff0000, v112
	v_add_f32_e32 v39, 1.0, v39
	v_mul_f32_e32 v37, v37, v40
	v_and_b32_e32 v40, 0xffff0000, v116
	v_rcp_f32_e32 v39, v39
	v_mul_f32_e32 v37, v37, v40
	v_lshlrev_b32_e32 v40, 16, v113
	v_add_f32_e32 v32, 1.0, v32
	v_mul_f32_e32 v38, v38, v40
	v_lshlrev_b32_e32 v40, 16, v117
	v_rcp_f32_e32 v32, v32
	v_mul_f32_e32 v33, 0xbfb8aa3b, v33
	v_mul_f32_e32 v38, v38, v40
	v_and_b32_e32 v40, 0xffff0000, v113
	v_exp_f32_e32 v33, v33
	v_mul_f32_e32 v39, v39, v40
	v_and_b32_e32 v40, 0xffff0000, v117
	v_mul_f32_e32 v39, v39, v40
	v_lshlrev_b32_e32 v40, 16, v114
	v_pk_add_f32 v[34:35], v[34:35], v[66:67]
	v_mul_f32_e32 v32, v32, v40
	v_lshlrev_b32_e32 v40, 16, v118
	v_mul_f32_e32 v40, v32, v40
	v_add_f32_e32 v32, 1.0, v33
	v_mul_f32_e32 v33, 0xbfb8aa3b, v34
	v_exp_f32_e32 v33, v33
	v_rcp_f32_e32 v32, v32
	v_mul_f32_e32 v35, 0xbfb8aa3b, v35
	v_exp_f32_e32 v35, v35
	v_add_f32_e32 v33, 1.0, v33
	v_rcp_f32_e32 v33, v33
	v_and_b32_e32 v34, 0xffff0000, v114
	v_pk_add_f32 v[28:29], v[28:29], v[76:77]
	v_mul_f32_e32 v32, v32, v34
	v_and_b32_e32 v34, 0xffff0000, v118
	v_mul_f32_e32 v28, 0xbfb8aa3b, v28
	v_mul_f32_e32 v34, v32, v34
	v_lshlrev_b32_e32 v32, 16, v115
	v_exp_f32_e32 v28, v28
	v_mul_f32_e32 v32, v33, v32
	v_add_f32_e32 v33, 1.0, v35
	v_mul_f32_e32 v29, 0xbfb8aa3b, v29
	v_rcp_f32_e32 v33, v33
	v_pk_add_f32 v[30:31], v[30:31], v[78:79]
	v_exp_f32_e32 v29, v29
	v_mul_f32_e32 v30, 0xbfb8aa3b, v30
	v_lshlrev_b32_e32 v35, 16, v119
	v_add_f32_e32 v28, 1.0, v28
	v_exp_f32_e32 v30, v30
	v_mul_f32_e32 v35, v32, v35
	v_and_b32_e32 v32, 0xffff0000, v115
	v_rcp_f32_e32 v28, v28
	v_mul_f32_e32 v31, 0xbfb8aa3b, v31
	v_mul_f32_e32 v32, v33, v32
	v_and_b32_e32 v33, 0xffff0000, v119
	v_pk_add_f32 v[24:25], v[24:25], v[72:73]
	v_add_f32_e32 v29, 1.0, v29
	v_exp_f32_e32 v31, v31
	v_mul_f32_e32 v41, v32, v33
	v_cvt_pk_bf16_f32 v32, v36, v37
	v_rcp_f32_e32 v29, v29
	v_mul_f32_e32 v24, 0xbfb8aa3b, v24
	v_cvt_pk_bf16_f32 v33, v38, v39
	v_cvt_pk_bf16_f32 v34, v40, v34
	v_cvt_pk_bf16_f32 v35, v35, v41
	global_store_dwordx4 v[44:45], v[32:35], off offset:256
	v_add_f32_e32 v30, 1.0, v30
	v_exp_f32_e32 v24, v24
	s_waitcnt vmcnt(11)
	v_lshlrev_b32_e32 v32, 16, v104
	v_mul_f32_e32 v28, v28, v32
	s_waitcnt vmcnt(9)
	v_lshlrev_b32_e32 v32, 16, v108
	v_rcp_f32_e32 v30, v30
	v_mul_f32_e32 v28, v28, v32
	v_and_b32_e32 v32, 0xffff0000, v104
	v_add_f32_e32 v31, 1.0, v31
	v_mul_f32_e32 v29, v29, v32
	v_and_b32_e32 v32, 0xffff0000, v108
	v_rcp_f32_e32 v31, v31
	v_mul_f32_e32 v29, v29, v32
	v_lshlrev_b32_e32 v32, 16, v105
	v_add_f32_e32 v24, 1.0, v24
	v_mul_f32_e32 v30, v30, v32
	v_lshlrev_b32_e32 v32, 16, v109
	v_rcp_f32_e32 v24, v24
	v_mul_f32_e32 v25, 0xbfb8aa3b, v25
	v_mul_f32_e32 v30, v30, v32
	v_and_b32_e32 v32, 0xffff0000, v105
	v_exp_f32_e32 v25, v25
	v_mul_f32_e32 v31, v31, v32
	v_and_b32_e32 v32, 0xffff0000, v109
	v_mul_f32_e32 v31, v31, v32
	v_lshlrev_b32_e32 v32, 16, v106
	v_pk_add_f32 v[26:27], v[26:27], v[74:75]
	v_mul_f32_e32 v24, v24, v32
	v_lshlrev_b32_e32 v32, 16, v110
	v_mul_f32_e32 v32, v24, v32
	v_add_f32_e32 v24, 1.0, v25
	v_mul_f32_e32 v25, 0xbfb8aa3b, v26
	v_exp_f32_e32 v25, v25
	v_rcp_f32_e32 v24, v24
	v_mul_f32_e32 v27, 0xbfb8aa3b, v27
	v_exp_f32_e32 v27, v27
	v_add_f32_e32 v25, 1.0, v25
	v_rcp_f32_e32 v25, v25
	v_and_b32_e32 v26, 0xffff0000, v106
	v_mul_f32_e32 v24, v24, v26
	v_and_b32_e32 v26, 0xffff0000, v110
	v_pk_add_f32 v[20:21], v[20:21], v[68:69]
	v_mul_f32_e32 v26, v24, v26
	v_lshlrev_b32_e32 v24, 16, v107
	v_mul_f32_e32 v20, 0xbfb8aa3b, v20
	v_mul_f32_e32 v24, v25, v24
	v_add_f32_e32 v25, 1.0, v27
	v_exp_f32_e32 v20, v20
	v_rcp_f32_e32 v25, v25
	v_mul_f32_e32 v21, 0xbfb8aa3b, v21
	v_pk_add_f32 v[22:23], v[22:23], v[70:71]
	v_exp_f32_e32 v21, v21
	v_lshlrev_b32_e32 v27, 16, v111
	v_mul_f32_e32 v22, 0xbfb8aa3b, v22
	v_mul_f32_e32 v27, v24, v27
	v_and_b32_e32 v24, 0xffff0000, v107
	v_add_f32_e32 v20, 1.0, v20
	v_exp_f32_e32 v22, v22
	v_mul_f32_e32 v24, v25, v24
	v_and_b32_e32 v25, 0xffff0000, v111
	v_rcp_f32_e32 v20, v20
	v_mul_f32_e32 v23, 0xbfb8aa3b, v23
	v_mul_f32_e32 v33, v24, v25
	v_cvt_pk_bf16_f32 v24, v28, v29
	v_mad_i64_i32 v[28:29], s[14:15], v138, s66, v[148:149]
	v_pk_add_f32 v[16:17], v[16:17], v[64:65]
	v_add_f32_e32 v21, 1.0, v21
	v_exp_f32_e32 v23, v23
	v_lshl_add_u64 v[28:29], v[28:29], 0, v[208:209]
	v_rcp_f32_e32 v21, v21
	v_mul_f32_e32 v16, 0xbfb8aa3b, v16
	v_cvt_pk_bf16_f32 v25, v30, v31
	v_cvt_pk_bf16_f32 v26, v32, v26
	v_cvt_pk_bf16_f32 v27, v27, v33
	global_store_dwordx4 v[28:29], v[24:27], off
	v_add_f32_e32 v22, 1.0, v22
	v_exp_f32_e32 v16, v16
	v_lshlrev_b32_e32 v24, 16, v96
	v_mul_f32_e32 v20, v20, v24
	s_waitcnt vmcnt(9)
	v_lshlrev_b32_e32 v24, 16, v100
	v_rcp_f32_e32 v22, v22
	v_mul_f32_e32 v20, v20, v24
	v_and_b32_e32 v24, 0xffff0000, v96
	v_add_f32_e32 v23, 1.0, v23
	v_mul_f32_e32 v21, v21, v24
	v_and_b32_e32 v24, 0xffff0000, v100
	v_rcp_f32_e32 v23, v23
	v_mul_f32_e32 v21, v21, v24
	v_lshlrev_b32_e32 v24, 16, v97
	v_add_f32_e32 v16, 1.0, v16
	v_mul_f32_e32 v22, v22, v24
	v_lshlrev_b32_e32 v24, 16, v101
	v_rcp_f32_e32 v16, v16
	v_mul_f32_e32 v17, 0xbfb8aa3b, v17
	v_mul_f32_e32 v22, v22, v24
	v_and_b32_e32 v24, 0xffff0000, v97
	v_exp_f32_e32 v17, v17
	v_mul_f32_e32 v23, v23, v24
	v_and_b32_e32 v24, 0xffff0000, v101
	v_mul_f32_e32 v23, v23, v24
	v_lshlrev_b32_e32 v24, 16, v98
	v_pk_add_f32 v[18:19], v[18:19], v[66:67]
	v_mul_f32_e32 v16, v16, v24
	v_lshlrev_b32_e32 v24, 16, v102
	v_mul_f32_e32 v24, v16, v24
	v_add_f32_e32 v16, 1.0, v17
	v_mul_f32_e32 v17, 0xbfb8aa3b, v18
	v_exp_f32_e32 v17, v17
	v_rcp_f32_e32 v16, v16
	v_mul_f32_e32 v19, 0xbfb8aa3b, v19
	v_exp_f32_e32 v19, v19
	v_add_f32_e32 v17, 1.0, v17
	v_rcp_f32_e32 v17, v17
	v_and_b32_e32 v18, 0xffff0000, v98
	v_pk_add_f32 v[12:13], v[12:13], v[76:77]
	v_mul_f32_e32 v16, v16, v18
	v_and_b32_e32 v18, 0xffff0000, v102
	v_mul_f32_e32 v12, 0xbfb8aa3b, v12
	v_mul_f32_e32 v18, v16, v18
	v_lshlrev_b32_e32 v16, 16, v99
	v_exp_f32_e32 v12, v12
	v_mul_f32_e32 v16, v17, v16
	v_add_f32_e32 v17, 1.0, v19
	v_mul_f32_e32 v13, 0xbfb8aa3b, v13
	v_rcp_f32_e32 v17, v17
	v_pk_add_f32 v[14:15], v[14:15], v[78:79]
	v_exp_f32_e32 v13, v13
	v_mul_f32_e32 v14, 0xbfb8aa3b, v14
	v_lshlrev_b32_e32 v19, 16, v103
	v_add_f32_e32 v12, 1.0, v12
	v_exp_f32_e32 v14, v14
	v_mul_f32_e32 v19, v16, v19
	v_and_b32_e32 v16, 0xffff0000, v99
	v_rcp_f32_e32 v12, v12
	v_mul_f32_e32 v15, 0xbfb8aa3b, v15
	v_mul_f32_e32 v16, v17, v16
	v_and_b32_e32 v17, 0xffff0000, v103
	v_pk_add_f32 v[8:9], v[8:9], v[72:73]
	v_add_f32_e32 v13, 1.0, v13
	v_exp_f32_e32 v15, v15
	v_mul_f32_e32 v25, v16, v17
	v_cvt_pk_bf16_f32 v16, v20, v21
	v_rcp_f32_e32 v13, v13
	v_mul_f32_e32 v8, 0xbfb8aa3b, v8
	v_cvt_pk_bf16_f32 v17, v22, v23
	v_cvt_pk_bf16_f32 v18, v24, v18
	v_cvt_pk_bf16_f32 v19, v19, v25
	global_store_dwordx4 v[28:29], v[16:19], off offset:256
	v_add_f32_e32 v14, 1.0, v14
	v_exp_f32_e32 v8, v8
	s_waitcnt vmcnt(9)
	v_lshlrev_b32_e32 v16, 16, v88
	v_mul_f32_e32 v12, v12, v16
	s_waitcnt vmcnt(7)
	v_lshlrev_b32_e32 v16, 16, v92
	v_rcp_f32_e32 v14, v14
	v_mul_f32_e32 v12, v12, v16
	v_and_b32_e32 v16, 0xffff0000, v88
	v_add_f32_e32 v15, 1.0, v15
	v_mul_f32_e32 v13, v13, v16
	v_and_b32_e32 v16, 0xffff0000, v92
	v_rcp_f32_e32 v15, v15
	v_mul_f32_e32 v13, v13, v16
	v_lshlrev_b32_e32 v16, 16, v89
	v_add_f32_e32 v8, 1.0, v8
	v_mul_f32_e32 v14, v14, v16
	v_lshlrev_b32_e32 v16, 16, v93
	v_rcp_f32_e32 v8, v8
	v_mul_f32_e32 v9, 0xbfb8aa3b, v9
	v_mul_f32_e32 v14, v14, v16
	v_and_b32_e32 v16, 0xffff0000, v89
	v_exp_f32_e32 v9, v9
	v_mul_f32_e32 v15, v15, v16
	v_and_b32_e32 v16, 0xffff0000, v93
	v_mul_f32_e32 v15, v15, v16
	v_lshlrev_b32_e32 v16, 16, v90
	v_pk_add_f32 v[10:11], v[10:11], v[74:75]
	v_mul_f32_e32 v8, v8, v16
	v_lshlrev_b32_e32 v16, 16, v94
	v_mul_f32_e32 v16, v8, v16
	v_add_f32_e32 v8, 1.0, v9
	v_mul_f32_e32 v9, 0xbfb8aa3b, v10
	v_exp_f32_e32 v9, v9
	v_rcp_f32_e32 v8, v8
	v_mul_f32_e32 v11, 0xbfb8aa3b, v11
	v_exp_f32_e32 v11, v11
	v_add_f32_e32 v9, 1.0, v9
	v_rcp_f32_e32 v9, v9
	v_and_b32_e32 v10, 0xffff0000, v90
	v_mul_f32_e32 v8, v8, v10
	v_and_b32_e32 v10, 0xffff0000, v94
	v_pk_add_f32 v[4:5], v[4:5], v[68:69]
	v_mul_f32_e32 v10, v8, v10
	v_lshlrev_b32_e32 v8, 16, v91
	v_mul_f32_e32 v4, 0xbfb8aa3b, v4
	v_mul_f32_e32 v8, v9, v8
	v_add_f32_e32 v9, 1.0, v11
	v_exp_f32_e32 v4, v4
	v_rcp_f32_e32 v9, v9
	v_mul_f32_e32 v5, 0xbfb8aa3b, v5
	v_pk_add_f32 v[6:7], v[6:7], v[70:71]
	v_exp_f32_e32 v5, v5
	v_lshlrev_b32_e32 v11, 16, v95
	v_mul_f32_e32 v6, 0xbfb8aa3b, v6
	v_mul_f32_e32 v11, v8, v11
	v_and_b32_e32 v8, 0xffff0000, v91
	v_add_f32_e32 v4, 1.0, v4
	v_exp_f32_e32 v6, v6
	v_mul_f32_e32 v8, v9, v8
	v_and_b32_e32 v9, 0xffff0000, v95
	v_rcp_f32_e32 v4, v4
	v_mul_f32_e32 v7, 0xbfb8aa3b, v7
	v_mul_f32_e32 v17, v8, v9
	v_cvt_pk_bf16_f32 v8, v12, v13
	v_mad_i64_i32 v[12:13], s[14:15], v136, s66, v[148:149]
	v_pk_add_f32 v[0:1], v[0:1], v[64:65]
	v_add_f32_e32 v5, 1.0, v5
	v_exp_f32_e32 v7, v7
	v_lshl_add_u64 v[12:13], v[12:13], 0, v[208:209]
	v_rcp_f32_e32 v5, v5
	v_mul_f32_e32 v0, 0xbfb8aa3b, v0
	v_cvt_pk_bf16_f32 v9, v14, v15
	v_cvt_pk_bf16_f32 v10, v16, v10
	v_cvt_pk_bf16_f32 v11, v11, v17
	global_store_dwordx4 v[12:13], v[8:11], off
	v_add_f32_e32 v6, 1.0, v6
	v_exp_f32_e32 v0, v0
	v_lshlrev_b32_e32 v8, 16, v80
	v_mul_f32_e32 v4, v4, v8
	s_waitcnt vmcnt(7)
	v_lshlrev_b32_e32 v8, 16, v84
	v_rcp_f32_e32 v6, v6
	v_mul_f32_e32 v4, v4, v8
	v_and_b32_e32 v8, 0xffff0000, v80
	v_add_f32_e32 v7, 1.0, v7
	v_mul_f32_e32 v5, v5, v8
	v_and_b32_e32 v8, 0xffff0000, v84
	v_rcp_f32_e32 v7, v7
	v_mul_f32_e32 v5, v5, v8
	v_lshlrev_b32_e32 v8, 16, v81
	v_add_f32_e32 v0, 1.0, v0
	v_mul_f32_e32 v6, v6, v8
	v_lshlrev_b32_e32 v8, 16, v85
	v_rcp_f32_e32 v0, v0
	v_mul_f32_e32 v1, 0xbfb8aa3b, v1
	v_mul_f32_e32 v6, v6, v8
	v_and_b32_e32 v8, 0xffff0000, v81
	v_exp_f32_e32 v1, v1
	v_mul_f32_e32 v7, v7, v8
	v_and_b32_e32 v8, 0xffff0000, v85
	v_mul_f32_e32 v7, v7, v8
	v_lshlrev_b32_e32 v8, 16, v82
	v_pk_add_f32 v[2:3], v[2:3], v[66:67]
	v_mul_f32_e32 v0, v0, v8
	v_lshlrev_b32_e32 v8, 16, v86
	v_mul_f32_e32 v8, v0, v8
	v_add_f32_e32 v0, 1.0, v1
	v_mul_f32_e32 v1, 0xbfb8aa3b, v2
	v_exp_f32_e32 v1, v1
	v_rcp_f32_e32 v0, v0
	v_mul_f32_e32 v3, 0xbfb8aa3b, v3
	v_exp_f32_e32 v3, v3
	v_add_f32_e32 v1, 1.0, v1
	v_rcp_f32_e32 v1, v1
	v_and_b32_e32 v2, 0xffff0000, v82
	v_mul_f32_e32 v0, v0, v2
	v_and_b32_e32 v2, 0xffff0000, v86
	v_mul_f32_e32 v2, v0, v2
	v_lshlrev_b32_e32 v0, 16, v83
	v_mul_f32_e32 v0, v1, v0
	v_add_f32_e32 v1, 1.0, v3
	v_rcp_f32_e32 v1, v1
	v_lshlrev_b32_e32 v3, 16, v87
	v_mul_f32_e32 v3, v0, v3
	v_and_b32_e32 v0, 0xffff0000, v83
	v_mul_f32_e32 v0, v1, v0
	v_and_b32_e32 v1, 0xffff0000, v87
	s_mov_b64 s[14:15], s[36:37]
	v_mul_f32_e32 v9, v0, v1
	v_cvt_pk_bf16_f32 v0, v4, v5
	v_cvt_pk_bf16_f32 v1, v6, v7
	v_cvt_pk_bf16_f32 v2, v8, v2
	v_cvt_pk_bf16_f32 v3, v3, v9
	global_store_dwordx4 v[12:13], v[0:3], off offset:256
	s_cbranch_vccz .LBB0_1387
	s_waitcnt vmcnt(0)
	s_cmpk_gt_u32 s52, 0xff
	s_cbranch_scc1 .LBB0_1398
	s_barrier

.LBB0_1473:
	s_add_u32 s6, s36, 0x100
	s_addc_u32 s7, s37, 0
	s_cmp_eq_u32 s72, 28
	s_cselect_b32 s41, s23, s7
	s_cselect_b32 s40, s22, s6
	s_cselect_b32 s39, s19, s71
	s_cselect_b32 s38, s69, s70
	s_add_i32 s73, 0, 0x14000
	v_add_u32_e32 v172, s73, v181
	ds_read_b128 v[128:131], v183
	ds_read_b128 v[132:135], v183 offset:1024
	ds_read_b128 v[136:139], v183 offset:2048
	ds_read_b128 v[140:143], v183 offset:3072
	ds_read_b128 v[144:147], v172
	ds_read_b128 v[164:167], v172 offset:1024
	ds_read_b128 v[168:171], v172 offset:2048
	ds_read_b128 v[172:175], v172 offset:3072
	s_add_i32 m0, s57, 0xc000
	ds_read_b128 v[176:179], v184
	ds_read_b128 v[186:189], v184 offset:1024
	ds_read_b128 v[190:193], v184 offset:2048
	ds_read_b128 v[194:197], v184 offset:3072
	ds_read_b128 v[198:201], v184 offset:4096
	ds_read_b128 v[202:205], v184 offset:5120
	ds_read_b128 v[206:209], v184 offset:6144
	ds_read_b128 v[210:213], v184 offset:7168
	global_load_lds_dwordx4 v158, s[36:37]
	s_add_i32 m0, s57, 0xe000
	s_nop 0
	global_load_lds_dwordx4 v156, s[36:37]
	s_waitcnt vmcnt(8)
	s_waitcnt lgkmcnt(0)
	s_barrier
	s_setprio 1
	s_waitcnt lgkmcnt(0)
	v_mfma_f32_16x16x32_bf16 v[124:127], v[128:131], v[176:179], v[124:127]
	v_mfma_f32_16x16x32_bf16 v[120:123], v[136:139], v[176:179], v[120:123]
	v_mfma_f32_16x16x32_bf16 v[116:119], v[128:131], v[190:193], v[116:119]
	v_mfma_f32_16x16x32_bf16 v[104:107], v[136:139], v[190:193], v[104:107]
	v_mfma_f32_16x16x32_bf16 v[92:95], v[128:131], v[198:201], v[92:95]
	v_mfma_f32_16x16x32_bf16 v[88:91], v[136:139], v[198:201], v[88:91]
	v_mfma_f32_16x16x32_bf16 v[76:79], v[128:131], v[206:209], v[76:79]
	v_mfma_f32_16x16x32_bf16 v[72:75], v[136:139], v[206:209], v[72:75]
	v_mfma_f32_16x16x32_bf16 v[124:127], v[132:135], v[186:189], v[124:127]
	v_mfma_f32_16x16x32_bf16 v[120:123], v[140:143], v[186:189], v[120:123]
	v_mfma_f32_16x16x32_bf16 v[116:119], v[132:135], v[194:197], v[116:119]
	v_mfma_f32_16x16x32_bf16 v[104:107], v[140:143], v[194:197], v[104:107]
	v_mfma_f32_16x16x32_bf16 v[92:95], v[132:135], v[202:205], v[92:95]
	v_mfma_f32_16x16x32_bf16 v[88:91], v[140:143], v[202:205], v[88:91]
	v_mfma_f32_16x16x32_bf16 v[76:79], v[132:135], v[210:213], v[76:79]
	v_mfma_f32_16x16x32_bf16 v[72:75], v[140:143], v[210:213], v[72:75]
	s_setprio 0
	s_setprio 1
	v_mfma_f32_16x16x32_bf16 v[112:115], v[144:147], v[176:179], v[112:115]
	v_mfma_f32_16x16x32_bf16 v[108:111], v[168:171], v[176:179], v[108:111]
	v_mfma_f32_16x16x32_bf16 v[100:103], v[144:147], v[190:193], v[100:103]
	v_mfma_f32_16x16x32_bf16 v[96:99], v[168:171], v[190:193], v[96:99]
	v_mfma_f32_16x16x32_bf16 v[84:87], v[144:147], v[198:201], v[84:87]
	v_mfma_f32_16x16x32_bf16 v[80:83], v[168:171], v[198:201], v[80:83]
	v_mfma_f32_16x16x32_bf16 v[68:71], v[144:147], v[206:209], v[68:71]
	v_mfma_f32_16x16x32_bf16 v[64:67], v[168:171], v[206:209], v[64:67]
	v_mfma_f32_16x16x32_bf16 v[112:115], v[164:167], v[186:189], v[112:115]
	v_mfma_f32_16x16x32_bf16 v[108:111], v[172:175], v[186:189], v[108:111]
	v_mfma_f32_16x16x32_bf16 v[100:103], v[164:167], v[194:197], v[100:103]
	v_mfma_f32_16x16x32_bf16 v[96:99], v[172:175], v[194:197], v[96:99]
	v_mfma_f32_16x16x32_bf16 v[84:87], v[164:167], v[202:205], v[84:87]
	v_mfma_f32_16x16x32_bf16 v[80:83], v[172:175], v[202:205], v[80:83]
	v_mfma_f32_16x16x32_bf16 v[68:71], v[164:167], v[210:213], v[68:71]
	v_mfma_f32_16x16x32_bf16 v[64:67], v[172:175], v[210:213], v[64:67]
	s_setprio 0
	s_barrier
	s_add_i32 s36, s65, s56
	s_mov_b64 s[98:99], s[38:39]
	s_mov_b32 m0, s36
	ds_read_b128 v[176:179], v184 offset:16384
	ds_read_b128 v[186:189], v184 offset:17408
	ds_read_b128 v[190:193], v184 offset:18432
	ds_read_b128 v[194:197], v184 offset:19456
	ds_read_b128 v[198:201], v184 offset:20480
	ds_read_b128 v[202:205], v184 offset:21504
	ds_read_b128 v[206:209], v184 offset:22528
	ds_read_b128 v[210:213], v184 offset:23552
	global_load_lds_dwordx4 v150, s[38:39]
	s_add_i32 m0, s36, 0x2000
	s_add_u32 s36, s38, 0x80000
	s_addc_u32 s37, s39, 0
	s_add_i32 s73, s73, s56
	global_load_lds_dwordx4 v154, s[38:39]
	s_mov_b32 m0, s73
	s_mov_b64 s[100:101], s[40:41]
	global_load_lds_dwordx4 v150, s[36:37]
	s_add_i32 m0, s73, 0x2000
	s_nop 0
	global_load_lds_dwordx4 v154, s[36:37]
	s_mov_b32 m0, s57
	s_nop 0
	global_load_lds_dwordx4 v148, s[40:41]
	s_mov_b32 m0, s58
	s_nop 0
	global_load_lds_dwordx4 v152, s[40:41]
	s_waitcnt vmcnt(8)
	s_waitcnt lgkmcnt(0)
	s_barrier
	s_setprio 1
	s_waitcnt lgkmcnt(0)
	v_mfma_f32_16x16x32_bf16 v[60:63], v[128:131], v[176:179], v[60:63]
	v_mfma_f32_16x16x32_bf16 v[56:59], v[136:139], v[176:179], v[56:59]
	v_mfma_f32_16x16x32_bf16 v[52:55], v[128:131], v[190:193], v[52:55]
	v_mfma_f32_16x16x32_bf16 v[40:43], v[136:139], v[190:193], v[40:43]
	v_mfma_f32_16x16x32_bf16 v[28:31], v[128:131], v[198:201], v[28:31]
	v_mfma_f32_16x16x32_bf16 v[24:27], v[136:139], v[198:201], v[24:27]
	v_mfma_f32_16x16x32_bf16 v[12:15], v[128:131], v[206:209], v[12:15]
	v_mfma_f32_16x16x32_bf16 v[8:11], v[136:139], v[206:209], v[8:11]
	v_mfma_f32_16x16x32_bf16 v[60:63], v[132:135], v[186:189], v[60:63]
	v_mfma_f32_16x16x32_bf16 v[56:59], v[140:143], v[186:189], v[56:59]
	v_mfma_f32_16x16x32_bf16 v[52:55], v[132:135], v[194:197], v[52:55]
	v_mfma_f32_16x16x32_bf16 v[40:43], v[140:143], v[194:197], v[40:43]
	v_mfma_f32_16x16x32_bf16 v[28:31], v[132:135], v[202:205], v[28:31]
	v_mfma_f32_16x16x32_bf16 v[24:27], v[140:143], v[202:205], v[24:27]
	v_mfma_f32_16x16x32_bf16 v[12:15], v[132:135], v[210:213], v[12:15]
	v_mfma_f32_16x16x32_bf16 v[8:11], v[140:143], v[210:213], v[8:11]
	s_setprio 0
	s_setprio 1
	v_mfma_f32_16x16x32_bf16 v[48:51], v[144:147], v[176:179], v[48:51]
	v_mfma_f32_16x16x32_bf16 v[44:47], v[168:171], v[176:179], v[44:47]
	v_mfma_f32_16x16x32_bf16 v[36:39], v[144:147], v[190:193], v[36:39]
	v_mfma_f32_16x16x32_bf16 v[32:35], v[168:171], v[190:193], v[32:35]
	v_mfma_f32_16x16x32_bf16 v[20:23], v[144:147], v[198:201], v[20:23]
	v_mfma_f32_16x16x32_bf16 v[16:19], v[168:171], v[198:201], v[16:19]
	v_mfma_f32_16x16x32_bf16 v[4:7], v[144:147], v[206:209], v[4:7]
	v_mfma_f32_16x16x32_bf16 v[0:3], v[168:171], v[206:209], v[0:3]
	v_mfma_f32_16x16x32_bf16 v[48:51], v[164:167], v[186:189], v[48:51]
	v_mfma_f32_16x16x32_bf16 v[44:47], v[172:175], v[186:189], v[44:47]
	v_mfma_f32_16x16x32_bf16 v[36:39], v[164:167], v[194:197], v[36:39]
	v_mfma_f32_16x16x32_bf16 v[32:35], v[172:175], v[194:197], v[32:35]
	v_mfma_f32_16x16x32_bf16 v[20:23], v[164:167], v[202:205], v[20:23]
	v_mfma_f32_16x16x32_bf16 v[16:19], v[172:175], v[202:205], v[16:19]
	v_mfma_f32_16x16x32_bf16 v[4:7], v[164:167], v[210:213], v[4:7]
	v_mfma_f32_16x16x32_bf16 v[0:3], v[172:175], v[210:213], v[0:3]
	s_setprio 0
	s_barrier
	s_add_i32 s73, 0, 0x18000
	s_add_i32 s74, 0, 0x1c000
	v_add_u32_e32 v140, s73, v181
	v_add_u32_e32 v172, s74, v181
	ds_read_b128 v[128:131], v140
	ds_read_b128 v[132:135], v140 offset:1024
	ds_read_b128 v[136:139], v140 offset:2048
	ds_read_b128 v[140:143], v140 offset:3072
	ds_read_b128 v[144:147], v172
	ds_read_b128 v[164:167], v172 offset:1024
	ds_read_b128 v[168:171], v172 offset:2048
	ds_read_b128 v[172:175], v172 offset:3072
	s_add_u32 s36, s40, 0x140000
	s_addc_u32 s37, s41, 0
	s_mov_b32 m0, s59
	ds_read_b128 v[176:179], v184 offset:32768
	ds_read_b128 v[186:189], v184 offset:33792
	ds_read_b128 v[190:193], v184 offset:34816
	ds_read_b128 v[194:197], v184 offset:35840
	ds_read_b128 v[198:201], v184 offset:36864
	ds_read_b128 v[202:205], v184 offset:37888
	ds_read_b128 v[206:209], v184 offset:38912
	ds_read_b128 v[210:213], v184 offset:39936
	global_load_lds_dwordx4 v148, s[36:37]
	s_mov_b32 m0, s60
	s_nop 0
	global_load_lds_dwordx4 v152, s[36:37]
	s_waitcnt vmcnt(8)
	s_waitcnt lgkmcnt(0)
	s_barrier
	s_setprio 1
	s_waitcnt lgkmcnt(0)
	v_mfma_f32_16x16x32_bf16 v[124:127], v[128:131], v[176:179], v[124:127]
	v_mfma_f32_16x16x32_bf16 v[120:123], v[136:139], v[176:179], v[120:123]
	v_mfma_f32_16x16x32_bf16 v[116:119], v[128:131], v[190:193], v[116:119]
	v_mfma_f32_16x16x32_bf16 v[104:107], v[136:139], v[190:193], v[104:107]
	v_mfma_f32_16x16x32_bf16 v[92:95], v[128:131], v[198:201], v[92:95]
	v_mfma_f32_16x16x32_bf16 v[88:91], v[136:139], v[198:201], v[88:91]
	v_mfma_f32_16x16x32_bf16 v[76:79], v[128:131], v[206:209], v[76:79]
	v_mfma_f32_16x16x32_bf16 v[72:75], v[136:139], v[206:209], v[72:75]
	v_mfma_f32_16x16x32_bf16 v[124:127], v[132:135], v[186:189], v[124:127]
	v_mfma_f32_16x16x32_bf16 v[120:123], v[140:143], v[186:189], v[120:123]
	v_mfma_f32_16x16x32_bf16 v[116:119], v[132:135], v[194:197], v[116:119]
	v_mfma_f32_16x16x32_bf16 v[104:107], v[140:143], v[194:197], v[104:107]
	v_mfma_f32_16x16x32_bf16 v[92:95], v[132:135], v[202:205], v[92:95]
	v_mfma_f32_16x16x32_bf16 v[88:91], v[140:143], v[202:205], v[88:91]
	v_mfma_f32_16x16x32_bf16 v[76:79], v[132:135], v[210:213], v[76:79]
	v_mfma_f32_16x16x32_bf16 v[72:75], v[140:143], v[210:213], v[72:75]
	s_setprio 0
	s_setprio 1
	v_mfma_f32_16x16x32_bf16 v[112:115], v[144:147], v[176:179], v[112:115]
	v_mfma_f32_16x16x32_bf16 v[108:111], v[168:171], v[176:179], v[108:111]
	v_mfma_f32_16x16x32_bf16 v[100:103], v[144:147], v[190:193], v[100:103]
	v_mfma_f32_16x16x32_bf16 v[96:99], v[168:171], v[190:193], v[96:99]
	v_mfma_f32_16x16x32_bf16 v[84:87], v[144:147], v[198:201], v[84:87]
	v_mfma_f32_16x16x32_bf16 v[80:83], v[168:171], v[198:201], v[80:83]
	v_mfma_f32_16x16x32_bf16 v[68:71], v[144:147], v[206:209], v[68:71]
	v_mfma_f32_16x16x32_bf16 v[64:67], v[168:171], v[206:209], v[64:67]
	v_mfma_f32_16x16x32_bf16 v[112:115], v[164:167], v[186:189], v[112:115]
	v_mfma_f32_16x16x32_bf16 v[108:111], v[172:175], v[186:189], v[108:111]
	v_mfma_f32_16x16x32_bf16 v[100:103], v[164:167], v[194:197], v[100:103]
	v_mfma_f32_16x16x32_bf16 v[96:99], v[172:175], v[194:197], v[96:99]
	v_mfma_f32_16x16x32_bf16 v[84:87], v[164:167], v[202:205], v[84:87]
	v_mfma_f32_16x16x32_bf16 v[80:83], v[172:175], v[202:205], v[80:83]
	v_mfma_f32_16x16x32_bf16 v[68:71], v[164:167], v[210:213], v[68:71]
	v_mfma_f32_16x16x32_bf16 v[64:67], v[172:175], v[210:213], v[64:67]
	s_setprio 0
	s_barrier
	s_add_i32 s36, s73, s56
	s_add_i32 m0, s36, 0xffffff80
	ds_read_b128 v[176:179], v184 offset:49152
	ds_read_b128 v[186:189], v184 offset:50176
	ds_read_b128 v[190:193], v184 offset:51200
	ds_read_b128 v[194:197], v184 offset:52224
	ds_read_b128 v[198:201], v184 offset:53248
	ds_read_b128 v[202:205], v184 offset:54272
	ds_read_b128 v[206:209], v184 offset:55296
	ds_read_b128 v[210:213], v184 offset:56320
	global_load_lds_dwordx4 v150, s[98:99] offset:128
	s_add_i32 m0, s36, 0x1f80
	s_add_u32 s36, s38, 0x80080
	s_addc_u32 s37, s39, 0
	s_add_i32 s38, s74, s56
	global_load_lds_dwordx4 v154, s[98:99] offset:128
	s_mov_b32 m0, s38
	s_nop 0
	global_load_lds_dwordx4 v150, s[36:37]
	s_add_i32 m0, s38, 0x2000
	s_nop 0
	global_load_lds_dwordx4 v154, s[36:37]
	s_add_i32 m0, s62, 0xffffff80
	s_nop 0
	global_load_lds_dwordx4 v148, s[100:101] offset:128
	s_add_i32 m0, s63, 0xffffff80
	s_nop 0
	global_load_lds_dwordx4 v152, s[100:101] offset:128
	s_waitcnt vmcnt(8)
	s_waitcnt lgkmcnt(0)
	s_barrier
	s_setprio 1
	s_waitcnt lgkmcnt(0)
	v_mfma_f32_16x16x32_bf16 v[60:63], v[128:131], v[176:179], v[60:63]
	v_mfma_f32_16x16x32_bf16 v[56:59], v[136:139], v[176:179], v[56:59]
	v_mfma_f32_16x16x32_bf16 v[52:55], v[128:131], v[190:193], v[52:55]
	v_mfma_f32_16x16x32_bf16 v[40:43], v[136:139], v[190:193], v[40:43]
	v_mfma_f32_16x16x32_bf16 v[28:31], v[128:131], v[198:201], v[28:31]
	v_mfma_f32_16x16x32_bf16 v[24:27], v[136:139], v[198:201], v[24:27]
	v_mfma_f32_16x16x32_bf16 v[12:15], v[128:131], v[206:209], v[12:15]
	v_mfma_f32_16x16x32_bf16 v[8:11], v[136:139], v[206:209], v[8:11]
	v_mfma_f32_16x16x32_bf16 v[60:63], v[132:135], v[186:189], v[60:63]
	v_mfma_f32_16x16x32_bf16 v[56:59], v[140:143], v[186:189], v[56:59]
	v_mfma_f32_16x16x32_bf16 v[52:55], v[132:135], v[194:197], v[52:55]
	v_mfma_f32_16x16x32_bf16 v[40:43], v[140:143], v[194:197], v[40:43]
	v_mfma_f32_16x16x32_bf16 v[28:31], v[132:135], v[202:205], v[28:31]
	v_mfma_f32_16x16x32_bf16 v[24:27], v[140:143], v[202:205], v[24:27]
	v_mfma_f32_16x16x32_bf16 v[12:15], v[132:135], v[210:213], v[12:15]
	v_mfma_f32_16x16x32_bf16 v[8:11], v[140:143], v[210:213], v[8:11]
	s_setprio 0
	s_setprio 1
	v_mfma_f32_16x16x32_bf16 v[48:51], v[144:147], v[176:179], v[48:51]
	v_mfma_f32_16x16x32_bf16 v[44:47], v[168:171], v[176:179], v[44:47]
	v_mfma_f32_16x16x32_bf16 v[36:39], v[144:147], v[190:193], v[36:39]
	v_mfma_f32_16x16x32_bf16 v[32:35], v[168:171], v[190:193], v[32:35]
	v_mfma_f32_16x16x32_bf16 v[20:23], v[144:147], v[198:201], v[20:23]
	v_mfma_f32_16x16x32_bf16 v[16:19], v[168:171], v[198:201], v[16:19]
	v_mfma_f32_16x16x32_bf16 v[4:7], v[144:147], v[206:209], v[4:7]
	v_mfma_f32_16x16x32_bf16 v[0:3], v[168:171], v[206:209], v[0:3]
	v_mfma_f32_16x16x32_bf16 v[48:51], v[164:167], v[186:189], v[48:51]
	v_mfma_f32_16x16x32_bf16 v[44:47], v[172:175], v[186:189], v[44:47]
	v_mfma_f32_16x16x32_bf16 v[36:39], v[164:167], v[194:197], v[36:39]
	v_mfma_f32_16x16x32_bf16 v[32:35], v[172:175], v[194:197], v[32:35]
	v_mfma_f32_16x16x32_bf16 v[20:23], v[164:167], v[202:205], v[20:23]
	v_mfma_f32_16x16x32_bf16 v[16:19], v[172:175], v[202:205], v[16:19]
	v_mfma_f32_16x16x32_bf16 v[4:7], v[164:167], v[210:213], v[4:7]
	v_mfma_f32_16x16x32_bf16 v[0:3], v[172:175], v[210:213], v[0:3]
	s_setprio 0
	s_barrier
	s_add_i32 s72, s72, 2
	s_add_u32 s70, s70, 0x100
	s_addc_u32 s71, s71, 0
	s_cmp_gt_u32 s72, 29
	s_mov_b64 s[36:37], s[6:7]
	s_cbranch_scc0 .LBB0_1473
	s_and_b64 vcc, exec, s[16:17]
	s_cbranch_vccz .LBB0_1476
	s_barrier

.LBB0_1558:
	ds_read_b128 v[24:27], v215
	ds_read_b128 v[32:35], v215 offset:1024
	ds_read_b128 v[40:43], v215 offset:2048
	ds_read_b128 v[44:47], v215 offset:3072
	ds_read_b128 v[56:59], v216
	ds_read_b128 v[60:63], v216 offset:1024
	ds_read_b128 v[64:67], v216 offset:2048
	ds_read_b128 v[68:71], v216 offset:3072
	s_add_u32 s10, s6, 0xfff80080
	s_addc_u32 s11, s7, -1
	s_cmp_eq_u32 s69, 28
	s_cselect_b32 s13, s5, s11
	s_cselect_b32 s12, s9, s10
	s_cselect_b32 s11, s33, s68
	s_cselect_b32 s10, s61, s63
	s_add_i32 m0, s72, 0xc000
	ds_read_b128 v[152:155], v217
	ds_read_b128 v[164:167], v217 offset:1024
	ds_read_b128 v[168:171], v217 offset:2048
	ds_read_b128 v[198:201], v217 offset:3072
	ds_read_b128 v[202:205], v217 offset:4096
	ds_read_b128 v[206:209], v217 offset:5120
	ds_read_b128 v[222:225], v217 offset:6144
	ds_read_b128 v[226:229], v217 offset:7168
	global_load_lds_dwordx4 v190, s[6:7]
	s_add_i32 m0, s72, 0xe000
	s_nop 0
	global_load_lds_dwordx4 v192, s[6:7]
	s_waitcnt vmcnt(8)
	s_waitcnt lgkmcnt(0)
	s_barrier
	s_setprio 1
	s_waitcnt lgkmcnt(0)
	v_mfma_f32_16x16x32_bf16 v[160:163], v[24:27], v[152:155], v[160:163]
	v_mfma_f32_16x16x32_bf16 v[156:159], v[40:43], v[152:155], v[156:159]
	v_mfma_f32_16x16x32_bf16 v[140:143], v[24:27], v[168:171], v[140:143]
	v_mfma_f32_16x16x32_bf16 v[136:139], v[40:43], v[168:171], v[136:139]
	v_mfma_f32_16x16x32_bf16 v[124:127], v[24:27], v[202:205], v[124:127]
	v_mfma_f32_16x16x32_bf16 v[120:123], v[40:43], v[202:205], v[120:123]
	v_mfma_f32_16x16x32_bf16 v[108:111], v[24:27], v[222:225], v[108:111]
	v_mfma_f32_16x16x32_bf16 v[104:107], v[40:43], v[222:225], v[104:107]
	v_mfma_f32_16x16x32_bf16 v[160:163], v[32:35], v[164:167], v[160:163]
	v_mfma_f32_16x16x32_bf16 v[156:159], v[44:47], v[164:167], v[156:159]
	v_mfma_f32_16x16x32_bf16 v[140:143], v[32:35], v[198:201], v[140:143]
	v_mfma_f32_16x16x32_bf16 v[136:139], v[44:47], v[198:201], v[136:139]
	v_mfma_f32_16x16x32_bf16 v[124:127], v[32:35], v[206:209], v[124:127]
	v_mfma_f32_16x16x32_bf16 v[120:123], v[44:47], v[206:209], v[120:123]
	v_mfma_f32_16x16x32_bf16 v[108:111], v[32:35], v[226:229], v[108:111]
	v_mfma_f32_16x16x32_bf16 v[104:107], v[44:47], v[226:229], v[104:107]
	s_setprio 0
	s_setprio 1
	v_mfma_f32_16x16x32_bf16 v[148:151], v[56:59], v[152:155], v[148:151]
	v_mfma_f32_16x16x32_bf16 v[144:147], v[64:67], v[152:155], v[144:147]
	v_mfma_f32_16x16x32_bf16 v[132:135], v[56:59], v[168:171], v[132:135]
	v_mfma_f32_16x16x32_bf16 v[128:131], v[64:67], v[168:171], v[128:131]
	v_mfma_f32_16x16x32_bf16 v[116:119], v[56:59], v[202:205], v[116:119]
	v_mfma_f32_16x16x32_bf16 v[112:115], v[64:67], v[202:205], v[112:115]
	v_mfma_f32_16x16x32_bf16 v[100:103], v[56:59], v[222:225], v[100:103]
	v_mfma_f32_16x16x32_bf16 v[96:99], v[64:67], v[222:225], v[96:99]
	v_mfma_f32_16x16x32_bf16 v[148:151], v[60:63], v[164:167], v[148:151]
	v_mfma_f32_16x16x32_bf16 v[144:147], v[68:71], v[164:167], v[144:147]
	v_mfma_f32_16x16x32_bf16 v[132:135], v[60:63], v[198:201], v[132:135]
	v_mfma_f32_16x16x32_bf16 v[128:131], v[68:71], v[198:201], v[128:131]
	v_mfma_f32_16x16x32_bf16 v[116:119], v[60:63], v[206:209], v[116:119]
	v_mfma_f32_16x16x32_bf16 v[112:115], v[68:71], v[206:209], v[112:115]
	v_mfma_f32_16x16x32_bf16 v[100:103], v[60:63], v[226:229], v[100:103]
	v_mfma_f32_16x16x32_bf16 v[96:99], v[68:71], v[226:229], v[96:99]
	s_setprio 0
	s_barrier
	s_add_i32 s88, s81, s71
	s_mov_b64 s[98:99], s[10:11]
	s_mov_b32 m0, s88
	ds_read_b128 v[152:155], v217 offset:16384
	ds_read_b128 v[164:167], v217 offset:17408
	ds_read_b128 v[168:171], v217 offset:18432
	ds_read_b128 v[198:201], v217 offset:19456
	ds_read_b128 v[202:205], v217 offset:20480
	ds_read_b128 v[206:209], v217 offset:21504
	ds_read_b128 v[222:225], v217 offset:22528
	ds_read_b128 v[226:229], v217 offset:23552
	global_load_lds_dwordx4 v174, s[10:11]
	s_add_i32 m0, s88, 0x2000
	s_add_u32 s88, s10, 0x80000
	s_addc_u32 s89, s11, 0
	s_add_i32 s90, s82, s71
	global_load_lds_dwordx4 v178, s[10:11]
	s_mov_b32 m0, s90
	s_mov_b64 s[100:101], s[12:13]
	global_load_lds_dwordx4 v174, s[88:89]
	s_add_i32 m0, s90, 0x2000
	s_nop 0
	global_load_lds_dwordx4 v178, s[88:89]
	s_mov_b32 m0, s72
	s_nop 0
	global_load_lds_dwordx4 v172, s[12:13]
	s_mov_b32 m0, s73
	s_nop 0
	global_load_lds_dwordx4 v176, s[12:13]
	s_waitcnt vmcnt(8)
	s_waitcnt lgkmcnt(0)
	s_barrier
	s_setprio 1
	s_waitcnt lgkmcnt(0)
	v_mfma_f32_16x16x32_bf16 v[92:95], v[24:27], v[152:155], v[92:95]
	v_mfma_f32_16x16x32_bf16 v[88:91], v[40:43], v[152:155], v[88:91]
	v_mfma_f32_16x16x32_bf16 v[76:79], v[24:27], v[168:171], v[76:79]
	v_mfma_f32_16x16x32_bf16 v[72:75], v[40:43], v[168:171], v[72:75]
	v_mfma_f32_16x16x32_bf16 v[36:39], v[24:27], v[202:205], v[36:39]
	v_mfma_f32_16x16x32_bf16 v[28:31], v[40:43], v[202:205], v[28:31]
	v_mfma_f32_16x16x32_bf16 v[12:15], v[24:27], v[222:225], v[12:15]
	v_mfma_f32_16x16x32_bf16 v[8:11], v[40:43], v[222:225], v[8:11]
	v_mfma_f32_16x16x32_bf16 v[92:95], v[32:35], v[164:167], v[92:95]
	v_mfma_f32_16x16x32_bf16 v[88:91], v[44:47], v[164:167], v[88:91]
	v_mfma_f32_16x16x32_bf16 v[76:79], v[32:35], v[198:201], v[76:79]
	v_mfma_f32_16x16x32_bf16 v[72:75], v[44:47], v[198:201], v[72:75]
	v_mfma_f32_16x16x32_bf16 v[36:39], v[32:35], v[206:209], v[36:39]
	v_mfma_f32_16x16x32_bf16 v[28:31], v[44:47], v[206:209], v[28:31]
	v_mfma_f32_16x16x32_bf16 v[12:15], v[32:35], v[226:229], v[12:15]
	v_mfma_f32_16x16x32_bf16 v[8:11], v[44:47], v[226:229], v[8:11]
	s_setprio 0
	s_setprio 1
	v_mfma_f32_16x16x32_bf16 v[20:23], v[56:59], v[202:205], v[20:23]
	v_mfma_f32_16x16x32_bf16 v[16:19], v[64:67], v[202:205], v[16:19]
	v_mfma_f32_16x16x32_bf16 v[4:7], v[56:59], v[222:225], v[4:7]
	v_mfma_f32_16x16x32_bf16 v[0:3], v[64:67], v[222:225], v[0:3]
	v_mfma_f32_16x16x32_bf16 v[24:27], v[56:59], v[152:155], v[84:87]
	v_mfma_f32_16x16x32_bf16 v[32:35], v[64:67], v[152:155], v[80:83]
	v_mfma_f32_16x16x32_bf16 v[40:43], v[56:59], v[168:171], v[52:55]
	v_mfma_f32_16x16x32_bf16 v[44:47], v[64:67], v[168:171], v[48:51]
	v_mfma_f32_16x16x32_bf16 v[20:23], v[60:63], v[206:209], v[20:23]
	v_mfma_f32_16x16x32_bf16 v[16:19], v[68:71], v[206:209], v[16:19]
	v_mfma_f32_16x16x32_bf16 v[4:7], v[60:63], v[226:229], v[4:7]
	v_mfma_f32_16x16x32_bf16 v[0:3], v[68:71], v[226:229], v[0:3]
	v_mfma_f32_16x16x32_bf16 v[24:27], v[60:63], v[164:167], v[24:27]
	v_mfma_f32_16x16x32_bf16 v[32:35], v[68:71], v[164:167], v[32:35]
	v_mfma_f32_16x16x32_bf16 v[40:43], v[60:63], v[198:201], v[40:43]
	v_mfma_f32_16x16x32_bf16 v[44:47], v[68:71], v[198:201], v[44:47]
	s_setprio 0
	s_barrier
	s_add_i32 s88, 0, 0x18000
	s_add_i32 s89, 0, 0x1c000
	v_add_u32_e32 v60, s88, v213
	v_add_u32_e32 v80, s89, v213
	ds_read_b128 v[48:51], v60
	ds_read_b128 v[52:55], v60 offset:1024
	ds_read_b128 v[56:59], v60 offset:2048
	ds_read_b128 v[60:63], v60 offset:3072
	ds_read_b128 v[64:67], v80
	ds_read_b128 v[68:71], v80 offset:1024
	ds_read_b128 v[152:155], v80 offset:2048
	ds_read_b128 v[164:167], v80 offset:3072
	s_add_u32 s12, s12, 0x80000
	s_addc_u32 s13, s13, 0
	s_mov_b32 m0, s74
	ds_read_b128 v[80:83], v217 offset:32768
	ds_read_b128 v[84:87], v217 offset:33792
	ds_read_b128 v[168:171], v217 offset:34816
	ds_read_b128 v[198:201], v217 offset:35840
	ds_read_b128 v[202:205], v217 offset:36864
	ds_read_b128 v[206:209], v217 offset:37888
	ds_read_b128 v[222:225], v217 offset:38912
	ds_read_b128 v[226:229], v217 offset:39936
	global_load_lds_dwordx4 v172, s[12:13]
	s_mov_b32 m0, s75
	s_nop 0
	global_load_lds_dwordx4 v176, s[12:13]
	s_waitcnt vmcnt(8)
	s_waitcnt lgkmcnt(0)
	s_barrier
	s_setprio 1
	s_waitcnt lgkmcnt(0)
	v_mfma_f32_16x16x32_bf16 v[160:163], v[48:51], v[80:83], v[160:163]
	v_mfma_f32_16x16x32_bf16 v[156:159], v[56:59], v[80:83], v[156:159]
	v_mfma_f32_16x16x32_bf16 v[140:143], v[48:51], v[168:171], v[140:143]
	v_mfma_f32_16x16x32_bf16 v[136:139], v[56:59], v[168:171], v[136:139]
	v_mfma_f32_16x16x32_bf16 v[124:127], v[48:51], v[202:205], v[124:127]
	v_mfma_f32_16x16x32_bf16 v[120:123], v[56:59], v[202:205], v[120:123]
	v_mfma_f32_16x16x32_bf16 v[108:111], v[48:51], v[222:225], v[108:111]
	v_mfma_f32_16x16x32_bf16 v[104:107], v[56:59], v[222:225], v[104:107]
	v_mfma_f32_16x16x32_bf16 v[160:163], v[52:55], v[84:87], v[160:163]
	v_mfma_f32_16x16x32_bf16 v[156:159], v[60:63], v[84:87], v[156:159]
	v_mfma_f32_16x16x32_bf16 v[140:143], v[52:55], v[198:201], v[140:143]
	v_mfma_f32_16x16x32_bf16 v[136:139], v[60:63], v[198:201], v[136:139]
	v_mfma_f32_16x16x32_bf16 v[124:127], v[52:55], v[206:209], v[124:127]
	v_mfma_f32_16x16x32_bf16 v[120:123], v[60:63], v[206:209], v[120:123]
	v_mfma_f32_16x16x32_bf16 v[108:111], v[52:55], v[226:229], v[108:111]
	v_mfma_f32_16x16x32_bf16 v[104:107], v[60:63], v[226:229], v[104:107]
	s_setprio 0
	s_setprio 1
	v_mfma_f32_16x16x32_bf16 v[148:151], v[64:67], v[80:83], v[148:151]
	v_mfma_f32_16x16x32_bf16 v[80:83], v[152:155], v[80:83], v[144:147]
	v_mfma_f32_16x16x32_bf16 v[144:147], v[164:167], v[84:87], v[80:83]
	v_mfma_f32_16x16x32_bf16 v[80:83], v[64:67], v[168:171], v[132:135]
	v_mfma_f32_16x16x32_bf16 v[132:135], v[68:71], v[198:201], v[80:83]
	v_mfma_f32_16x16x32_bf16 v[80:83], v[152:155], v[168:171], v[128:131]
	v_mfma_f32_16x16x32_bf16 v[128:131], v[164:167], v[198:201], v[80:83]
	v_mfma_f32_16x16x32_bf16 v[80:83], v[64:67], v[202:205], v[116:119]
	v_mfma_f32_16x16x32_bf16 v[116:119], v[68:71], v[206:209], v[80:83]
	v_mfma_f32_16x16x32_bf16 v[80:83], v[152:155], v[202:205], v[112:115]
	v_mfma_f32_16x16x32_bf16 v[112:115], v[164:167], v[206:209], v[80:83]
	v_mfma_f32_16x16x32_bf16 v[80:83], v[64:67], v[222:225], v[100:103]
	v_mfma_f32_16x16x32_bf16 v[100:103], v[68:71], v[226:229], v[80:83]
	v_mfma_f32_16x16x32_bf16 v[80:83], v[152:155], v[222:225], v[96:99]
	v_mfma_f32_16x16x32_bf16 v[148:151], v[68:71], v[84:87], v[148:151]
	v_mfma_f32_16x16x32_bf16 v[96:99], v[164:167], v[226:229], v[80:83]
	s_setprio 0
	s_barrier
	s_add_i32 s12, s88, s71
	s_add_i32 m0, s12, 0xffffff80
	s_nop 0
	ds_read_b128 v[80:83], v217 offset:49152
	ds_read_b128 v[168:171], v217 offset:50176
	ds_read_b128 v[198:201], v217 offset:51200
	ds_read_b128 v[202:205], v217 offset:52224
	ds_read_b128 v[206:209], v217 offset:53248
	ds_read_b128 v[222:225], v217 offset:54272
	ds_read_b128 v[226:229], v217 offset:55296
	ds_read_b128 v[230:233], v217 offset:56320
	global_load_lds_dwordx4 v174, s[98:99] offset:128
	s_add_i32 m0, s12, 0x1f80
	s_add_u32 s10, s10, 0x80080
	s_addc_u32 s11, s11, 0
	s_add_i32 s12, s89, s71
	global_load_lds_dwordx4 v178, s[98:99] offset:128
	s_mov_b32 m0, s12
	s_nop 0
	global_load_lds_dwordx4 v174, s[10:11]
	s_add_i32 m0, s12, 0x2000
	s_nop 0
	global_load_lds_dwordx4 v178, s[10:11]
	s_add_i32 m0, s77, 0xffffff80
	s_nop 0
	global_load_lds_dwordx4 v172, s[100:101] offset:128
	s_add_i32 m0, s78, 0xffffff80
	s_nop 0
	global_load_lds_dwordx4 v176, s[100:101] offset:128
	s_waitcnt vmcnt(8)
	s_waitcnt lgkmcnt(0)
	s_barrier
	s_setprio 1
	s_waitcnt lgkmcnt(0)
	v_mfma_f32_16x16x32_bf16 v[84:87], v[48:51], v[80:83], v[92:95]
	v_mfma_f32_16x16x32_bf16 v[92:95], v[52:55], v[168:171], v[84:87]
	v_mfma_f32_16x16x32_bf16 v[84:87], v[56:59], v[80:83], v[88:91]
	v_mfma_f32_16x16x32_bf16 v[76:79], v[48:51], v[198:201], v[76:79]
	v_mfma_f32_16x16x32_bf16 v[72:75], v[56:59], v[198:201], v[72:75]
	v_mfma_f32_16x16x32_bf16 v[36:39], v[48:51], v[206:209], v[36:39]
	v_mfma_f32_16x16x32_bf16 v[28:31], v[56:59], v[206:209], v[28:31]
	v_mfma_f32_16x16x32_bf16 v[12:15], v[48:51], v[226:229], v[12:15]
	v_mfma_f32_16x16x32_bf16 v[8:11], v[56:59], v[226:229], v[8:11]
	v_mfma_f32_16x16x32_bf16 v[88:91], v[60:63], v[168:171], v[84:87]
	v_mfma_f32_16x16x32_bf16 v[76:79], v[52:55], v[202:205], v[76:79]
	v_mfma_f32_16x16x32_bf16 v[72:75], v[60:63], v[202:205], v[72:75]
	v_mfma_f32_16x16x32_bf16 v[36:39], v[52:55], v[222:225], v[36:39]
	v_mfma_f32_16x16x32_bf16 v[28:31], v[60:63], v[222:225], v[28:31]
	v_mfma_f32_16x16x32_bf16 v[12:15], v[52:55], v[230:233], v[12:15]
	v_mfma_f32_16x16x32_bf16 v[8:11], v[60:63], v[230:233], v[8:11]
	s_setprio 0
	s_setprio 1
	v_mfma_f32_16x16x32_bf16 v[24:27], v[64:67], v[80:83], v[24:27]
	v_mfma_f32_16x16x32_bf16 v[84:87], v[68:71], v[168:171], v[24:27]
	v_mfma_f32_16x16x32_bf16 v[24:27], v[152:155], v[80:83], v[32:35]
	v_mfma_f32_16x16x32_bf16 v[80:83], v[164:167], v[168:171], v[24:27]
	v_mfma_f32_16x16x32_bf16 v[24:27], v[64:67], v[198:201], v[40:43]
	v_mfma_f32_16x16x32_bf16 v[52:55], v[68:71], v[202:205], v[24:27]
	v_mfma_f32_16x16x32_bf16 v[24:27], v[152:155], v[198:201], v[44:47]
	v_mfma_f32_16x16x32_bf16 v[20:23], v[64:67], v[206:209], v[20:23]
	v_mfma_f32_16x16x32_bf16 v[16:19], v[152:155], v[206:209], v[16:19]
	v_mfma_f32_16x16x32_bf16 v[4:7], v[64:67], v[226:229], v[4:7]
	v_mfma_f32_16x16x32_bf16 v[0:3], v[152:155], v[226:229], v[0:3]
	v_mfma_f32_16x16x32_bf16 v[48:51], v[164:167], v[202:205], v[24:27]
	v_mfma_f32_16x16x32_bf16 v[20:23], v[68:71], v[222:225], v[20:23]
	v_mfma_f32_16x16x32_bf16 v[16:19], v[164:167], v[222:225], v[16:19]
	v_mfma_f32_16x16x32_bf16 v[4:7], v[68:71], v[230:233], v[4:7]
	v_mfma_f32_16x16x32_bf16 v[0:3], v[164:167], v[230:233], v[0:3]
	s_setprio 0
	s_barrier
	s_add_i32 s69, s69, 2
	s_add_u32 s6, s6, 0x100
	s_addc_u32 s7, s7, 0
	s_add_u32 s63, s63, 0x100
	s_addc_u32 s68, s68, 0
	s_cmp_gt_u32 s69, 29
	s_cbranch_scc0 .LBB0_1558
	s_and_b64 vcc, exec, s[38:39]
	s_cbranch_vccz .LBB0_1561
	s_barrier

.LBB0_1946:
	ds_read_b128 v[144:147], v159
	ds_read_b128 v[148:151], v159 offset:1024
	ds_read_b128 v[152:155], v159 offset:2048
	ds_read_b128 v[162:165], v159 offset:3072
	ds_read_b128 v[166:169], v160
	ds_read_b128 v[170:173], v160 offset:1024
	ds_read_b128 v[174:177], v160 offset:2048
	ds_read_b128 v[178:181], v160 offset:3072
	s_add_u32 s40, s38, 0xffe00080
	s_addc_u32 s41, s39, -1
	s_cmp_eq_u32 s65, 28
	s_cselect_b32 s43, s21, s41
	s_cselect_b32 s42, s61, s40
	s_cselect_b32 s41, s19, s64
	s_cselect_b32 s40, s62, s63
	s_add_i32 m0, s51, 0xc000
	ds_read_b128 v[182:185], v161
	ds_read_b128 v[186:189], v161 offset:1024
	ds_read_b128 v[190:193], v161 offset:2048
	ds_read_b128 v[194:197], v161 offset:3072
	ds_read_b128 v[198:201], v161 offset:4096
	ds_read_b128 v[202:205], v161 offset:5120
	ds_read_b128 v[206:209], v161 offset:6144
	ds_read_b128 v[210:213], v161 offset:7168
	global_load_lds_dwordx4 v136, s[38:39]
	s_add_i32 m0, s51, 0xe000
	s_nop 0
	global_load_lds_dwordx4 v138, s[38:39]
	s_waitcnt vmcnt(8)
	s_waitcnt lgkmcnt(0)
	s_barrier
	s_setprio 1
	s_waitcnt lgkmcnt(0)
	v_mfma_f32_16x16x32_bf16 v[124:127], v[144:147], v[182:185], v[124:127]
	v_mfma_f32_16x16x32_bf16 v[120:123], v[152:155], v[182:185], v[120:123]
	v_mfma_f32_16x16x32_bf16 v[116:119], v[144:147], v[190:193], v[116:119]
	v_mfma_f32_16x16x32_bf16 v[112:115], v[152:155], v[190:193], v[112:115]
	v_mfma_f32_16x16x32_bf16 v[104:107], v[144:147], v[198:201], v[104:107]
	v_mfma_f32_16x16x32_bf16 v[96:99], v[152:155], v[198:201], v[96:99]
	v_mfma_f32_16x16x32_bf16 v[88:91], v[144:147], v[206:209], v[88:91]
	v_mfma_f32_16x16x32_bf16 v[80:83], v[152:155], v[206:209], v[80:83]
	v_mfma_f32_16x16x32_bf16 v[124:127], v[148:151], v[186:189], v[124:127]
	v_mfma_f32_16x16x32_bf16 v[120:123], v[162:165], v[186:189], v[120:123]
	v_mfma_f32_16x16x32_bf16 v[116:119], v[148:151], v[194:197], v[116:119]
	v_mfma_f32_16x16x32_bf16 v[112:115], v[162:165], v[194:197], v[112:115]
	v_mfma_f32_16x16x32_bf16 v[104:107], v[148:151], v[202:205], v[104:107]
	v_mfma_f32_16x16x32_bf16 v[96:99], v[162:165], v[202:205], v[96:99]
	v_mfma_f32_16x16x32_bf16 v[88:91], v[148:151], v[210:213], v[88:91]
	v_mfma_f32_16x16x32_bf16 v[80:83], v[162:165], v[210:213], v[80:83]
	s_setprio 0
	s_setprio 1
	v_mfma_f32_16x16x32_bf16 v[108:111], v[166:169], v[182:185], v[108:111]
	v_mfma_f32_16x16x32_bf16 v[100:103], v[174:177], v[182:185], v[100:103]
	v_mfma_f32_16x16x32_bf16 v[92:95], v[166:169], v[190:193], v[92:95]
	v_mfma_f32_16x16x32_bf16 v[84:87], v[174:177], v[190:193], v[84:87]
	v_mfma_f32_16x16x32_bf16 v[76:79], v[166:169], v[198:201], v[76:79]
	v_mfma_f32_16x16x32_bf16 v[72:75], v[174:177], v[198:201], v[72:75]
	v_mfma_f32_16x16x32_bf16 v[68:71], v[166:169], v[206:209], v[68:71]
	v_mfma_f32_16x16x32_bf16 v[64:67], v[174:177], v[206:209], v[64:67]
	v_mfma_f32_16x16x32_bf16 v[108:111], v[170:173], v[186:189], v[108:111]
	v_mfma_f32_16x16x32_bf16 v[100:103], v[178:181], v[186:189], v[100:103]
	v_mfma_f32_16x16x32_bf16 v[92:95], v[170:173], v[194:197], v[92:95]
	v_mfma_f32_16x16x32_bf16 v[84:87], v[178:181], v[194:197], v[84:87]
	v_mfma_f32_16x16x32_bf16 v[76:79], v[170:173], v[202:205], v[76:79]
	v_mfma_f32_16x16x32_bf16 v[72:75], v[178:181], v[202:205], v[72:75]
	v_mfma_f32_16x16x32_bf16 v[68:71], v[170:173], v[210:213], v[68:71]
	v_mfma_f32_16x16x32_bf16 v[64:67], v[178:181], v[210:213], v[64:67]
	s_setprio 0
	s_barrier
	s_add_i32 s66, s59, s50
	s_mov_b64 s[98:99], s[40:41]
	s_mov_b32 m0, s66
	ds_read_b128 v[182:185], v161 offset:16384
	ds_read_b128 v[186:189], v161 offset:17408
	ds_read_b128 v[190:193], v161 offset:18432
	ds_read_b128 v[194:197], v161 offset:19456
	ds_read_b128 v[198:201], v161 offset:20480
	ds_read_b128 v[202:205], v161 offset:21504
	ds_read_b128 v[206:209], v161 offset:22528
	ds_read_b128 v[210:213], v161 offset:23552
	global_load_lds_dwordx4 v130, s[40:41]
	s_add_i32 m0, s66, 0x2000
	s_add_u32 s66, s40, 0x80000
	s_addc_u32 s67, s41, 0
	s_add_i32 s68, s60, s50
	global_load_lds_dwordx4 v134, s[40:41]
	s_mov_b32 m0, s68
	s_mov_b64 s[100:101], s[42:43]
	global_load_lds_dwordx4 v130, s[66:67]
	s_add_i32 m0, s68, 0x2000
	s_nop 0
	global_load_lds_dwordx4 v134, s[66:67]
	s_mov_b32 m0, s51
	s_nop 0
	global_load_lds_dwordx4 v128, s[42:43]
	s_mov_b32 m0, s52
	s_nop 0
	global_load_lds_dwordx4 v132, s[42:43]
	s_waitcnt vmcnt(8)
	s_waitcnt lgkmcnt(0)
	s_barrier
	s_setprio 1
	s_waitcnt lgkmcnt(0)
	v_mfma_f32_16x16x32_bf16 v[60:63], v[144:147], v[182:185], v[60:63]
	v_mfma_f32_16x16x32_bf16 v[56:59], v[152:155], v[182:185], v[56:59]
	v_mfma_f32_16x16x32_bf16 v[52:55], v[144:147], v[190:193], v[52:55]
	v_mfma_f32_16x16x32_bf16 v[44:47], v[152:155], v[190:193], v[44:47]
	v_mfma_f32_16x16x32_bf16 v[36:39], v[144:147], v[198:201], v[36:39]
	v_mfma_f32_16x16x32_bf16 v[28:31], v[152:155], v[198:201], v[28:31]
	v_mfma_f32_16x16x32_bf16 v[20:23], v[144:147], v[206:209], v[20:23]
	v_mfma_f32_16x16x32_bf16 v[8:11], v[152:155], v[206:209], v[8:11]
	v_mfma_f32_16x16x32_bf16 v[60:63], v[148:151], v[186:189], v[60:63]
	v_mfma_f32_16x16x32_bf16 v[56:59], v[162:165], v[186:189], v[56:59]
	v_mfma_f32_16x16x32_bf16 v[52:55], v[148:151], v[194:197], v[52:55]
	v_mfma_f32_16x16x32_bf16 v[44:47], v[162:165], v[194:197], v[44:47]
	v_mfma_f32_16x16x32_bf16 v[36:39], v[148:151], v[202:205], v[36:39]
	v_mfma_f32_16x16x32_bf16 v[28:31], v[162:165], v[202:205], v[28:31]
	v_mfma_f32_16x16x32_bf16 v[20:23], v[148:151], v[210:213], v[20:23]
	v_mfma_f32_16x16x32_bf16 v[8:11], v[162:165], v[210:213], v[8:11]
	s_setprio 0
	s_setprio 1
	v_mfma_f32_16x16x32_bf16 v[48:51], v[166:169], v[182:185], v[48:51]
	v_mfma_f32_16x16x32_bf16 v[40:43], v[174:177], v[182:185], v[40:43]
	v_mfma_f32_16x16x32_bf16 v[32:35], v[166:169], v[190:193], v[32:35]
	v_mfma_f32_16x16x32_bf16 v[24:27], v[174:177], v[190:193], v[24:27]
	v_mfma_f32_16x16x32_bf16 v[16:19], v[166:169], v[198:201], v[16:19]
	v_mfma_f32_16x16x32_bf16 v[12:15], v[174:177], v[198:201], v[12:15]
	v_mfma_f32_16x16x32_bf16 v[4:7], v[166:169], v[206:209], v[4:7]
	v_mfma_f32_16x16x32_bf16 v[0:3], v[174:177], v[206:209], v[0:3]
	v_mfma_f32_16x16x32_bf16 v[48:51], v[170:173], v[186:189], v[48:51]
	v_mfma_f32_16x16x32_bf16 v[40:43], v[178:181], v[186:189], v[40:43]
	v_mfma_f32_16x16x32_bf16 v[32:35], v[170:173], v[194:197], v[32:35]
	v_mfma_f32_16x16x32_bf16 v[24:27], v[178:181], v[194:197], v[24:27]
	v_mfma_f32_16x16x32_bf16 v[16:19], v[170:173], v[202:205], v[16:19]
	v_mfma_f32_16x16x32_bf16 v[12:15], v[178:181], v[202:205], v[12:15]
	v_mfma_f32_16x16x32_bf16 v[4:7], v[170:173], v[210:213], v[4:7]
	v_mfma_f32_16x16x32_bf16 v[0:3], v[178:181], v[210:213], v[0:3]
	s_setprio 0
	s_barrier
	s_add_i32 s66, 0, 0x18000
	s_add_i32 s67, 0, 0x1c000
	v_add_u32_e32 v162, s66, v157
	v_add_u32_e32 v178, s67, v157
	ds_read_b128 v[144:147], v162
	ds_read_b128 v[148:151], v162 offset:1024
	ds_read_b128 v[152:155], v162 offset:2048
	ds_read_b128 v[162:165], v162 offset:3072
	ds_read_b128 v[166:169], v178
	ds_read_b128 v[170:173], v178 offset:1024
	ds_read_b128 v[174:177], v178 offset:2048
	ds_read_b128 v[178:181], v178 offset:3072
	s_add_u32 s42, s42, 0x200000
	s_addc_u32 s43, s43, 0
	s_mov_b32 m0, s53
	ds_read_b128 v[182:185], v161 offset:32768
	ds_read_b128 v[186:189], v161 offset:33792
	ds_read_b128 v[190:193], v161 offset:34816
	ds_read_b128 v[194:197], v161 offset:35840
	ds_read_b128 v[198:201], v161 offset:36864
	ds_read_b128 v[202:205], v161 offset:37888
	ds_read_b128 v[206:209], v161 offset:38912
	ds_read_b128 v[210:213], v161 offset:39936
	global_load_lds_dwordx4 v128, s[42:43]
	s_mov_b32 m0, s54
	s_nop 0
	global_load_lds_dwordx4 v132, s[42:43]
	s_waitcnt vmcnt(8)
	s_waitcnt lgkmcnt(0)
	s_barrier
	s_setprio 1
	s_waitcnt lgkmcnt(0)
	v_mfma_f32_16x16x32_bf16 v[124:127], v[144:147], v[182:185], v[124:127]
	v_mfma_f32_16x16x32_bf16 v[120:123], v[152:155], v[182:185], v[120:123]
	v_mfma_f32_16x16x32_bf16 v[116:119], v[144:147], v[190:193], v[116:119]
	v_mfma_f32_16x16x32_bf16 v[112:115], v[152:155], v[190:193], v[112:115]
	v_mfma_f32_16x16x32_bf16 v[104:107], v[144:147], v[198:201], v[104:107]
	v_mfma_f32_16x16x32_bf16 v[96:99], v[152:155], v[198:201], v[96:99]
	v_mfma_f32_16x16x32_bf16 v[88:91], v[144:147], v[206:209], v[88:91]
	v_mfma_f32_16x16x32_bf16 v[80:83], v[152:155], v[206:209], v[80:83]
	v_mfma_f32_16x16x32_bf16 v[124:127], v[148:151], v[186:189], v[124:127]
	v_mfma_f32_16x16x32_bf16 v[120:123], v[162:165], v[186:189], v[120:123]
	v_mfma_f32_16x16x32_bf16 v[116:119], v[148:151], v[194:197], v[116:119]
	v_mfma_f32_16x16x32_bf16 v[112:115], v[162:165], v[194:197], v[112:115]
	v_mfma_f32_16x16x32_bf16 v[104:107], v[148:151], v[202:205], v[104:107]
	v_mfma_f32_16x16x32_bf16 v[96:99], v[162:165], v[202:205], v[96:99]
	v_mfma_f32_16x16x32_bf16 v[88:91], v[148:151], v[210:213], v[88:91]
	v_mfma_f32_16x16x32_bf16 v[80:83], v[162:165], v[210:213], v[80:83]
	s_setprio 0
	s_setprio 1
	v_mfma_f32_16x16x32_bf16 v[108:111], v[166:169], v[182:185], v[108:111]
	v_mfma_f32_16x16x32_bf16 v[100:103], v[174:177], v[182:185], v[100:103]
	v_mfma_f32_16x16x32_bf16 v[92:95], v[166:169], v[190:193], v[92:95]
	v_mfma_f32_16x16x32_bf16 v[84:87], v[174:177], v[190:193], v[84:87]
	v_mfma_f32_16x16x32_bf16 v[76:79], v[166:169], v[198:201], v[76:79]
	v_mfma_f32_16x16x32_bf16 v[72:75], v[174:177], v[198:201], v[72:75]
	v_mfma_f32_16x16x32_bf16 v[68:71], v[166:169], v[206:209], v[68:71]
	v_mfma_f32_16x16x32_bf16 v[64:67], v[174:177], v[206:209], v[64:67]
	v_mfma_f32_16x16x32_bf16 v[108:111], v[170:173], v[186:189], v[108:111]
	v_mfma_f32_16x16x32_bf16 v[100:103], v[178:181], v[186:189], v[100:103]
	v_mfma_f32_16x16x32_bf16 v[92:95], v[170:173], v[194:197], v[92:95]
	v_mfma_f32_16x16x32_bf16 v[84:87], v[178:181], v[194:197], v[84:87]
	v_mfma_f32_16x16x32_bf16 v[76:79], v[170:173], v[202:205], v[76:79]
	v_mfma_f32_16x16x32_bf16 v[72:75], v[178:181], v[202:205], v[72:75]
	v_mfma_f32_16x16x32_bf16 v[68:71], v[170:173], v[210:213], v[68:71]
	v_mfma_f32_16x16x32_bf16 v[64:67], v[178:181], v[210:213], v[64:67]
	s_setprio 0
	s_barrier
	s_add_i32 s42, s66, s50
	s_add_i32 m0, s42, 0xffffff80
	ds_read_b128 v[182:185], v161 offset:49152
	ds_read_b128 v[186:189], v161 offset:50176
	ds_read_b128 v[190:193], v161 offset:51200
	ds_read_b128 v[194:197], v161 offset:52224
	ds_read_b128 v[198:201], v161 offset:53248
	ds_read_b128 v[202:205], v161 offset:54272
	ds_read_b128 v[206:209], v161 offset:55296
	ds_read_b128 v[210:213], v161 offset:56320
	global_load_lds_dwordx4 v130, s[98:99] offset:128
	s_add_i32 m0, s42, 0x1f80
	s_add_u32 s40, s40, 0x80080
	s_addc_u32 s41, s41, 0
	s_add_i32 s42, s67, s50
	global_load_lds_dwordx4 v134, s[98:99] offset:128
	s_mov_b32 m0, s42
	s_nop 0
	global_load_lds_dwordx4 v130, s[40:41]
	s_add_i32 m0, s42, 0x2000
	s_nop 0
	global_load_lds_dwordx4 v134, s[40:41]
	s_add_i32 m0, s56, 0xffffff80
	s_nop 0
	global_load_lds_dwordx4 v128, s[100:101] offset:128
	s_add_i32 m0, s57, 0xffffff80
	s_nop 0
	global_load_lds_dwordx4 v132, s[100:101] offset:128
	s_waitcnt vmcnt(8)
	s_waitcnt lgkmcnt(0)
	s_barrier
	s_setprio 1
	s_waitcnt lgkmcnt(0)
	v_mfma_f32_16x16x32_bf16 v[60:63], v[144:147], v[182:185], v[60:63]
	v_mfma_f32_16x16x32_bf16 v[56:59], v[152:155], v[182:185], v[56:59]
	v_mfma_f32_16x16x32_bf16 v[52:55], v[144:147], v[190:193], v[52:55]
	v_mfma_f32_16x16x32_bf16 v[44:47], v[152:155], v[190:193], v[44:47]
	v_mfma_f32_16x16x32_bf16 v[36:39], v[144:147], v[198:201], v[36:39]
	v_mfma_f32_16x16x32_bf16 v[28:31], v[152:155], v[198:201], v[28:31]
	v_mfma_f32_16x16x32_bf16 v[20:23], v[144:147], v[206:209], v[20:23]
	v_mfma_f32_16x16x32_bf16 v[8:11], v[152:155], v[206:209], v[8:11]
	v_mfma_f32_16x16x32_bf16 v[60:63], v[148:151], v[186:189], v[60:63]
	v_mfma_f32_16x16x32_bf16 v[56:59], v[162:165], v[186:189], v[56:59]
	v_mfma_f32_16x16x32_bf16 v[52:55], v[148:151], v[194:197], v[52:55]
	v_mfma_f32_16x16x32_bf16 v[44:47], v[162:165], v[194:197], v[44:47]
	v_mfma_f32_16x16x32_bf16 v[36:39], v[148:151], v[202:205], v[36:39]
	v_mfma_f32_16x16x32_bf16 v[28:31], v[162:165], v[202:205], v[28:31]
	v_mfma_f32_16x16x32_bf16 v[20:23], v[148:151], v[210:213], v[20:23]
	v_mfma_f32_16x16x32_bf16 v[8:11], v[162:165], v[210:213], v[8:11]
	s_setprio 0
	s_setprio 1
	v_mfma_f32_16x16x32_bf16 v[48:51], v[166:169], v[182:185], v[48:51]
	v_mfma_f32_16x16x32_bf16 v[40:43], v[174:177], v[182:185], v[40:43]
	v_mfma_f32_16x16x32_bf16 v[32:35], v[166:169], v[190:193], v[32:35]
	v_mfma_f32_16x16x32_bf16 v[24:27], v[174:177], v[190:193], v[24:27]
	v_mfma_f32_16x16x32_bf16 v[16:19], v[166:169], v[198:201], v[16:19]
	v_mfma_f32_16x16x32_bf16 v[12:15], v[174:177], v[198:201], v[12:15]
	v_mfma_f32_16x16x32_bf16 v[4:7], v[166:169], v[206:209], v[4:7]
	v_mfma_f32_16x16x32_bf16 v[0:3], v[174:177], v[206:209], v[0:3]
	v_mfma_f32_16x16x32_bf16 v[48:51], v[170:173], v[186:189], v[48:51]
	v_mfma_f32_16x16x32_bf16 v[40:43], v[178:181], v[186:189], v[40:43]
	v_mfma_f32_16x16x32_bf16 v[32:35], v[170:173], v[194:197], v[32:35]
	v_mfma_f32_16x16x32_bf16 v[24:27], v[178:181], v[194:197], v[24:27]
	v_mfma_f32_16x16x32_bf16 v[16:19], v[170:173], v[202:205], v[16:19]
	v_mfma_f32_16x16x32_bf16 v[12:15], v[178:181], v[202:205], v[12:15]
	v_mfma_f32_16x16x32_bf16 v[4:7], v[170:173], v[210:213], v[4:7]
	v_mfma_f32_16x16x32_bf16 v[0:3], v[178:181], v[210:213], v[0:3]
	s_setprio 0
	s_barrier
	s_add_i32 s65, s65, 2
	s_add_u32 s38, s38, 0x100
	s_addc_u32 s39, s39, 0
	s_add_u32 s63, s63, 0x100
	s_addc_u32 s64, s64, 0
	s_cmp_gt_u32 s65, 29
	s_cbranch_scc0 .LBB0_1946
	s_and_b64 vcc, exec, s[8:9]
	s_cbranch_vccz .LBB0_1949
	s_barrier
